# P2 depthwise conv rewritten: eight tokens per wave, static f32 row ring over the 31 taps, counted waits from the static issue order, DPP LayerNorm reductions (exact-division silu kept)
# speedup vs baseline: 1.0118x; 1.0118x over previous
.LBB0_272:
	s_cmp_lt_i32 s74, 3
	s_cselect_b64 s[2:3], -1, 0
	s_add_u32 s44, s72, 0x5a00000
	s_addc_u32 s45, s73, 0
	s_and_b64 s[2:3], s[2:3], s[0:1]
	s_andn2_b64 vcc, exec, s[2:3]
	s_cbranch_vccnz .LBB0_293
	v_readlane_b32 s0, v254, 41
	s_cmpk_gt_i32 s0, 0xfff
	s_cbranch_scc1 .LBB0_280
	v_mov_b32_e32 v86, 0
	v_readlane_b32 s4, v254, 23
	v_lshlrev_b32_e32 v2, 4, v199
	v_mov_b32_e32 v3, v86
	v_readlane_b32 s5, v254, 24
	v_mbcnt_lo_u32_b32 v1, -1, 0
	v_lshl_add_u64 v[88:89], s[64:65], 0, v[2:3]
	v_lshl_add_u64 v[92:93], s[62:63], 0, v[2:3]
	v_lshl_add_u64 v[94:95], s[66:67], 0, v[2:3]
	v_lshl_add_u64 v[96:97], s[4:5], 0, v[2:3]
	v_mbcnt_hi_u32_b32 v2, -1, v1
	v_and_b32_e32 v1, 64, v2
	v_add_u32_e32 v3, 64, v1
	v_xor_b32_e32 v1, 1, v2
	v_cmp_lt_i32_e32 vcc, v1, v3
	v_xor_b32_e32 v6, 2, v2
	v_readlane_b32 s1, v254, 40
	v_cndmask_b32_e32 v1, v2, v1, vcc
	v_cmp_lt_i32_e32 vcc, v6, v3
	s_lshl_b32 s0, s80, 5
	s_lshl_b32 s1, s1, 2
	v_cndmask_b32_e32 v6, v2, v6, vcc
	v_lshlrev_b32_e32 v162, 2, v6
	v_xor_b32_e32 v6, 4, v2
	v_cmp_lt_i32_e32 vcc, v6, v3
	v_lshlrev_b32_e32 v4, 3, v199
	v_mov_b32_e32 v5, v86
	v_cndmask_b32_e32 v6, v2, v6, vcc
	v_lshlrev_b32_e32 v163, 2, v6
	v_xor_b32_e32 v6, 8, v2
	v_cmp_lt_i32_e32 vcc, v6, v3
	v_readlane_b32 s8, v254, 27
	v_readlane_b32 s9, v254, 28
	v_cndmask_b32_e32 v6, v2, v6, vcc
	v_lshlrev_b32_e32 v164, 2, v6
	v_xor_b32_e32 v6, 16, v2
	v_cmp_lt_i32_e32 vcc, v6, v3
	v_readlane_b32 s10, v254, 29
	v_readlane_b32 s11, v254, 30
	v_cndmask_b32_e32 v6, v2, v6, vcc
	v_lshlrev_b32_e32 v165, 2, v6
	v_xor_b32_e32 v6, 32, v2
	v_cmp_lt_i32_e32 vcc, v6, v3
	v_readlane_b32 s12, v254, 31
	v_readlane_b32 s13, v254, 32
	v_readlane_b32 s14, v254, 33
	v_readlane_b32 s15, v254, 34
	v_cndmask_b32_e32 v2, v2, v6, vcc
	s_add_i32 s0, s0, s1
	v_lshl_add_u64 v[90:91], s[38:39], 0, v[4:5]
	v_lshlrev_b32_e32 v1, 2, v1
	v_lshlrev_b32_e32 v166, 2, v2
	v_lshl_add_u64 v[98:99], s[44:45], 0, v[4:5]
	s_sub_i32 s8, s0, 27
	s_lshl_b32 s9, s33, 5
	v_mov_b32_e32 v167, 0x600
	s_movk_i32 s10, 0x1000
	s_movk_i32 s11, 0x2000
	s_movk_i32 s12, 0x3000
	s_movk_i32 s13, 0x4000
	s_movk_i32 s14, 0x5000
	v_mov_b32_e32 v168, 0x3727c5ac
	v_readlane_b32 s15, v254, 41
	v_readlane_b32 s6, v254, 25
	v_readlane_b32 s7, v254, 26
	v_readlane_b32 s16, v254, 35
	v_readlane_b32 s17, v254, 36
	v_readlane_b32 s18, v254, 37
	v_readlane_b32 s19, v254, 38
	v_readlane_b32 s40, v254, 41
	v_readlane_b32 s42, v254, 23
	v_readlane_b32 s43, v254, 24
	v_lshlrev_b32_e32 v2, 4, v199
	v_lshlrev_b32_e32 v3, 3, v199
	s_lshl_b32 s41, s40, 3
	s_mov_b64 s[50:51], s[62:63]
	global_load_dwordx4 v[222:225], v2, s[64:65]
	global_load_dwordx4 v[226:229], v2, s[64:65] offset:1024
	global_load_dwordx4 v[230:233], v2, s[64:65] offset:2048
	s_add_i32 s52, s41, -30
	s_max_i32 s52, s52, 0
	s_mulk_i32 s52, 0x600
	v_add_u32_e32 v196, s52, v3
	global_load_dwordx2 v[234:235], v196, s[38:39]
	global_load_dwordx2 v[236:237], v196, s[38:39] offset:512
	global_load_dwordx2 v[238:239], v196, s[38:39] offset:1024
	s_add_i32 s52, s41, -29
	s_max_i32 s52, s52, 0
	s_mulk_i32 s52, 0x600
	v_add_u32_e32 v196, s52, v3
	global_load_dwordx2 v[240:241], v196, s[38:39]
	global_load_dwordx2 v[242:243], v196, s[38:39] offset:512
	global_load_dwordx2 v[244:245], v196, s[38:39] offset:1024
	s_add_i32 s52, s41, -28
	s_max_i32 s52, s52, 0
	s_mulk_i32 s52, 0x600
	v_add_u32_e32 v196, s52, v3
	global_load_dwordx2 v[246:247], v196, s[38:39]
	global_load_dwordx2 v[248:249], v196, s[38:39] offset:512
	global_load_dwordx2 v[250:251], v196, s[38:39] offset:1024
	s_add_i32 s52, s41, -27
	s_max_i32 s52, s52, 0
	s_mulk_i32 s52, 0x600
	v_add_u32_e32 v196, s52, v3
	global_load_dwordx2 v[204:205], v196, s[38:39]
	global_load_dwordx2 v[206:207], v196, s[38:39] offset:512
	global_load_dwordx2 v[252:253], v196, s[38:39] offset:1024
	s_add_i32 s52, s41, -26
	s_max_i32 s52, s52, 0
	s_mulk_i32 s52, 0x600
	v_add_u32_e32 v196, s52, v3
	global_load_dwordx2 v[154:155], v196, s[38:39]
	global_load_dwordx2 v[156:157], v196, s[38:39] offset:512
	global_load_dwordx2 v[158:159], v196, s[38:39] offset:1024
	s_add_i32 s52, s41, -25
	s_max_i32 s52, s52, 0
	s_mulk_i32 s52, 0x600
	v_add_u32_e32 v196, s52, v3
	global_load_dwordx2 v[166:167], v196, s[38:39]
	global_load_dwordx2 v[168:169], v196, s[38:39] offset:512
	global_load_dwordx2 v[170:171], v196, s[38:39] offset:1024
	s_add_i32 s52, s41, -24
	s_max_i32 s52, s52, 0
	s_mulk_i32 s52, 0x600
	v_add_u32_e32 v196, s52, v3
	global_load_dwordx2 v[178:179], v196, s[38:39]
	global_load_dwordx2 v[180:181], v196, s[38:39] offset:512
	global_load_dwordx2 v[182:183], v196, s[38:39] offset:1024
	s_add_i32 s52, s41, -23
	s_max_i32 s52, s52, 0
	s_mulk_i32 s52, 0x600
	v_add_u32_e32 v196, s52, v3
	global_load_dwordx2 v[190:191], v196, s[38:39]
	global_load_dwordx2 v[192:193], v196, s[38:39] offset:512
	global_load_dwordx2 v[194:195], v196, s[38:39] offset:1024
	global_load_dwordx4 v[210:213], v2, s[50:51]
	global_load_dwordx4 v[214:217], v2, s[50:51] offset:1024
	global_load_dwordx4 v[218:221], v2, s[50:51] offset:2048
	s_add_u32 s50, s50, 0xc00
	s_addc_u32 s51, s51, 0
	s_waitcnt vmcnt(27)
	v_mov_b32_e32 v4, v222
	v_mov_b32_e32 v5, v223
	v_mov_b32_e32 v6, v224
	v_mov_b32_e32 v7, v225
	v_mov_b32_e32 v8, v226
	v_mov_b32_e32 v9, v227
	v_mov_b32_e32 v10, v228
	v_mov_b32_e32 v11, v229
	v_mov_b32_e32 v12, v230
	v_mov_b32_e32 v13, v231
	v_mov_b32_e32 v14, v232
	v_mov_b32_e32 v15, v233
	v_mov_b32_e32 v16, v222
	v_mov_b32_e32 v17, v223
	v_mov_b32_e32 v18, v224
	v_mov_b32_e32 v19, v225
	v_mov_b32_e32 v20, v226
	v_mov_b32_e32 v21, v227
	v_mov_b32_e32 v22, v228
	v_mov_b32_e32 v23, v229
	v_mov_b32_e32 v24, v230
	v_mov_b32_e32 v25, v231
	v_mov_b32_e32 v26, v232
	v_mov_b32_e32 v27, v233
	v_mov_b32_e32 v28, v222
	v_mov_b32_e32 v29, v223
	v_mov_b32_e32 v30, v224
	v_mov_b32_e32 v31, v225
	v_mov_b32_e32 v32, v226
	v_mov_b32_e32 v33, v227
	v_mov_b32_e32 v34, v228
	v_mov_b32_e32 v35, v229
	v_mov_b32_e32 v36, v230
	v_mov_b32_e32 v37, v231
	v_mov_b32_e32 v38, v232
	v_mov_b32_e32 v39, v233
	v_mov_b32_e32 v40, v222
	v_mov_b32_e32 v41, v223
	v_mov_b32_e32 v42, v224
	v_mov_b32_e32 v43, v225
	v_mov_b32_e32 v44, v226
	v_mov_b32_e32 v45, v227
	v_mov_b32_e32 v46, v228
	v_mov_b32_e32 v47, v229
	v_mov_b32_e32 v48, v230
	v_mov_b32_e32 v49, v231
	v_mov_b32_e32 v50, v232
	v_mov_b32_e32 v51, v233
	v_mov_b32_e32 v52, v222
	v_mov_b32_e32 v53, v223
	v_mov_b32_e32 v54, v224
	v_mov_b32_e32 v55, v225
	v_mov_b32_e32 v56, v226
	v_mov_b32_e32 v57, v227
	v_mov_b32_e32 v58, v228
	v_mov_b32_e32 v59, v229
	v_mov_b32_e32 v60, v230
	v_mov_b32_e32 v61, v231
	v_mov_b32_e32 v62, v232
	v_mov_b32_e32 v63, v233
	v_mov_b32_e32 v64, v222
	v_mov_b32_e32 v65, v223
	v_mov_b32_e32 v66, v224
	v_mov_b32_e32 v67, v225
	v_mov_b32_e32 v68, v226
	v_mov_b32_e32 v69, v227
	v_mov_b32_e32 v70, v228
	v_mov_b32_e32 v71, v229
	v_mov_b32_e32 v72, v230
	v_mov_b32_e32 v73, v231
	v_mov_b32_e32 v74, v232
	v_mov_b32_e32 v75, v233
	v_mov_b32_e32 v76, v222
	v_mov_b32_e32 v77, v223
	v_mov_b32_e32 v78, v224
	v_mov_b32_e32 v79, v225
	v_mov_b32_e32 v80, v226
	v_mov_b32_e32 v81, v227
	v_mov_b32_e32 v82, v228
	v_mov_b32_e32 v83, v229
	v_mov_b32_e32 v84, v230
	v_mov_b32_e32 v85, v231
	v_mov_b32_e32 v86, v232
	v_mov_b32_e32 v87, v233
	v_mov_b32_e32 v88, v222
	v_mov_b32_e32 v89, v223
	v_mov_b32_e32 v90, v224
	v_mov_b32_e32 v91, v225
	v_mov_b32_e32 v92, v226
	v_mov_b32_e32 v93, v227
	v_mov_b32_e32 v94, v228
	v_mov_b32_e32 v95, v229
	v_mov_b32_e32 v96, v230
	v_mov_b32_e32 v97, v231
	v_mov_b32_e32 v98, v232
	v_mov_b32_e32 v99, v233
	global_load_dwordx4 v[222:225], v2, s[50:51]
	global_load_dwordx4 v[226:229], v2, s[50:51] offset:1024
	global_load_dwordx4 v[230:233], v2, s[50:51] offset:2048
	s_add_u32 s50, s50, 0xc00
	s_addc_u32 s51, s51, 0
	s_waitcnt vmcnt(27)
	s_add_i32 s52, s41, -30
	s_cmp_lt_i32 s52, 0
	s_cbranch_scc1 .Lcv_z0_zero
	v_lshlrev_b32_e32 v100, 16, v234
	v_and_b32_e32 v101, 0xffff0000, v234
	v_lshlrev_b32_e32 v102, 16, v235
	v_and_b32_e32 v103, 0xffff0000, v235
	v_lshlrev_b32_e32 v104, 16, v236
	v_and_b32_e32 v105, 0xffff0000, v236
	v_lshlrev_b32_e32 v106, 16, v237
	v_and_b32_e32 v107, 0xffff0000, v237
	v_lshlrev_b32_e32 v108, 16, v238
	v_and_b32_e32 v109, 0xffff0000, v238
	v_lshlrev_b32_e32 v110, 16, v239
	v_and_b32_e32 v111, 0xffff0000, v239
	s_branch .Lcv_z0_done
.Lcv_z0_zero:
	v_mov_b32_e32 v100, 0
	v_mov_b32_e32 v101, 0
	v_mov_b32_e32 v102, 0
	v_mov_b32_e32 v103, 0
	v_mov_b32_e32 v104, 0
	v_mov_b32_e32 v105, 0
	v_mov_b32_e32 v106, 0
	v_mov_b32_e32 v107, 0
	v_mov_b32_e32 v108, 0
	v_mov_b32_e32 v109, 0
	v_mov_b32_e32 v110, 0
	v_mov_b32_e32 v111, 0
.Lcv_z0_done:
	s_add_i32 s52, s41, -22
	s_max_i32 s52, s52, 0
	s_mulk_i32 s52, 0x600
	v_add_u32_e32 v196, s52, v3
	global_load_dwordx2 v[234:235], v196, s[38:39]
	global_load_dwordx2 v[236:237], v196, s[38:39] offset:512
	global_load_dwordx2 v[238:239], v196, s[38:39] offset:1024
	s_waitcnt vmcnt(27)
	s_add_i32 s52, s41, -29
	s_cmp_lt_i32 s52, 0
	s_cbranch_scc1 .Lcv_z1_zero
	v_lshlrev_b32_e32 v112, 16, v240
	v_and_b32_e32 v113, 0xffff0000, v240
	v_lshlrev_b32_e32 v114, 16, v241
	v_and_b32_e32 v115, 0xffff0000, v241
	v_lshlrev_b32_e32 v116, 16, v242
	v_and_b32_e32 v117, 0xffff0000, v242
	v_lshlrev_b32_e32 v118, 16, v243
	v_and_b32_e32 v119, 0xffff0000, v243
	v_lshlrev_b32_e32 v120, 16, v244
	v_and_b32_e32 v121, 0xffff0000, v244
	v_lshlrev_b32_e32 v122, 16, v245
	v_and_b32_e32 v123, 0xffff0000, v245
	s_branch .Lcv_z1_done
.Lcv_z1_zero:
	v_mov_b32_e32 v112, 0
	v_mov_b32_e32 v113, 0
	v_mov_b32_e32 v114, 0
	v_mov_b32_e32 v115, 0
	v_mov_b32_e32 v116, 0
	v_mov_b32_e32 v117, 0
	v_mov_b32_e32 v118, 0
	v_mov_b32_e32 v119, 0
	v_mov_b32_e32 v120, 0
	v_mov_b32_e32 v121, 0
	v_mov_b32_e32 v122, 0
	v_mov_b32_e32 v123, 0
.Lcv_z1_done:
	s_add_i32 s52, s41, -21
	s_max_i32 s52, s52, 0
	s_mulk_i32 s52, 0x600
	v_add_u32_e32 v196, s52, v3
	global_load_dwordx2 v[240:241], v196, s[38:39]
	global_load_dwordx2 v[242:243], v196, s[38:39] offset:512
	global_load_dwordx2 v[244:245], v196, s[38:39] offset:1024
	s_waitcnt vmcnt(27)
	s_add_i32 s52, s41, -28
	s_cmp_lt_i32 s52, 0
	s_cbranch_scc1 .Lcv_z2_zero
	v_lshlrev_b32_e32 v124, 16, v246
	v_and_b32_e32 v125, 0xffff0000, v246
	v_lshlrev_b32_e32 v126, 16, v247
	v_and_b32_e32 v127, 0xffff0000, v247
	v_lshlrev_b32_e32 v128, 16, v248
	v_and_b32_e32 v129, 0xffff0000, v248
	v_lshlrev_b32_e32 v130, 16, v249
	v_and_b32_e32 v131, 0xffff0000, v249
	v_lshlrev_b32_e32 v132, 16, v250
	v_and_b32_e32 v133, 0xffff0000, v250
	v_lshlrev_b32_e32 v134, 16, v251
	v_and_b32_e32 v135, 0xffff0000, v251
	s_branch .Lcv_z2_done
.Lcv_z2_zero:
	v_mov_b32_e32 v124, 0
	v_mov_b32_e32 v125, 0
	v_mov_b32_e32 v126, 0
	v_mov_b32_e32 v127, 0
	v_mov_b32_e32 v128, 0
	v_mov_b32_e32 v129, 0
	v_mov_b32_e32 v130, 0
	v_mov_b32_e32 v131, 0
	v_mov_b32_e32 v132, 0
	v_mov_b32_e32 v133, 0
	v_mov_b32_e32 v134, 0
	v_mov_b32_e32 v135, 0
.Lcv_z2_done:
	s_add_i32 s52, s41, -20
	s_max_i32 s52, s52, 0
	s_mulk_i32 s52, 0x600
	v_add_u32_e32 v196, s52, v3
	global_load_dwordx2 v[246:247], v196, s[38:39]
	global_load_dwordx2 v[248:249], v196, s[38:39] offset:512
	global_load_dwordx2 v[250:251], v196, s[38:39] offset:1024
	s_waitcnt vmcnt(27)
	s_add_i32 s52, s41, -27
	s_cmp_lt_i32 s52, 0
	s_cbranch_scc1 .Lcv_z3_zero
	v_lshlrev_b32_e32 v136, 16, v204
	v_and_b32_e32 v137, 0xffff0000, v204
	v_lshlrev_b32_e32 v138, 16, v205
	v_and_b32_e32 v139, 0xffff0000, v205
	v_lshlrev_b32_e32 v140, 16, v206
	v_and_b32_e32 v141, 0xffff0000, v206
	v_lshlrev_b32_e32 v142, 16, v207
	v_and_b32_e32 v143, 0xffff0000, v207
	v_lshlrev_b32_e32 v144, 16, v252
	v_and_b32_e32 v145, 0xffff0000, v252
	v_lshlrev_b32_e32 v146, 16, v253
	v_and_b32_e32 v147, 0xffff0000, v253
	s_branch .Lcv_z3_done
.Lcv_z3_zero:
	v_mov_b32_e32 v136, 0
	v_mov_b32_e32 v137, 0
	v_mov_b32_e32 v138, 0
	v_mov_b32_e32 v139, 0
	v_mov_b32_e32 v140, 0
	v_mov_b32_e32 v141, 0
	v_mov_b32_e32 v142, 0
	v_mov_b32_e32 v143, 0
	v_mov_b32_e32 v144, 0
	v_mov_b32_e32 v145, 0
	v_mov_b32_e32 v146, 0
	v_mov_b32_e32 v147, 0
.Lcv_z3_done:
	s_add_i32 s52, s41, -19
	s_max_i32 s52, s52, 0
	s_mulk_i32 s52, 0x600
	v_add_u32_e32 v196, s52, v3
	global_load_dwordx2 v[204:205], v196, s[38:39]
	global_load_dwordx2 v[206:207], v196, s[38:39] offset:512
	global_load_dwordx2 v[252:253], v196, s[38:39] offset:1024
	s_waitcnt vmcnt(27)
	s_add_i32 s52, s41, -26
	s_cmp_lt_i32 s52, 0
	s_cbranch_scc1 .Lcv_z4_zero
	v_lshlrev_b32_e32 v148, 16, v154
	v_and_b32_e32 v149, 0xffff0000, v154
	v_lshlrev_b32_e32 v150, 16, v155
	v_and_b32_e32 v151, 0xffff0000, v155
	v_lshlrev_b32_e32 v152, 16, v156
	v_and_b32_e32 v153, 0xffff0000, v156
	v_lshlrev_b32_e32 v154, 16, v157
	v_and_b32_e32 v155, 0xffff0000, v157
	v_lshlrev_b32_e32 v156, 16, v158
	v_and_b32_e32 v157, 0xffff0000, v158
	v_lshlrev_b32_e32 v158, 16, v159
	v_and_b32_e32 v159, 0xffff0000, v159
	s_branch .Lcv_z4_done
.Lcv_z4_zero:
	v_mov_b32_e32 v148, 0
	v_mov_b32_e32 v149, 0
	v_mov_b32_e32 v150, 0
	v_mov_b32_e32 v151, 0
	v_mov_b32_e32 v152, 0
	v_mov_b32_e32 v153, 0
	v_mov_b32_e32 v154, 0
	v_mov_b32_e32 v155, 0
	v_mov_b32_e32 v156, 0
	v_mov_b32_e32 v157, 0
	v_mov_b32_e32 v158, 0
	v_mov_b32_e32 v159, 0
.Lcv_z4_done:
	s_waitcnt vmcnt(24)
	s_add_i32 s52, s41, -25
	s_cmp_lt_i32 s52, 0
	s_cbranch_scc1 .Lcv_z5_zero
	v_lshlrev_b32_e32 v160, 16, v166
	v_and_b32_e32 v161, 0xffff0000, v166
	v_lshlrev_b32_e32 v162, 16, v167
	v_and_b32_e32 v163, 0xffff0000, v167
	v_lshlrev_b32_e32 v164, 16, v168
	v_and_b32_e32 v165, 0xffff0000, v168
	v_lshlrev_b32_e32 v166, 16, v169
	v_and_b32_e32 v167, 0xffff0000, v169
	v_lshlrev_b32_e32 v168, 16, v170
	v_and_b32_e32 v169, 0xffff0000, v170
	v_lshlrev_b32_e32 v170, 16, v171
	v_and_b32_e32 v171, 0xffff0000, v171
	s_branch .Lcv_z5_done
.Lcv_z5_zero:
	v_mov_b32_e32 v160, 0
	v_mov_b32_e32 v161, 0
	v_mov_b32_e32 v162, 0
	v_mov_b32_e32 v163, 0
	v_mov_b32_e32 v164, 0
	v_mov_b32_e32 v165, 0
	v_mov_b32_e32 v166, 0
	v_mov_b32_e32 v167, 0
	v_mov_b32_e32 v168, 0
	v_mov_b32_e32 v169, 0
	v_mov_b32_e32 v170, 0
	v_mov_b32_e32 v171, 0
.Lcv_z5_done:
	s_waitcnt vmcnt(21)
	s_add_i32 s52, s41, -24
	s_cmp_lt_i32 s52, 0
	s_cbranch_scc1 .Lcv_z6_zero
	v_lshlrev_b32_e32 v172, 16, v178
	v_and_b32_e32 v173, 0xffff0000, v178
	v_lshlrev_b32_e32 v174, 16, v179
	v_and_b32_e32 v175, 0xffff0000, v179
	v_lshlrev_b32_e32 v176, 16, v180
	v_and_b32_e32 v177, 0xffff0000, v180
	v_lshlrev_b32_e32 v178, 16, v181
	v_and_b32_e32 v179, 0xffff0000, v181
	v_lshlrev_b32_e32 v180, 16, v182
	v_and_b32_e32 v181, 0xffff0000, v182
	v_lshlrev_b32_e32 v182, 16, v183
	v_and_b32_e32 v183, 0xffff0000, v183
	s_branch .Lcv_z6_done
.Lcv_z6_zero:
	v_mov_b32_e32 v172, 0
	v_mov_b32_e32 v173, 0
	v_mov_b32_e32 v174, 0
	v_mov_b32_e32 v175, 0
	v_mov_b32_e32 v176, 0
	v_mov_b32_e32 v177, 0
	v_mov_b32_e32 v178, 0
	v_mov_b32_e32 v179, 0
	v_mov_b32_e32 v180, 0
	v_mov_b32_e32 v181, 0
	v_mov_b32_e32 v182, 0
	v_mov_b32_e32 v183, 0
.Lcv_z6_done:
	s_waitcnt vmcnt(18)
	s_add_i32 s52, s41, -23
	s_cmp_lt_i32 s52, 0
	s_cbranch_scc1 .Lcv_z7_zero
	v_lshlrev_b32_e32 v184, 16, v190
	v_and_b32_e32 v185, 0xffff0000, v190
	v_lshlrev_b32_e32 v186, 16, v191
	v_and_b32_e32 v187, 0xffff0000, v191
	v_lshlrev_b32_e32 v188, 16, v192
	v_and_b32_e32 v189, 0xffff0000, v192
	v_lshlrev_b32_e32 v190, 16, v193
	v_and_b32_e32 v191, 0xffff0000, v193
	v_lshlrev_b32_e32 v192, 16, v194
	v_and_b32_e32 v193, 0xffff0000, v194
	v_lshlrev_b32_e32 v194, 16, v195
	v_and_b32_e32 v195, 0xffff0000, v195
	s_branch .Lcv_z7_done
.Lcv_z7_zero:
	v_mov_b32_e32 v184, 0
	v_mov_b32_e32 v185, 0
	v_mov_b32_e32 v186, 0
	v_mov_b32_e32 v187, 0
	v_mov_b32_e32 v188, 0
	v_mov_b32_e32 v189, 0
	v_mov_b32_e32 v190, 0
	v_mov_b32_e32 v191, 0
	v_mov_b32_e32 v192, 0
	v_mov_b32_e32 v193, 0
	v_mov_b32_e32 v194, 0
	v_mov_b32_e32 v195, 0
.Lcv_z7_done:
	s_waitcnt vmcnt(15)
	v_pk_fma_f32 v[4:5], v[100:101], v[210:211], v[4:5]
	v_pk_fma_f32 v[6:7], v[102:103], v[212:213], v[6:7]
	v_pk_fma_f32 v[8:9], v[104:105], v[214:215], v[8:9]
	v_pk_fma_f32 v[10:11], v[106:107], v[216:217], v[10:11]
	v_pk_fma_f32 v[12:13], v[108:109], v[218:219], v[12:13]
	v_pk_fma_f32 v[14:15], v[110:111], v[220:221], v[14:15]
	v_pk_fma_f32 v[16:17], v[112:113], v[210:211], v[16:17]
	v_pk_fma_f32 v[18:19], v[114:115], v[212:213], v[18:19]
	v_pk_fma_f32 v[20:21], v[116:117], v[214:215], v[20:21]
	v_pk_fma_f32 v[22:23], v[118:119], v[216:217], v[22:23]
	v_pk_fma_f32 v[24:25], v[120:121], v[218:219], v[24:25]
	v_pk_fma_f32 v[26:27], v[122:123], v[220:221], v[26:27]
	v_pk_fma_f32 v[28:29], v[124:125], v[210:211], v[28:29]
	v_pk_fma_f32 v[30:31], v[126:127], v[212:213], v[30:31]
	v_pk_fma_f32 v[32:33], v[128:129], v[214:215], v[32:33]
	v_pk_fma_f32 v[34:35], v[130:131], v[216:217], v[34:35]
	v_pk_fma_f32 v[36:37], v[132:133], v[218:219], v[36:37]
	v_pk_fma_f32 v[38:39], v[134:135], v[220:221], v[38:39]
	v_pk_fma_f32 v[40:41], v[136:137], v[210:211], v[40:41]
	v_pk_fma_f32 v[42:43], v[138:139], v[212:213], v[42:43]
	v_pk_fma_f32 v[44:45], v[140:141], v[214:215], v[44:45]
	v_pk_fma_f32 v[46:47], v[142:143], v[216:217], v[46:47]
	v_pk_fma_f32 v[48:49], v[144:145], v[218:219], v[48:49]
	v_pk_fma_f32 v[50:51], v[146:147], v[220:221], v[50:51]
	v_pk_fma_f32 v[52:53], v[148:149], v[210:211], v[52:53]
	v_pk_fma_f32 v[54:55], v[150:151], v[212:213], v[54:55]
	v_pk_fma_f32 v[56:57], v[152:153], v[214:215], v[56:57]
	v_pk_fma_f32 v[58:59], v[154:155], v[216:217], v[58:59]
	v_pk_fma_f32 v[60:61], v[156:157], v[218:219], v[60:61]
	v_pk_fma_f32 v[62:63], v[158:159], v[220:221], v[62:63]
	v_pk_fma_f32 v[64:65], v[160:161], v[210:211], v[64:65]
	v_pk_fma_f32 v[66:67], v[162:163], v[212:213], v[66:67]
	v_pk_fma_f32 v[68:69], v[164:165], v[214:215], v[68:69]
	v_pk_fma_f32 v[70:71], v[166:167], v[216:217], v[70:71]
	v_pk_fma_f32 v[72:73], v[168:169], v[218:219], v[72:73]
	v_pk_fma_f32 v[74:75], v[170:171], v[220:221], v[74:75]
	v_pk_fma_f32 v[76:77], v[172:173], v[210:211], v[76:77]
	v_pk_fma_f32 v[78:79], v[174:175], v[212:213], v[78:79]
	v_pk_fma_f32 v[80:81], v[176:177], v[214:215], v[80:81]
	v_pk_fma_f32 v[82:83], v[178:179], v[216:217], v[82:83]
	v_pk_fma_f32 v[84:85], v[180:181], v[218:219], v[84:85]
	v_pk_fma_f32 v[86:87], v[182:183], v[220:221], v[86:87]
	v_pk_fma_f32 v[88:89], v[184:185], v[210:211], v[88:89]
	v_pk_fma_f32 v[90:91], v[186:187], v[212:213], v[90:91]
	v_pk_fma_f32 v[92:93], v[188:189], v[214:215], v[92:93]
	v_pk_fma_f32 v[94:95], v[190:191], v[216:217], v[94:95]
	v_pk_fma_f32 v[96:97], v[192:193], v[218:219], v[96:97]
	v_pk_fma_f32 v[98:99], v[194:195], v[220:221], v[98:99]
	global_load_dwordx4 v[210:213], v2, s[50:51]
	global_load_dwordx4 v[214:217], v2, s[50:51] offset:1024
	global_load_dwordx4 v[218:221], v2, s[50:51] offset:2048
	s_add_u32 s50, s50, 0xc00
	s_addc_u32 s51, s51, 0
	s_waitcnt vmcnt(12)
	s_add_i32 s52, s41, -22
	s_cmp_lt_i32 s52, 0
	s_cbranch_scc1 .Lcv_z8_zero
	v_lshlrev_b32_e32 v100, 16, v234
	v_and_b32_e32 v101, 0xffff0000, v234
	v_lshlrev_b32_e32 v102, 16, v235
	v_and_b32_e32 v103, 0xffff0000, v235
	v_lshlrev_b32_e32 v104, 16, v236
	v_and_b32_e32 v105, 0xffff0000, v236
	v_lshlrev_b32_e32 v106, 16, v237
	v_and_b32_e32 v107, 0xffff0000, v237
	v_lshlrev_b32_e32 v108, 16, v238
	v_and_b32_e32 v109, 0xffff0000, v238
	v_lshlrev_b32_e32 v110, 16, v239
	v_and_b32_e32 v111, 0xffff0000, v239
	s_branch .Lcv_z8_done

.Lcv_z8_done:
	s_add_i32 s52, s41, -18
	s_max_i32 s52, s52, 0
	s_mulk_i32 s52, 0x600
	v_add_u32_e32 v196, s52, v3
	global_load_dwordx2 v[234:235], v196, s[38:39]
	global_load_dwordx2 v[236:237], v196, s[38:39] offset:512
	global_load_dwordx2 v[238:239], v196, s[38:39] offset:1024
	v_pk_fma_f32 v[4:5], v[112:113], v[222:223], v[4:5]
	v_pk_fma_f32 v[6:7], v[114:115], v[224:225], v[6:7]
	v_pk_fma_f32 v[8:9], v[116:117], v[226:227], v[8:9]
	v_pk_fma_f32 v[10:11], v[118:119], v[228:229], v[10:11]
	v_pk_fma_f32 v[12:13], v[120:121], v[230:231], v[12:13]
	v_pk_fma_f32 v[14:15], v[122:123], v[232:233], v[14:15]
	v_pk_fma_f32 v[16:17], v[124:125], v[222:223], v[16:17]
	v_pk_fma_f32 v[18:19], v[126:127], v[224:225], v[18:19]
	v_pk_fma_f32 v[20:21], v[128:129], v[226:227], v[20:21]
	v_pk_fma_f32 v[22:23], v[130:131], v[228:229], v[22:23]
	v_pk_fma_f32 v[24:25], v[132:133], v[230:231], v[24:25]
	v_pk_fma_f32 v[26:27], v[134:135], v[232:233], v[26:27]
	v_pk_fma_f32 v[28:29], v[136:137], v[222:223], v[28:29]
	v_pk_fma_f32 v[30:31], v[138:139], v[224:225], v[30:31]
	v_pk_fma_f32 v[32:33], v[140:141], v[226:227], v[32:33]
	v_pk_fma_f32 v[34:35], v[142:143], v[228:229], v[34:35]
	v_pk_fma_f32 v[36:37], v[144:145], v[230:231], v[36:37]
	v_pk_fma_f32 v[38:39], v[146:147], v[232:233], v[38:39]
	v_pk_fma_f32 v[40:41], v[148:149], v[222:223], v[40:41]
	v_pk_fma_f32 v[42:43], v[150:151], v[224:225], v[42:43]
	v_pk_fma_f32 v[44:45], v[152:153], v[226:227], v[44:45]
	v_pk_fma_f32 v[46:47], v[154:155], v[228:229], v[46:47]
	v_pk_fma_f32 v[48:49], v[156:157], v[230:231], v[48:49]
	v_pk_fma_f32 v[50:51], v[158:159], v[232:233], v[50:51]
	v_pk_fma_f32 v[52:53], v[160:161], v[222:223], v[52:53]
	v_pk_fma_f32 v[54:55], v[162:163], v[224:225], v[54:55]
	v_pk_fma_f32 v[56:57], v[164:165], v[226:227], v[56:57]
	v_pk_fma_f32 v[58:59], v[166:167], v[228:229], v[58:59]
	v_pk_fma_f32 v[60:61], v[168:169], v[230:231], v[60:61]
	v_pk_fma_f32 v[62:63], v[170:171], v[232:233], v[62:63]
	v_pk_fma_f32 v[64:65], v[172:173], v[222:223], v[64:65]
	v_pk_fma_f32 v[66:67], v[174:175], v[224:225], v[66:67]
	v_pk_fma_f32 v[68:69], v[176:177], v[226:227], v[68:69]
	v_pk_fma_f32 v[70:71], v[178:179], v[228:229], v[70:71]
	v_pk_fma_f32 v[72:73], v[180:181], v[230:231], v[72:73]
	v_pk_fma_f32 v[74:75], v[182:183], v[232:233], v[74:75]
	v_pk_fma_f32 v[76:77], v[184:185], v[222:223], v[76:77]
	v_pk_fma_f32 v[78:79], v[186:187], v[224:225], v[78:79]
	v_pk_fma_f32 v[80:81], v[188:189], v[226:227], v[80:81]
	v_pk_fma_f32 v[82:83], v[190:191], v[228:229], v[82:83]
	v_pk_fma_f32 v[84:85], v[192:193], v[230:231], v[84:85]
	v_pk_fma_f32 v[86:87], v[194:195], v[232:233], v[86:87]
	v_pk_fma_f32 v[88:89], v[100:101], v[222:223], v[88:89]
	v_pk_fma_f32 v[90:91], v[102:103], v[224:225], v[90:91]
	v_pk_fma_f32 v[92:93], v[104:105], v[226:227], v[92:93]
	v_pk_fma_f32 v[94:95], v[106:107], v[228:229], v[94:95]
	v_pk_fma_f32 v[96:97], v[108:109], v[230:231], v[96:97]
	v_pk_fma_f32 v[98:99], v[110:111], v[232:233], v[98:99]
	global_load_dwordx4 v[222:225], v2, s[50:51]
	global_load_dwordx4 v[226:229], v2, s[50:51] offset:1024
	global_load_dwordx4 v[230:233], v2, s[50:51] offset:2048
	s_add_u32 s50, s50, 0xc00
	s_addc_u32 s51, s51, 0
	s_waitcnt vmcnt(15)
	s_add_i32 s52, s41, -21
	s_cmp_lt_i32 s52, 0
	s_cbranch_scc1 .Lcv_z9_zero
	v_lshlrev_b32_e32 v112, 16, v240
	v_and_b32_e32 v113, 0xffff0000, v240
	v_lshlrev_b32_e32 v114, 16, v241
	v_and_b32_e32 v115, 0xffff0000, v241
	v_lshlrev_b32_e32 v116, 16, v242
	v_and_b32_e32 v117, 0xffff0000, v242
	v_lshlrev_b32_e32 v118, 16, v243
	v_and_b32_e32 v119, 0xffff0000, v243
	v_lshlrev_b32_e32 v120, 16, v244
	v_and_b32_e32 v121, 0xffff0000, v244
	v_lshlrev_b32_e32 v122, 16, v245
	v_and_b32_e32 v123, 0xffff0000, v245
	s_branch .Lcv_z9_done

.Lcv_z9_done:
	s_add_i32 s52, s41, -17
	s_max_i32 s52, s52, 0
	s_mulk_i32 s52, 0x600
	v_add_u32_e32 v196, s52, v3
	global_load_dwordx2 v[240:241], v196, s[38:39]
	global_load_dwordx2 v[242:243], v196, s[38:39] offset:512
	global_load_dwordx2 v[244:245], v196, s[38:39] offset:1024
	s_waitcnt vmcnt(9)
	v_pk_fma_f32 v[4:5], v[124:125], v[210:211], v[4:5]
	v_pk_fma_f32 v[6:7], v[126:127], v[212:213], v[6:7]
	v_pk_fma_f32 v[8:9], v[128:129], v[214:215], v[8:9]
	v_pk_fma_f32 v[10:11], v[130:131], v[216:217], v[10:11]
	v_pk_fma_f32 v[12:13], v[132:133], v[218:219], v[12:13]
	v_pk_fma_f32 v[14:15], v[134:135], v[220:221], v[14:15]
	v_pk_fma_f32 v[16:17], v[136:137], v[210:211], v[16:17]
	v_pk_fma_f32 v[18:19], v[138:139], v[212:213], v[18:19]
	v_pk_fma_f32 v[20:21], v[140:141], v[214:215], v[20:21]
	v_pk_fma_f32 v[22:23], v[142:143], v[216:217], v[22:23]
	v_pk_fma_f32 v[24:25], v[144:145], v[218:219], v[24:25]
	v_pk_fma_f32 v[26:27], v[146:147], v[220:221], v[26:27]
	v_pk_fma_f32 v[28:29], v[148:149], v[210:211], v[28:29]
	v_pk_fma_f32 v[30:31], v[150:151], v[212:213], v[30:31]
	v_pk_fma_f32 v[32:33], v[152:153], v[214:215], v[32:33]
	v_pk_fma_f32 v[34:35], v[154:155], v[216:217], v[34:35]
	v_pk_fma_f32 v[36:37], v[156:157], v[218:219], v[36:37]
	v_pk_fma_f32 v[38:39], v[158:159], v[220:221], v[38:39]
	v_pk_fma_f32 v[40:41], v[160:161], v[210:211], v[40:41]
	v_pk_fma_f32 v[42:43], v[162:163], v[212:213], v[42:43]
	v_pk_fma_f32 v[44:45], v[164:165], v[214:215], v[44:45]
	v_pk_fma_f32 v[46:47], v[166:167], v[216:217], v[46:47]
	v_pk_fma_f32 v[48:49], v[168:169], v[218:219], v[48:49]
	v_pk_fma_f32 v[50:51], v[170:171], v[220:221], v[50:51]
	v_pk_fma_f32 v[52:53], v[172:173], v[210:211], v[52:53]
	v_pk_fma_f32 v[54:55], v[174:175], v[212:213], v[54:55]
	v_pk_fma_f32 v[56:57], v[176:177], v[214:215], v[56:57]
	v_pk_fma_f32 v[58:59], v[178:179], v[216:217], v[58:59]
	v_pk_fma_f32 v[60:61], v[180:181], v[218:219], v[60:61]
	v_pk_fma_f32 v[62:63], v[182:183], v[220:221], v[62:63]
	v_pk_fma_f32 v[64:65], v[184:185], v[210:211], v[64:65]
	v_pk_fma_f32 v[66:67], v[186:187], v[212:213], v[66:67]
	v_pk_fma_f32 v[68:69], v[188:189], v[214:215], v[68:69]
	v_pk_fma_f32 v[70:71], v[190:191], v[216:217], v[70:71]
	v_pk_fma_f32 v[72:73], v[192:193], v[218:219], v[72:73]
	v_pk_fma_f32 v[74:75], v[194:195], v[220:221], v[74:75]
	v_pk_fma_f32 v[76:77], v[100:101], v[210:211], v[76:77]
	v_pk_fma_f32 v[78:79], v[102:103], v[212:213], v[78:79]
	v_pk_fma_f32 v[80:81], v[104:105], v[214:215], v[80:81]
	v_pk_fma_f32 v[82:83], v[106:107], v[216:217], v[82:83]
	v_pk_fma_f32 v[84:85], v[108:109], v[218:219], v[84:85]
	v_pk_fma_f32 v[86:87], v[110:111], v[220:221], v[86:87]
	v_pk_fma_f32 v[88:89], v[112:113], v[210:211], v[88:89]
	v_pk_fma_f32 v[90:91], v[114:115], v[212:213], v[90:91]
	v_pk_fma_f32 v[92:93], v[116:117], v[214:215], v[92:93]
	v_pk_fma_f32 v[94:95], v[118:119], v[216:217], v[94:95]
	v_pk_fma_f32 v[96:97], v[120:121], v[218:219], v[96:97]
	v_pk_fma_f32 v[98:99], v[122:123], v[220:221], v[98:99]
	global_load_dwordx4 v[210:213], v2, s[50:51]
	global_load_dwordx4 v[214:217], v2, s[50:51] offset:1024
	global_load_dwordx4 v[218:221], v2, s[50:51] offset:2048
	s_add_u32 s50, s50, 0xc00
	s_addc_u32 s51, s51, 0
	s_add_i32 s52, s41, -20
	s_cmp_lt_i32 s52, 0
	s_cbranch_scc1 .Lcv_z10_zero
	v_lshlrev_b32_e32 v124, 16, v246
	v_and_b32_e32 v125, 0xffff0000, v246
	v_lshlrev_b32_e32 v126, 16, v247
	v_and_b32_e32 v127, 0xffff0000, v247
	v_lshlrev_b32_e32 v128, 16, v248
	v_and_b32_e32 v129, 0xffff0000, v248
	v_lshlrev_b32_e32 v130, 16, v249
	v_and_b32_e32 v131, 0xffff0000, v249
	v_lshlrev_b32_e32 v132, 16, v250
	v_and_b32_e32 v133, 0xffff0000, v250
	v_lshlrev_b32_e32 v134, 16, v251
	v_and_b32_e32 v135, 0xffff0000, v251
	s_branch .Lcv_z10_done

.Lcv_z10_done:
	s_add_i32 s52, s41, -16
	s_max_i32 s52, s52, 0
	s_mulk_i32 s52, 0x600
	v_add_u32_e32 v196, s52, v3
	global_load_dwordx2 v[246:247], v196, s[38:39]
	global_load_dwordx2 v[248:249], v196, s[38:39] offset:512
	global_load_dwordx2 v[250:251], v196, s[38:39] offset:1024
	s_waitcnt vmcnt(9)
	v_pk_fma_f32 v[4:5], v[136:137], v[222:223], v[4:5]
	v_pk_fma_f32 v[6:7], v[138:139], v[224:225], v[6:7]
	v_pk_fma_f32 v[8:9], v[140:141], v[226:227], v[8:9]
	v_pk_fma_f32 v[10:11], v[142:143], v[228:229], v[10:11]
	v_pk_fma_f32 v[12:13], v[144:145], v[230:231], v[12:13]
	v_pk_fma_f32 v[14:15], v[146:147], v[232:233], v[14:15]
	v_pk_fma_f32 v[16:17], v[148:149], v[222:223], v[16:17]
	v_pk_fma_f32 v[18:19], v[150:151], v[224:225], v[18:19]
	v_pk_fma_f32 v[20:21], v[152:153], v[226:227], v[20:21]
	v_pk_fma_f32 v[22:23], v[154:155], v[228:229], v[22:23]
	v_pk_fma_f32 v[24:25], v[156:157], v[230:231], v[24:25]
	v_pk_fma_f32 v[26:27], v[158:159], v[232:233], v[26:27]
	v_pk_fma_f32 v[28:29], v[160:161], v[222:223], v[28:29]
	v_pk_fma_f32 v[30:31], v[162:163], v[224:225], v[30:31]
	v_pk_fma_f32 v[32:33], v[164:165], v[226:227], v[32:33]
	v_pk_fma_f32 v[34:35], v[166:167], v[228:229], v[34:35]
	v_pk_fma_f32 v[36:37], v[168:169], v[230:231], v[36:37]
	v_pk_fma_f32 v[38:39], v[170:171], v[232:233], v[38:39]
	v_pk_fma_f32 v[40:41], v[172:173], v[222:223], v[40:41]
	v_pk_fma_f32 v[42:43], v[174:175], v[224:225], v[42:43]
	v_pk_fma_f32 v[44:45], v[176:177], v[226:227], v[44:45]
	v_pk_fma_f32 v[46:47], v[178:179], v[228:229], v[46:47]
	v_pk_fma_f32 v[48:49], v[180:181], v[230:231], v[48:49]
	v_pk_fma_f32 v[50:51], v[182:183], v[232:233], v[50:51]
	v_pk_fma_f32 v[52:53], v[184:185], v[222:223], v[52:53]
	v_pk_fma_f32 v[54:55], v[186:187], v[224:225], v[54:55]
	v_pk_fma_f32 v[56:57], v[188:189], v[226:227], v[56:57]
	v_pk_fma_f32 v[58:59], v[190:191], v[228:229], v[58:59]
	v_pk_fma_f32 v[60:61], v[192:193], v[230:231], v[60:61]
	v_pk_fma_f32 v[62:63], v[194:195], v[232:233], v[62:63]
	v_pk_fma_f32 v[64:65], v[100:101], v[222:223], v[64:65]
	v_pk_fma_f32 v[66:67], v[102:103], v[224:225], v[66:67]
	v_pk_fma_f32 v[68:69], v[104:105], v[226:227], v[68:69]
	v_pk_fma_f32 v[70:71], v[106:107], v[228:229], v[70:71]
	v_pk_fma_f32 v[72:73], v[108:109], v[230:231], v[72:73]
	v_pk_fma_f32 v[74:75], v[110:111], v[232:233], v[74:75]
	v_pk_fma_f32 v[76:77], v[112:113], v[222:223], v[76:77]
	v_pk_fma_f32 v[78:79], v[114:115], v[224:225], v[78:79]
	v_pk_fma_f32 v[80:81], v[116:117], v[226:227], v[80:81]
	v_pk_fma_f32 v[82:83], v[118:119], v[228:229], v[82:83]
	v_pk_fma_f32 v[84:85], v[120:121], v[230:231], v[84:85]
	v_pk_fma_f32 v[86:87], v[122:123], v[232:233], v[86:87]
	v_pk_fma_f32 v[88:89], v[124:125], v[222:223], v[88:89]
	v_pk_fma_f32 v[90:91], v[126:127], v[224:225], v[90:91]
	v_pk_fma_f32 v[92:93], v[128:129], v[226:227], v[92:93]
	v_pk_fma_f32 v[94:95], v[130:131], v[228:229], v[94:95]
	v_pk_fma_f32 v[96:97], v[132:133], v[230:231], v[96:97]
	v_pk_fma_f32 v[98:99], v[134:135], v[232:233], v[98:99]
	global_load_dwordx4 v[222:225], v2, s[50:51]
	global_load_dwordx4 v[226:229], v2, s[50:51] offset:1024
	global_load_dwordx4 v[230:233], v2, s[50:51] offset:2048
	s_add_u32 s50, s50, 0xc00
	s_addc_u32 s51, s51, 0
	s_add_i32 s52, s41, -19
	s_cmp_lt_i32 s52, 0
	s_cbranch_scc1 .Lcv_z11_zero
	v_lshlrev_b32_e32 v136, 16, v204
	v_and_b32_e32 v137, 0xffff0000, v204
	v_lshlrev_b32_e32 v138, 16, v205
	v_and_b32_e32 v139, 0xffff0000, v205
	v_lshlrev_b32_e32 v140, 16, v206
	v_and_b32_e32 v141, 0xffff0000, v206
	v_lshlrev_b32_e32 v142, 16, v207
	v_and_b32_e32 v143, 0xffff0000, v207
	v_lshlrev_b32_e32 v144, 16, v252
	v_and_b32_e32 v145, 0xffff0000, v252
	v_lshlrev_b32_e32 v146, 16, v253
	v_and_b32_e32 v147, 0xffff0000, v253
	s_branch .Lcv_z11_done

.Lcv_z11_done:
	s_add_i32 s52, s41, -15
	s_max_i32 s52, s52, 0
	s_mulk_i32 s52, 0x600
	v_add_u32_e32 v196, s52, v3
	global_load_dwordx2 v[204:205], v196, s[38:39]
	global_load_dwordx2 v[206:207], v196, s[38:39] offset:512
	global_load_dwordx2 v[252:253], v196, s[38:39] offset:1024
	s_waitcnt vmcnt(9)
	v_pk_fma_f32 v[4:5], v[148:149], v[210:211], v[4:5]
	v_pk_fma_f32 v[6:7], v[150:151], v[212:213], v[6:7]
	v_pk_fma_f32 v[8:9], v[152:153], v[214:215], v[8:9]
	v_pk_fma_f32 v[10:11], v[154:155], v[216:217], v[10:11]
	v_pk_fma_f32 v[12:13], v[156:157], v[218:219], v[12:13]
	v_pk_fma_f32 v[14:15], v[158:159], v[220:221], v[14:15]
	v_pk_fma_f32 v[16:17], v[160:161], v[210:211], v[16:17]
	v_pk_fma_f32 v[18:19], v[162:163], v[212:213], v[18:19]
	v_pk_fma_f32 v[20:21], v[164:165], v[214:215], v[20:21]
	v_pk_fma_f32 v[22:23], v[166:167], v[216:217], v[22:23]
	v_pk_fma_f32 v[24:25], v[168:169], v[218:219], v[24:25]
	v_pk_fma_f32 v[26:27], v[170:171], v[220:221], v[26:27]
	v_pk_fma_f32 v[28:29], v[172:173], v[210:211], v[28:29]
	v_pk_fma_f32 v[30:31], v[174:175], v[212:213], v[30:31]
	v_pk_fma_f32 v[32:33], v[176:177], v[214:215], v[32:33]
	v_pk_fma_f32 v[34:35], v[178:179], v[216:217], v[34:35]
	v_pk_fma_f32 v[36:37], v[180:181], v[218:219], v[36:37]
	v_pk_fma_f32 v[38:39], v[182:183], v[220:221], v[38:39]
	v_pk_fma_f32 v[40:41], v[184:185], v[210:211], v[40:41]
	v_pk_fma_f32 v[42:43], v[186:187], v[212:213], v[42:43]
	v_pk_fma_f32 v[44:45], v[188:189], v[214:215], v[44:45]
	v_pk_fma_f32 v[46:47], v[190:191], v[216:217], v[46:47]
	v_pk_fma_f32 v[48:49], v[192:193], v[218:219], v[48:49]
	v_pk_fma_f32 v[50:51], v[194:195], v[220:221], v[50:51]
	v_pk_fma_f32 v[52:53], v[100:101], v[210:211], v[52:53]
	v_pk_fma_f32 v[54:55], v[102:103], v[212:213], v[54:55]
	v_pk_fma_f32 v[56:57], v[104:105], v[214:215], v[56:57]
	v_pk_fma_f32 v[58:59], v[106:107], v[216:217], v[58:59]
	v_pk_fma_f32 v[60:61], v[108:109], v[218:219], v[60:61]
	v_pk_fma_f32 v[62:63], v[110:111], v[220:221], v[62:63]
	v_pk_fma_f32 v[64:65], v[112:113], v[210:211], v[64:65]
	v_pk_fma_f32 v[66:67], v[114:115], v[212:213], v[66:67]
	v_pk_fma_f32 v[68:69], v[116:117], v[214:215], v[68:69]
	v_pk_fma_f32 v[70:71], v[118:119], v[216:217], v[70:71]
	v_pk_fma_f32 v[72:73], v[120:121], v[218:219], v[72:73]
	v_pk_fma_f32 v[74:75], v[122:123], v[220:221], v[74:75]
	v_pk_fma_f32 v[76:77], v[124:125], v[210:211], v[76:77]
	v_pk_fma_f32 v[78:79], v[126:127], v[212:213], v[78:79]
	v_pk_fma_f32 v[80:81], v[128:129], v[214:215], v[80:81]
	v_pk_fma_f32 v[82:83], v[130:131], v[216:217], v[82:83]
	v_pk_fma_f32 v[84:85], v[132:133], v[218:219], v[84:85]
	v_pk_fma_f32 v[86:87], v[134:135], v[220:221], v[86:87]
	v_pk_fma_f32 v[88:89], v[136:137], v[210:211], v[88:89]
	v_pk_fma_f32 v[90:91], v[138:139], v[212:213], v[90:91]
	v_pk_fma_f32 v[92:93], v[140:141], v[214:215], v[92:93]
	v_pk_fma_f32 v[94:95], v[142:143], v[216:217], v[94:95]
	v_pk_fma_f32 v[96:97], v[144:145], v[218:219], v[96:97]
	v_pk_fma_f32 v[98:99], v[146:147], v[220:221], v[98:99]
	global_load_dwordx4 v[210:213], v2, s[50:51]
	global_load_dwordx4 v[214:217], v2, s[50:51] offset:1024
	global_load_dwordx4 v[218:221], v2, s[50:51] offset:2048
	s_add_u32 s50, s50, 0xc00
	s_addc_u32 s51, s51, 0
	s_add_i32 s52, s41, -18
	s_cmp_lt_i32 s52, 0
	s_cbranch_scc1 .Lcv_z12_zero
	v_lshlrev_b32_e32 v148, 16, v234
	v_and_b32_e32 v149, 0xffff0000, v234
	v_lshlrev_b32_e32 v150, 16, v235
	v_and_b32_e32 v151, 0xffff0000, v235
	v_lshlrev_b32_e32 v152, 16, v236
	v_and_b32_e32 v153, 0xffff0000, v236
	v_lshlrev_b32_e32 v154, 16, v237
	v_and_b32_e32 v155, 0xffff0000, v237
	v_lshlrev_b32_e32 v156, 16, v238
	v_and_b32_e32 v157, 0xffff0000, v238
	v_lshlrev_b32_e32 v158, 16, v239
	v_and_b32_e32 v159, 0xffff0000, v239
	s_branch .Lcv_z12_done

.Lcv_z12_done:
	s_add_i32 s52, s41, -14
	s_max_i32 s52, s52, 0
	s_mulk_i32 s52, 0x600
	v_add_u32_e32 v196, s52, v3
	global_load_dwordx2 v[234:235], v196, s[38:39]
	global_load_dwordx2 v[236:237], v196, s[38:39] offset:512
	global_load_dwordx2 v[238:239], v196, s[38:39] offset:1024
	s_waitcnt vmcnt(9)
	v_pk_fma_f32 v[4:5], v[160:161], v[222:223], v[4:5]
	v_pk_fma_f32 v[6:7], v[162:163], v[224:225], v[6:7]
	v_pk_fma_f32 v[8:9], v[164:165], v[226:227], v[8:9]
	v_pk_fma_f32 v[10:11], v[166:167], v[228:229], v[10:11]
	v_pk_fma_f32 v[12:13], v[168:169], v[230:231], v[12:13]
	v_pk_fma_f32 v[14:15], v[170:171], v[232:233], v[14:15]
	v_pk_fma_f32 v[16:17], v[172:173], v[222:223], v[16:17]
	v_pk_fma_f32 v[18:19], v[174:175], v[224:225], v[18:19]
	v_pk_fma_f32 v[20:21], v[176:177], v[226:227], v[20:21]
	v_pk_fma_f32 v[22:23], v[178:179], v[228:229], v[22:23]
	v_pk_fma_f32 v[24:25], v[180:181], v[230:231], v[24:25]
	v_pk_fma_f32 v[26:27], v[182:183], v[232:233], v[26:27]
	v_pk_fma_f32 v[28:29], v[184:185], v[222:223], v[28:29]
	v_pk_fma_f32 v[30:31], v[186:187], v[224:225], v[30:31]
	v_pk_fma_f32 v[32:33], v[188:189], v[226:227], v[32:33]
	v_pk_fma_f32 v[34:35], v[190:191], v[228:229], v[34:35]
	v_pk_fma_f32 v[36:37], v[192:193], v[230:231], v[36:37]
	v_pk_fma_f32 v[38:39], v[194:195], v[232:233], v[38:39]
	v_pk_fma_f32 v[40:41], v[100:101], v[222:223], v[40:41]
	v_pk_fma_f32 v[42:43], v[102:103], v[224:225], v[42:43]
	v_pk_fma_f32 v[44:45], v[104:105], v[226:227], v[44:45]
	v_pk_fma_f32 v[46:47], v[106:107], v[228:229], v[46:47]
	v_pk_fma_f32 v[48:49], v[108:109], v[230:231], v[48:49]
	v_pk_fma_f32 v[50:51], v[110:111], v[232:233], v[50:51]
	v_pk_fma_f32 v[52:53], v[112:113], v[222:223], v[52:53]
	v_pk_fma_f32 v[54:55], v[114:115], v[224:225], v[54:55]
	v_pk_fma_f32 v[56:57], v[116:117], v[226:227], v[56:57]
	v_pk_fma_f32 v[58:59], v[118:119], v[228:229], v[58:59]
	v_pk_fma_f32 v[60:61], v[120:121], v[230:231], v[60:61]
	v_pk_fma_f32 v[62:63], v[122:123], v[232:233], v[62:63]
	v_pk_fma_f32 v[64:65], v[124:125], v[222:223], v[64:65]
	v_pk_fma_f32 v[66:67], v[126:127], v[224:225], v[66:67]
	v_pk_fma_f32 v[68:69], v[128:129], v[226:227], v[68:69]
	v_pk_fma_f32 v[70:71], v[130:131], v[228:229], v[70:71]
	v_pk_fma_f32 v[72:73], v[132:133], v[230:231], v[72:73]
	v_pk_fma_f32 v[74:75], v[134:135], v[232:233], v[74:75]
	v_pk_fma_f32 v[76:77], v[136:137], v[222:223], v[76:77]
	v_pk_fma_f32 v[78:79], v[138:139], v[224:225], v[78:79]
	v_pk_fma_f32 v[80:81], v[140:141], v[226:227], v[80:81]
	v_pk_fma_f32 v[82:83], v[142:143], v[228:229], v[82:83]
	v_pk_fma_f32 v[84:85], v[144:145], v[230:231], v[84:85]
	v_pk_fma_f32 v[86:87], v[146:147], v[232:233], v[86:87]
	v_pk_fma_f32 v[88:89], v[148:149], v[222:223], v[88:89]
	v_pk_fma_f32 v[90:91], v[150:151], v[224:225], v[90:91]
	v_pk_fma_f32 v[92:93], v[152:153], v[226:227], v[92:93]
	v_pk_fma_f32 v[94:95], v[154:155], v[228:229], v[94:95]
	v_pk_fma_f32 v[96:97], v[156:157], v[230:231], v[96:97]
	v_pk_fma_f32 v[98:99], v[158:159], v[232:233], v[98:99]
	global_load_dwordx4 v[222:225], v2, s[50:51]
	global_load_dwordx4 v[226:229], v2, s[50:51] offset:1024
	global_load_dwordx4 v[230:233], v2, s[50:51] offset:2048
	s_add_u32 s50, s50, 0xc00
	s_addc_u32 s51, s51, 0
	s_add_i32 s52, s41, -17
	s_cmp_lt_i32 s52, 0
	s_cbranch_scc1 .Lcv_z13_zero
	v_lshlrev_b32_e32 v160, 16, v240
	v_and_b32_e32 v161, 0xffff0000, v240
	v_lshlrev_b32_e32 v162, 16, v241
	v_and_b32_e32 v163, 0xffff0000, v241
	v_lshlrev_b32_e32 v164, 16, v242
	v_and_b32_e32 v165, 0xffff0000, v242
	v_lshlrev_b32_e32 v166, 16, v243
	v_and_b32_e32 v167, 0xffff0000, v243
	v_lshlrev_b32_e32 v168, 16, v244
	v_and_b32_e32 v169, 0xffff0000, v244
	v_lshlrev_b32_e32 v170, 16, v245
	v_and_b32_e32 v171, 0xffff0000, v245
	s_branch .Lcv_z13_done

.Lcv_z13_done:
	s_add_i32 s52, s41, -13
	s_max_i32 s52, s52, 0
	s_mulk_i32 s52, 0x600
	v_add_u32_e32 v196, s52, v3
	global_load_dwordx2 v[240:241], v196, s[38:39]
	global_load_dwordx2 v[242:243], v196, s[38:39] offset:512
	global_load_dwordx2 v[244:245], v196, s[38:39] offset:1024
	s_waitcnt vmcnt(9)
	v_pk_fma_f32 v[4:5], v[172:173], v[210:211], v[4:5]
	v_pk_fma_f32 v[6:7], v[174:175], v[212:213], v[6:7]
	v_pk_fma_f32 v[8:9], v[176:177], v[214:215], v[8:9]
	v_pk_fma_f32 v[10:11], v[178:179], v[216:217], v[10:11]
	v_pk_fma_f32 v[12:13], v[180:181], v[218:219], v[12:13]
	v_pk_fma_f32 v[14:15], v[182:183], v[220:221], v[14:15]
	v_pk_fma_f32 v[16:17], v[184:185], v[210:211], v[16:17]
	v_pk_fma_f32 v[18:19], v[186:187], v[212:213], v[18:19]
	v_pk_fma_f32 v[20:21], v[188:189], v[214:215], v[20:21]
	v_pk_fma_f32 v[22:23], v[190:191], v[216:217], v[22:23]
	v_pk_fma_f32 v[24:25], v[192:193], v[218:219], v[24:25]
	v_pk_fma_f32 v[26:27], v[194:195], v[220:221], v[26:27]
	v_pk_fma_f32 v[28:29], v[100:101], v[210:211], v[28:29]
	v_pk_fma_f32 v[30:31], v[102:103], v[212:213], v[30:31]
	v_pk_fma_f32 v[32:33], v[104:105], v[214:215], v[32:33]
	v_pk_fma_f32 v[34:35], v[106:107], v[216:217], v[34:35]
	v_pk_fma_f32 v[36:37], v[108:109], v[218:219], v[36:37]
	v_pk_fma_f32 v[38:39], v[110:111], v[220:221], v[38:39]
	v_pk_fma_f32 v[40:41], v[112:113], v[210:211], v[40:41]
	v_pk_fma_f32 v[42:43], v[114:115], v[212:213], v[42:43]
	v_pk_fma_f32 v[44:45], v[116:117], v[214:215], v[44:45]
	v_pk_fma_f32 v[46:47], v[118:119], v[216:217], v[46:47]
	v_pk_fma_f32 v[48:49], v[120:121], v[218:219], v[48:49]
	v_pk_fma_f32 v[50:51], v[122:123], v[220:221], v[50:51]
	v_pk_fma_f32 v[52:53], v[124:125], v[210:211], v[52:53]
	v_pk_fma_f32 v[54:55], v[126:127], v[212:213], v[54:55]
	v_pk_fma_f32 v[56:57], v[128:129], v[214:215], v[56:57]
	v_pk_fma_f32 v[58:59], v[130:131], v[216:217], v[58:59]
	v_pk_fma_f32 v[60:61], v[132:133], v[218:219], v[60:61]
	v_pk_fma_f32 v[62:63], v[134:135], v[220:221], v[62:63]
	v_pk_fma_f32 v[64:65], v[136:137], v[210:211], v[64:65]
	v_pk_fma_f32 v[66:67], v[138:139], v[212:213], v[66:67]
	v_pk_fma_f32 v[68:69], v[140:141], v[214:215], v[68:69]
	v_pk_fma_f32 v[70:71], v[142:143], v[216:217], v[70:71]
	v_pk_fma_f32 v[72:73], v[144:145], v[218:219], v[72:73]
	v_pk_fma_f32 v[74:75], v[146:147], v[220:221], v[74:75]
	v_pk_fma_f32 v[76:77], v[148:149], v[210:211], v[76:77]
	v_pk_fma_f32 v[78:79], v[150:151], v[212:213], v[78:79]
	v_pk_fma_f32 v[80:81], v[152:153], v[214:215], v[80:81]
	v_pk_fma_f32 v[82:83], v[154:155], v[216:217], v[82:83]
	v_pk_fma_f32 v[84:85], v[156:157], v[218:219], v[84:85]
	v_pk_fma_f32 v[86:87], v[158:159], v[220:221], v[86:87]
	v_pk_fma_f32 v[88:89], v[160:161], v[210:211], v[88:89]
	v_pk_fma_f32 v[90:91], v[162:163], v[212:213], v[90:91]
	v_pk_fma_f32 v[92:93], v[164:165], v[214:215], v[92:93]
	v_pk_fma_f32 v[94:95], v[166:167], v[216:217], v[94:95]
	v_pk_fma_f32 v[96:97], v[168:169], v[218:219], v[96:97]
	v_pk_fma_f32 v[98:99], v[170:171], v[220:221], v[98:99]
	global_load_dwordx4 v[210:213], v2, s[50:51]
	global_load_dwordx4 v[214:217], v2, s[50:51] offset:1024
	global_load_dwordx4 v[218:221], v2, s[50:51] offset:2048
	s_add_u32 s50, s50, 0xc00
	s_addc_u32 s51, s51, 0
	s_add_i32 s52, s41, -16
	s_cmp_lt_i32 s52, 0
	s_cbranch_scc1 .Lcv_z14_zero
	v_lshlrev_b32_e32 v172, 16, v246
	v_and_b32_e32 v173, 0xffff0000, v246
	v_lshlrev_b32_e32 v174, 16, v247
	v_and_b32_e32 v175, 0xffff0000, v247
	v_lshlrev_b32_e32 v176, 16, v248
	v_and_b32_e32 v177, 0xffff0000, v248
	v_lshlrev_b32_e32 v178, 16, v249
	v_and_b32_e32 v179, 0xffff0000, v249
	v_lshlrev_b32_e32 v180, 16, v250
	v_and_b32_e32 v181, 0xffff0000, v250
	v_lshlrev_b32_e32 v182, 16, v251
	v_and_b32_e32 v183, 0xffff0000, v251
	s_branch .Lcv_z14_done

.Lcv_z14_done:
	s_add_i32 s52, s41, -12
	s_max_i32 s52, s52, 0
	s_mulk_i32 s52, 0x600
	v_add_u32_e32 v196, s52, v3
	global_load_dwordx2 v[246:247], v196, s[38:39]
	global_load_dwordx2 v[248:249], v196, s[38:39] offset:512
	global_load_dwordx2 v[250:251], v196, s[38:39] offset:1024
	s_waitcnt vmcnt(9)
	v_pk_fma_f32 v[4:5], v[184:185], v[222:223], v[4:5]
	v_pk_fma_f32 v[6:7], v[186:187], v[224:225], v[6:7]
	v_pk_fma_f32 v[8:9], v[188:189], v[226:227], v[8:9]
	v_pk_fma_f32 v[10:11], v[190:191], v[228:229], v[10:11]
	v_pk_fma_f32 v[12:13], v[192:193], v[230:231], v[12:13]
	v_pk_fma_f32 v[14:15], v[194:195], v[232:233], v[14:15]
	v_pk_fma_f32 v[16:17], v[100:101], v[222:223], v[16:17]
	v_pk_fma_f32 v[18:19], v[102:103], v[224:225], v[18:19]
	v_pk_fma_f32 v[20:21], v[104:105], v[226:227], v[20:21]
	v_pk_fma_f32 v[22:23], v[106:107], v[228:229], v[22:23]
	v_pk_fma_f32 v[24:25], v[108:109], v[230:231], v[24:25]
	v_pk_fma_f32 v[26:27], v[110:111], v[232:233], v[26:27]
	v_pk_fma_f32 v[28:29], v[112:113], v[222:223], v[28:29]
	v_pk_fma_f32 v[30:31], v[114:115], v[224:225], v[30:31]
	v_pk_fma_f32 v[32:33], v[116:117], v[226:227], v[32:33]
	v_pk_fma_f32 v[34:35], v[118:119], v[228:229], v[34:35]
	v_pk_fma_f32 v[36:37], v[120:121], v[230:231], v[36:37]
	v_pk_fma_f32 v[38:39], v[122:123], v[232:233], v[38:39]
	v_pk_fma_f32 v[40:41], v[124:125], v[222:223], v[40:41]
	v_pk_fma_f32 v[42:43], v[126:127], v[224:225], v[42:43]
	v_pk_fma_f32 v[44:45], v[128:129], v[226:227], v[44:45]
	v_pk_fma_f32 v[46:47], v[130:131], v[228:229], v[46:47]
	v_pk_fma_f32 v[48:49], v[132:133], v[230:231], v[48:49]
	v_pk_fma_f32 v[50:51], v[134:135], v[232:233], v[50:51]
	v_pk_fma_f32 v[52:53], v[136:137], v[222:223], v[52:53]
	v_pk_fma_f32 v[54:55], v[138:139], v[224:225], v[54:55]
	v_pk_fma_f32 v[56:57], v[140:141], v[226:227], v[56:57]
	v_pk_fma_f32 v[58:59], v[142:143], v[228:229], v[58:59]
	v_pk_fma_f32 v[60:61], v[144:145], v[230:231], v[60:61]
	v_pk_fma_f32 v[62:63], v[146:147], v[232:233], v[62:63]
	v_pk_fma_f32 v[64:65], v[148:149], v[222:223], v[64:65]
	v_pk_fma_f32 v[66:67], v[150:151], v[224:225], v[66:67]
	v_pk_fma_f32 v[68:69], v[152:153], v[226:227], v[68:69]
	v_pk_fma_f32 v[70:71], v[154:155], v[228:229], v[70:71]
	v_pk_fma_f32 v[72:73], v[156:157], v[230:231], v[72:73]
	v_pk_fma_f32 v[74:75], v[158:159], v[232:233], v[74:75]
	v_pk_fma_f32 v[76:77], v[160:161], v[222:223], v[76:77]
	v_pk_fma_f32 v[78:79], v[162:163], v[224:225], v[78:79]
	v_pk_fma_f32 v[80:81], v[164:165], v[226:227], v[80:81]
	v_pk_fma_f32 v[82:83], v[166:167], v[228:229], v[82:83]
	v_pk_fma_f32 v[84:85], v[168:169], v[230:231], v[84:85]
	v_pk_fma_f32 v[86:87], v[170:171], v[232:233], v[86:87]
	v_pk_fma_f32 v[88:89], v[172:173], v[222:223], v[88:89]
	v_pk_fma_f32 v[90:91], v[174:175], v[224:225], v[90:91]
	v_pk_fma_f32 v[92:93], v[176:177], v[226:227], v[92:93]
	v_pk_fma_f32 v[94:95], v[178:179], v[228:229], v[94:95]
	v_pk_fma_f32 v[96:97], v[180:181], v[230:231], v[96:97]
	v_pk_fma_f32 v[98:99], v[182:183], v[232:233], v[98:99]
	global_load_dwordx4 v[222:225], v2, s[50:51]
	global_load_dwordx4 v[226:229], v2, s[50:51] offset:1024
	global_load_dwordx4 v[230:233], v2, s[50:51] offset:2048
	s_add_u32 s50, s50, 0xc00
	s_addc_u32 s51, s51, 0
	s_add_i32 s52, s41, -15
	s_cmp_lt_i32 s52, 0
	s_cbranch_scc1 .Lcv_z15_zero
	v_lshlrev_b32_e32 v184, 16, v204
	v_and_b32_e32 v185, 0xffff0000, v204
	v_lshlrev_b32_e32 v186, 16, v205
	v_and_b32_e32 v187, 0xffff0000, v205
	v_lshlrev_b32_e32 v188, 16, v206
	v_and_b32_e32 v189, 0xffff0000, v206
	v_lshlrev_b32_e32 v190, 16, v207
	v_and_b32_e32 v191, 0xffff0000, v207
	v_lshlrev_b32_e32 v192, 16, v252
	v_and_b32_e32 v193, 0xffff0000, v252
	v_lshlrev_b32_e32 v194, 16, v253
	v_and_b32_e32 v195, 0xffff0000, v253
	s_branch .Lcv_z15_done

.Lcv_z15_done:
	s_add_i32 s52, s41, -11
	s_max_i32 s52, s52, 0
	s_mulk_i32 s52, 0x600
	v_add_u32_e32 v196, s52, v3
	global_load_dwordx2 v[204:205], v196, s[38:39]
	global_load_dwordx2 v[206:207], v196, s[38:39] offset:512
	global_load_dwordx2 v[252:253], v196, s[38:39] offset:1024
	s_waitcnt vmcnt(9)
	v_pk_fma_f32 v[4:5], v[100:101], v[210:211], v[4:5]
	v_pk_fma_f32 v[6:7], v[102:103], v[212:213], v[6:7]
	v_pk_fma_f32 v[8:9], v[104:105], v[214:215], v[8:9]
	v_pk_fma_f32 v[10:11], v[106:107], v[216:217], v[10:11]
	v_pk_fma_f32 v[12:13], v[108:109], v[218:219], v[12:13]
	v_pk_fma_f32 v[14:15], v[110:111], v[220:221], v[14:15]
	v_pk_fma_f32 v[16:17], v[112:113], v[210:211], v[16:17]
	v_pk_fma_f32 v[18:19], v[114:115], v[212:213], v[18:19]
	v_pk_fma_f32 v[20:21], v[116:117], v[214:215], v[20:21]
	v_pk_fma_f32 v[22:23], v[118:119], v[216:217], v[22:23]
	v_pk_fma_f32 v[24:25], v[120:121], v[218:219], v[24:25]
	v_pk_fma_f32 v[26:27], v[122:123], v[220:221], v[26:27]
	v_pk_fma_f32 v[28:29], v[124:125], v[210:211], v[28:29]
	v_pk_fma_f32 v[30:31], v[126:127], v[212:213], v[30:31]
	v_pk_fma_f32 v[32:33], v[128:129], v[214:215], v[32:33]
	v_pk_fma_f32 v[34:35], v[130:131], v[216:217], v[34:35]
	v_pk_fma_f32 v[36:37], v[132:133], v[218:219], v[36:37]
	v_pk_fma_f32 v[38:39], v[134:135], v[220:221], v[38:39]
	v_pk_fma_f32 v[40:41], v[136:137], v[210:211], v[40:41]
	v_pk_fma_f32 v[42:43], v[138:139], v[212:213], v[42:43]
	v_pk_fma_f32 v[44:45], v[140:141], v[214:215], v[44:45]
	v_pk_fma_f32 v[46:47], v[142:143], v[216:217], v[46:47]
	v_pk_fma_f32 v[48:49], v[144:145], v[218:219], v[48:49]
	v_pk_fma_f32 v[50:51], v[146:147], v[220:221], v[50:51]
	v_pk_fma_f32 v[52:53], v[148:149], v[210:211], v[52:53]
	v_pk_fma_f32 v[54:55], v[150:151], v[212:213], v[54:55]
	v_pk_fma_f32 v[56:57], v[152:153], v[214:215], v[56:57]
	v_pk_fma_f32 v[58:59], v[154:155], v[216:217], v[58:59]
	v_pk_fma_f32 v[60:61], v[156:157], v[218:219], v[60:61]
	v_pk_fma_f32 v[62:63], v[158:159], v[220:221], v[62:63]
	v_pk_fma_f32 v[64:65], v[160:161], v[210:211], v[64:65]
	v_pk_fma_f32 v[66:67], v[162:163], v[212:213], v[66:67]
	v_pk_fma_f32 v[68:69], v[164:165], v[214:215], v[68:69]
	v_pk_fma_f32 v[70:71], v[166:167], v[216:217], v[70:71]
	v_pk_fma_f32 v[72:73], v[168:169], v[218:219], v[72:73]
	v_pk_fma_f32 v[74:75], v[170:171], v[220:221], v[74:75]
	v_pk_fma_f32 v[76:77], v[172:173], v[210:211], v[76:77]
	v_pk_fma_f32 v[78:79], v[174:175], v[212:213], v[78:79]
	v_pk_fma_f32 v[80:81], v[176:177], v[214:215], v[80:81]
	v_pk_fma_f32 v[82:83], v[178:179], v[216:217], v[82:83]
	v_pk_fma_f32 v[84:85], v[180:181], v[218:219], v[84:85]
	v_pk_fma_f32 v[86:87], v[182:183], v[220:221], v[86:87]
	v_pk_fma_f32 v[88:89], v[184:185], v[210:211], v[88:89]
	v_pk_fma_f32 v[90:91], v[186:187], v[212:213], v[90:91]
	v_pk_fma_f32 v[92:93], v[188:189], v[214:215], v[92:93]
	v_pk_fma_f32 v[94:95], v[190:191], v[216:217], v[94:95]
	v_pk_fma_f32 v[96:97], v[192:193], v[218:219], v[96:97]
	v_pk_fma_f32 v[98:99], v[194:195], v[220:221], v[98:99]
	global_load_dwordx4 v[210:213], v2, s[50:51]
	global_load_dwordx4 v[214:217], v2, s[50:51] offset:1024
	global_load_dwordx4 v[218:221], v2, s[50:51] offset:2048
	s_add_u32 s50, s50, 0xc00
	s_addc_u32 s51, s51, 0
	s_add_i32 s52, s41, -14
	s_cmp_lt_i32 s52, 0
	s_cbranch_scc1 .Lcv_z16_zero
	v_lshlrev_b32_e32 v100, 16, v234
	v_and_b32_e32 v101, 0xffff0000, v234
	v_lshlrev_b32_e32 v102, 16, v235
	v_and_b32_e32 v103, 0xffff0000, v235
	v_lshlrev_b32_e32 v104, 16, v236
	v_and_b32_e32 v105, 0xffff0000, v236
	v_lshlrev_b32_e32 v106, 16, v237
	v_and_b32_e32 v107, 0xffff0000, v237
	v_lshlrev_b32_e32 v108, 16, v238
	v_and_b32_e32 v109, 0xffff0000, v238
	v_lshlrev_b32_e32 v110, 16, v239
	v_and_b32_e32 v111, 0xffff0000, v239
	s_branch .Lcv_z16_done

.Lcv_z16_done:
	s_add_i32 s52, s41, -10
	s_max_i32 s52, s52, 0
	s_mulk_i32 s52, 0x600
	v_add_u32_e32 v196, s52, v3
	global_load_dwordx2 v[234:235], v196, s[38:39]
	global_load_dwordx2 v[236:237], v196, s[38:39] offset:512
	global_load_dwordx2 v[238:239], v196, s[38:39] offset:1024
	s_waitcnt vmcnt(9)
	v_pk_fma_f32 v[4:5], v[112:113], v[222:223], v[4:5]
	v_pk_fma_f32 v[6:7], v[114:115], v[224:225], v[6:7]
	v_pk_fma_f32 v[8:9], v[116:117], v[226:227], v[8:9]
	v_pk_fma_f32 v[10:11], v[118:119], v[228:229], v[10:11]
	v_pk_fma_f32 v[12:13], v[120:121], v[230:231], v[12:13]
	v_pk_fma_f32 v[14:15], v[122:123], v[232:233], v[14:15]
	v_pk_fma_f32 v[16:17], v[124:125], v[222:223], v[16:17]
	v_pk_fma_f32 v[18:19], v[126:127], v[224:225], v[18:19]
	v_pk_fma_f32 v[20:21], v[128:129], v[226:227], v[20:21]
	v_pk_fma_f32 v[22:23], v[130:131], v[228:229], v[22:23]
	v_pk_fma_f32 v[24:25], v[132:133], v[230:231], v[24:25]
	v_pk_fma_f32 v[26:27], v[134:135], v[232:233], v[26:27]
	v_pk_fma_f32 v[28:29], v[136:137], v[222:223], v[28:29]
	v_pk_fma_f32 v[30:31], v[138:139], v[224:225], v[30:31]
	v_pk_fma_f32 v[32:33], v[140:141], v[226:227], v[32:33]
	v_pk_fma_f32 v[34:35], v[142:143], v[228:229], v[34:35]
	v_pk_fma_f32 v[36:37], v[144:145], v[230:231], v[36:37]
	v_pk_fma_f32 v[38:39], v[146:147], v[232:233], v[38:39]
	v_pk_fma_f32 v[40:41], v[148:149], v[222:223], v[40:41]
	v_pk_fma_f32 v[42:43], v[150:151], v[224:225], v[42:43]
	v_pk_fma_f32 v[44:45], v[152:153], v[226:227], v[44:45]
	v_pk_fma_f32 v[46:47], v[154:155], v[228:229], v[46:47]
	v_pk_fma_f32 v[48:49], v[156:157], v[230:231], v[48:49]
	v_pk_fma_f32 v[50:51], v[158:159], v[232:233], v[50:51]
	v_pk_fma_f32 v[52:53], v[160:161], v[222:223], v[52:53]
	v_pk_fma_f32 v[54:55], v[162:163], v[224:225], v[54:55]
	v_pk_fma_f32 v[56:57], v[164:165], v[226:227], v[56:57]
	v_pk_fma_f32 v[58:59], v[166:167], v[228:229], v[58:59]
	v_pk_fma_f32 v[60:61], v[168:169], v[230:231], v[60:61]
	v_pk_fma_f32 v[62:63], v[170:171], v[232:233], v[62:63]
	v_pk_fma_f32 v[64:65], v[172:173], v[222:223], v[64:65]
	v_pk_fma_f32 v[66:67], v[174:175], v[224:225], v[66:67]
	v_pk_fma_f32 v[68:69], v[176:177], v[226:227], v[68:69]
	v_pk_fma_f32 v[70:71], v[178:179], v[228:229], v[70:71]
	v_pk_fma_f32 v[72:73], v[180:181], v[230:231], v[72:73]
	v_pk_fma_f32 v[74:75], v[182:183], v[232:233], v[74:75]
	v_pk_fma_f32 v[76:77], v[184:185], v[222:223], v[76:77]
	v_pk_fma_f32 v[78:79], v[186:187], v[224:225], v[78:79]
	v_pk_fma_f32 v[80:81], v[188:189], v[226:227], v[80:81]
	v_pk_fma_f32 v[82:83], v[190:191], v[228:229], v[82:83]
	v_pk_fma_f32 v[84:85], v[192:193], v[230:231], v[84:85]
	v_pk_fma_f32 v[86:87], v[194:195], v[232:233], v[86:87]
	v_pk_fma_f32 v[88:89], v[100:101], v[222:223], v[88:89]
	v_pk_fma_f32 v[90:91], v[102:103], v[224:225], v[90:91]
	v_pk_fma_f32 v[92:93], v[104:105], v[226:227], v[92:93]
	v_pk_fma_f32 v[94:95], v[106:107], v[228:229], v[94:95]
	v_pk_fma_f32 v[96:97], v[108:109], v[230:231], v[96:97]
	v_pk_fma_f32 v[98:99], v[110:111], v[232:233], v[98:99]
	global_load_dwordx4 v[222:225], v2, s[50:51]
	global_load_dwordx4 v[226:229], v2, s[50:51] offset:1024
	global_load_dwordx4 v[230:233], v2, s[50:51] offset:2048
	s_add_u32 s50, s50, 0xc00
	s_addc_u32 s51, s51, 0
	s_add_i32 s52, s41, -13
	s_cmp_lt_i32 s52, 0
	s_cbranch_scc1 .Lcv_z17_zero
	v_lshlrev_b32_e32 v112, 16, v240
	v_and_b32_e32 v113, 0xffff0000, v240
	v_lshlrev_b32_e32 v114, 16, v241
	v_and_b32_e32 v115, 0xffff0000, v241
	v_lshlrev_b32_e32 v116, 16, v242
	v_and_b32_e32 v117, 0xffff0000, v242
	v_lshlrev_b32_e32 v118, 16, v243
	v_and_b32_e32 v119, 0xffff0000, v243
	v_lshlrev_b32_e32 v120, 16, v244
	v_and_b32_e32 v121, 0xffff0000, v244
	v_lshlrev_b32_e32 v122, 16, v245
	v_and_b32_e32 v123, 0xffff0000, v245
	s_branch .Lcv_z17_done

.Lcv_z17_done:
	s_add_i32 s52, s41, -9
	s_max_i32 s52, s52, 0
	s_mulk_i32 s52, 0x600
	v_add_u32_e32 v196, s52, v3
	global_load_dwordx2 v[240:241], v196, s[38:39]
	global_load_dwordx2 v[242:243], v196, s[38:39] offset:512
	global_load_dwordx2 v[244:245], v196, s[38:39] offset:1024
	s_waitcnt vmcnt(9)
	v_pk_fma_f32 v[4:5], v[124:125], v[210:211], v[4:5]
	v_pk_fma_f32 v[6:7], v[126:127], v[212:213], v[6:7]
	v_pk_fma_f32 v[8:9], v[128:129], v[214:215], v[8:9]
	v_pk_fma_f32 v[10:11], v[130:131], v[216:217], v[10:11]
	v_pk_fma_f32 v[12:13], v[132:133], v[218:219], v[12:13]
	v_pk_fma_f32 v[14:15], v[134:135], v[220:221], v[14:15]
	v_pk_fma_f32 v[16:17], v[136:137], v[210:211], v[16:17]
	v_pk_fma_f32 v[18:19], v[138:139], v[212:213], v[18:19]
	v_pk_fma_f32 v[20:21], v[140:141], v[214:215], v[20:21]
	v_pk_fma_f32 v[22:23], v[142:143], v[216:217], v[22:23]
	v_pk_fma_f32 v[24:25], v[144:145], v[218:219], v[24:25]
	v_pk_fma_f32 v[26:27], v[146:147], v[220:221], v[26:27]
	v_pk_fma_f32 v[28:29], v[148:149], v[210:211], v[28:29]
	v_pk_fma_f32 v[30:31], v[150:151], v[212:213], v[30:31]
	v_pk_fma_f32 v[32:33], v[152:153], v[214:215], v[32:33]
	v_pk_fma_f32 v[34:35], v[154:155], v[216:217], v[34:35]
	v_pk_fma_f32 v[36:37], v[156:157], v[218:219], v[36:37]
	v_pk_fma_f32 v[38:39], v[158:159], v[220:221], v[38:39]
	v_pk_fma_f32 v[40:41], v[160:161], v[210:211], v[40:41]
	v_pk_fma_f32 v[42:43], v[162:163], v[212:213], v[42:43]
	v_pk_fma_f32 v[44:45], v[164:165], v[214:215], v[44:45]
	v_pk_fma_f32 v[46:47], v[166:167], v[216:217], v[46:47]
	v_pk_fma_f32 v[48:49], v[168:169], v[218:219], v[48:49]
	v_pk_fma_f32 v[50:51], v[170:171], v[220:221], v[50:51]
	v_pk_fma_f32 v[52:53], v[172:173], v[210:211], v[52:53]
	v_pk_fma_f32 v[54:55], v[174:175], v[212:213], v[54:55]
	v_pk_fma_f32 v[56:57], v[176:177], v[214:215], v[56:57]
	v_pk_fma_f32 v[58:59], v[178:179], v[216:217], v[58:59]
	v_pk_fma_f32 v[60:61], v[180:181], v[218:219], v[60:61]
	v_pk_fma_f32 v[62:63], v[182:183], v[220:221], v[62:63]
	v_pk_fma_f32 v[64:65], v[184:185], v[210:211], v[64:65]
	v_pk_fma_f32 v[66:67], v[186:187], v[212:213], v[66:67]
	v_pk_fma_f32 v[68:69], v[188:189], v[214:215], v[68:69]
	v_pk_fma_f32 v[70:71], v[190:191], v[216:217], v[70:71]
	v_pk_fma_f32 v[72:73], v[192:193], v[218:219], v[72:73]
	v_pk_fma_f32 v[74:75], v[194:195], v[220:221], v[74:75]
	v_pk_fma_f32 v[76:77], v[100:101], v[210:211], v[76:77]
	v_pk_fma_f32 v[78:79], v[102:103], v[212:213], v[78:79]
	v_pk_fma_f32 v[80:81], v[104:105], v[214:215], v[80:81]
	v_pk_fma_f32 v[82:83], v[106:107], v[216:217], v[82:83]
	v_pk_fma_f32 v[84:85], v[108:109], v[218:219], v[84:85]
	v_pk_fma_f32 v[86:87], v[110:111], v[220:221], v[86:87]
	v_pk_fma_f32 v[88:89], v[112:113], v[210:211], v[88:89]
	v_pk_fma_f32 v[90:91], v[114:115], v[212:213], v[90:91]
	v_pk_fma_f32 v[92:93], v[116:117], v[214:215], v[92:93]
	v_pk_fma_f32 v[94:95], v[118:119], v[216:217], v[94:95]
	v_pk_fma_f32 v[96:97], v[120:121], v[218:219], v[96:97]
	v_pk_fma_f32 v[98:99], v[122:123], v[220:221], v[98:99]
	global_load_dwordx4 v[210:213], v2, s[50:51]
	global_load_dwordx4 v[214:217], v2, s[50:51] offset:1024
	global_load_dwordx4 v[218:221], v2, s[50:51] offset:2048
	s_add_u32 s50, s50, 0xc00
	s_addc_u32 s51, s51, 0
	s_add_i32 s52, s41, -12
	s_cmp_lt_i32 s52, 0
	s_cbranch_scc1 .Lcv_z18_zero
	v_lshlrev_b32_e32 v124, 16, v246
	v_and_b32_e32 v125, 0xffff0000, v246
	v_lshlrev_b32_e32 v126, 16, v247
	v_and_b32_e32 v127, 0xffff0000, v247
	v_lshlrev_b32_e32 v128, 16, v248
	v_and_b32_e32 v129, 0xffff0000, v248
	v_lshlrev_b32_e32 v130, 16, v249
	v_and_b32_e32 v131, 0xffff0000, v249
	v_lshlrev_b32_e32 v132, 16, v250
	v_and_b32_e32 v133, 0xffff0000, v250
	v_lshlrev_b32_e32 v134, 16, v251
	v_and_b32_e32 v135, 0xffff0000, v251
	s_branch .Lcv_z18_done

.Lcv_z18_done:
	s_add_i32 s52, s41, -8
	s_max_i32 s52, s52, 0
	s_mulk_i32 s52, 0x600
	v_add_u32_e32 v196, s52, v3
	global_load_dwordx2 v[246:247], v196, s[38:39]
	global_load_dwordx2 v[248:249], v196, s[38:39] offset:512
	global_load_dwordx2 v[250:251], v196, s[38:39] offset:1024
	s_waitcnt vmcnt(9)
	v_pk_fma_f32 v[4:5], v[136:137], v[222:223], v[4:5]
	v_pk_fma_f32 v[6:7], v[138:139], v[224:225], v[6:7]
	v_pk_fma_f32 v[8:9], v[140:141], v[226:227], v[8:9]
	v_pk_fma_f32 v[10:11], v[142:143], v[228:229], v[10:11]
	v_pk_fma_f32 v[12:13], v[144:145], v[230:231], v[12:13]
	v_pk_fma_f32 v[14:15], v[146:147], v[232:233], v[14:15]
	v_pk_fma_f32 v[16:17], v[148:149], v[222:223], v[16:17]
	v_pk_fma_f32 v[18:19], v[150:151], v[224:225], v[18:19]
	v_pk_fma_f32 v[20:21], v[152:153], v[226:227], v[20:21]
	v_pk_fma_f32 v[22:23], v[154:155], v[228:229], v[22:23]
	v_pk_fma_f32 v[24:25], v[156:157], v[230:231], v[24:25]
	v_pk_fma_f32 v[26:27], v[158:159], v[232:233], v[26:27]
	v_pk_fma_f32 v[28:29], v[160:161], v[222:223], v[28:29]
	v_pk_fma_f32 v[30:31], v[162:163], v[224:225], v[30:31]
	v_pk_fma_f32 v[32:33], v[164:165], v[226:227], v[32:33]
	v_pk_fma_f32 v[34:35], v[166:167], v[228:229], v[34:35]
	v_pk_fma_f32 v[36:37], v[168:169], v[230:231], v[36:37]
	v_pk_fma_f32 v[38:39], v[170:171], v[232:233], v[38:39]
	v_pk_fma_f32 v[40:41], v[172:173], v[222:223], v[40:41]
	v_pk_fma_f32 v[42:43], v[174:175], v[224:225], v[42:43]
	v_pk_fma_f32 v[44:45], v[176:177], v[226:227], v[44:45]
	v_pk_fma_f32 v[46:47], v[178:179], v[228:229], v[46:47]
	v_pk_fma_f32 v[48:49], v[180:181], v[230:231], v[48:49]
	v_pk_fma_f32 v[50:51], v[182:183], v[232:233], v[50:51]
	v_pk_fma_f32 v[52:53], v[184:185], v[222:223], v[52:53]
	v_pk_fma_f32 v[54:55], v[186:187], v[224:225], v[54:55]
	v_pk_fma_f32 v[56:57], v[188:189], v[226:227], v[56:57]
	v_pk_fma_f32 v[58:59], v[190:191], v[228:229], v[58:59]
	v_pk_fma_f32 v[60:61], v[192:193], v[230:231], v[60:61]
	v_pk_fma_f32 v[62:63], v[194:195], v[232:233], v[62:63]
	v_pk_fma_f32 v[64:65], v[100:101], v[222:223], v[64:65]
	v_pk_fma_f32 v[66:67], v[102:103], v[224:225], v[66:67]
	v_pk_fma_f32 v[68:69], v[104:105], v[226:227], v[68:69]
	v_pk_fma_f32 v[70:71], v[106:107], v[228:229], v[70:71]
	v_pk_fma_f32 v[72:73], v[108:109], v[230:231], v[72:73]
	v_pk_fma_f32 v[74:75], v[110:111], v[232:233], v[74:75]
	v_pk_fma_f32 v[76:77], v[112:113], v[222:223], v[76:77]
	v_pk_fma_f32 v[78:79], v[114:115], v[224:225], v[78:79]
	v_pk_fma_f32 v[80:81], v[116:117], v[226:227], v[80:81]
	v_pk_fma_f32 v[82:83], v[118:119], v[228:229], v[82:83]
	v_pk_fma_f32 v[84:85], v[120:121], v[230:231], v[84:85]
	v_pk_fma_f32 v[86:87], v[122:123], v[232:233], v[86:87]
	v_pk_fma_f32 v[88:89], v[124:125], v[222:223], v[88:89]
	v_pk_fma_f32 v[90:91], v[126:127], v[224:225], v[90:91]
	v_pk_fma_f32 v[92:93], v[128:129], v[226:227], v[92:93]
	v_pk_fma_f32 v[94:95], v[130:131], v[228:229], v[94:95]
	v_pk_fma_f32 v[96:97], v[132:133], v[230:231], v[96:97]
	v_pk_fma_f32 v[98:99], v[134:135], v[232:233], v[98:99]
	global_load_dwordx4 v[222:225], v2, s[50:51]
	global_load_dwordx4 v[226:229], v2, s[50:51] offset:1024
	global_load_dwordx4 v[230:233], v2, s[50:51] offset:2048
	s_add_u32 s50, s50, 0xc00
	s_addc_u32 s51, s51, 0
	s_add_i32 s52, s41, -11
	s_cmp_lt_i32 s52, 0
	s_cbranch_scc1 .Lcv_z19_zero
	v_lshlrev_b32_e32 v136, 16, v204
	v_and_b32_e32 v137, 0xffff0000, v204
	v_lshlrev_b32_e32 v138, 16, v205
	v_and_b32_e32 v139, 0xffff0000, v205
	v_lshlrev_b32_e32 v140, 16, v206
	v_and_b32_e32 v141, 0xffff0000, v206
	v_lshlrev_b32_e32 v142, 16, v207
	v_and_b32_e32 v143, 0xffff0000, v207
	v_lshlrev_b32_e32 v144, 16, v252
	v_and_b32_e32 v145, 0xffff0000, v252
	v_lshlrev_b32_e32 v146, 16, v253
	v_and_b32_e32 v147, 0xffff0000, v253
	s_branch .Lcv_z19_done

.Lcv_z19_done:
	s_add_i32 s52, s41, -7
	s_max_i32 s52, s52, 0
	s_mulk_i32 s52, 0x600
	v_add_u32_e32 v196, s52, v3
	global_load_dwordx2 v[204:205], v196, s[38:39]
	global_load_dwordx2 v[206:207], v196, s[38:39] offset:512
	global_load_dwordx2 v[252:253], v196, s[38:39] offset:1024
	s_waitcnt vmcnt(9)
	v_pk_fma_f32 v[4:5], v[148:149], v[210:211], v[4:5]
	v_pk_fma_f32 v[6:7], v[150:151], v[212:213], v[6:7]
	v_pk_fma_f32 v[8:9], v[152:153], v[214:215], v[8:9]
	v_pk_fma_f32 v[10:11], v[154:155], v[216:217], v[10:11]
	v_pk_fma_f32 v[12:13], v[156:157], v[218:219], v[12:13]
	v_pk_fma_f32 v[14:15], v[158:159], v[220:221], v[14:15]
	v_pk_fma_f32 v[16:17], v[160:161], v[210:211], v[16:17]
	v_pk_fma_f32 v[18:19], v[162:163], v[212:213], v[18:19]
	v_pk_fma_f32 v[20:21], v[164:165], v[214:215], v[20:21]
	v_pk_fma_f32 v[22:23], v[166:167], v[216:217], v[22:23]
	v_pk_fma_f32 v[24:25], v[168:169], v[218:219], v[24:25]
	v_pk_fma_f32 v[26:27], v[170:171], v[220:221], v[26:27]
	v_pk_fma_f32 v[28:29], v[172:173], v[210:211], v[28:29]
	v_pk_fma_f32 v[30:31], v[174:175], v[212:213], v[30:31]
	v_pk_fma_f32 v[32:33], v[176:177], v[214:215], v[32:33]
	v_pk_fma_f32 v[34:35], v[178:179], v[216:217], v[34:35]
	v_pk_fma_f32 v[36:37], v[180:181], v[218:219], v[36:37]
	v_pk_fma_f32 v[38:39], v[182:183], v[220:221], v[38:39]
	v_pk_fma_f32 v[40:41], v[184:185], v[210:211], v[40:41]
	v_pk_fma_f32 v[42:43], v[186:187], v[212:213], v[42:43]
	v_pk_fma_f32 v[44:45], v[188:189], v[214:215], v[44:45]
	v_pk_fma_f32 v[46:47], v[190:191], v[216:217], v[46:47]
	v_pk_fma_f32 v[48:49], v[192:193], v[218:219], v[48:49]
	v_pk_fma_f32 v[50:51], v[194:195], v[220:221], v[50:51]
	v_pk_fma_f32 v[52:53], v[100:101], v[210:211], v[52:53]
	v_pk_fma_f32 v[54:55], v[102:103], v[212:213], v[54:55]
	v_pk_fma_f32 v[56:57], v[104:105], v[214:215], v[56:57]
	v_pk_fma_f32 v[58:59], v[106:107], v[216:217], v[58:59]
	v_pk_fma_f32 v[60:61], v[108:109], v[218:219], v[60:61]
	v_pk_fma_f32 v[62:63], v[110:111], v[220:221], v[62:63]
	v_pk_fma_f32 v[64:65], v[112:113], v[210:211], v[64:65]
	v_pk_fma_f32 v[66:67], v[114:115], v[212:213], v[66:67]
	v_pk_fma_f32 v[68:69], v[116:117], v[214:215], v[68:69]
	v_pk_fma_f32 v[70:71], v[118:119], v[216:217], v[70:71]
	v_pk_fma_f32 v[72:73], v[120:121], v[218:219], v[72:73]
	v_pk_fma_f32 v[74:75], v[122:123], v[220:221], v[74:75]
	v_pk_fma_f32 v[76:77], v[124:125], v[210:211], v[76:77]
	v_pk_fma_f32 v[78:79], v[126:127], v[212:213], v[78:79]
	v_pk_fma_f32 v[80:81], v[128:129], v[214:215], v[80:81]
	v_pk_fma_f32 v[82:83], v[130:131], v[216:217], v[82:83]
	v_pk_fma_f32 v[84:85], v[132:133], v[218:219], v[84:85]
	v_pk_fma_f32 v[86:87], v[134:135], v[220:221], v[86:87]
	v_pk_fma_f32 v[88:89], v[136:137], v[210:211], v[88:89]
	v_pk_fma_f32 v[90:91], v[138:139], v[212:213], v[90:91]
	v_pk_fma_f32 v[92:93], v[140:141], v[214:215], v[92:93]
	v_pk_fma_f32 v[94:95], v[142:143], v[216:217], v[94:95]
	v_pk_fma_f32 v[96:97], v[144:145], v[218:219], v[96:97]
	v_pk_fma_f32 v[98:99], v[146:147], v[220:221], v[98:99]
	global_load_dwordx4 v[210:213], v2, s[50:51]
	global_load_dwordx4 v[214:217], v2, s[50:51] offset:1024
	global_load_dwordx4 v[218:221], v2, s[50:51] offset:2048
	s_add_u32 s50, s50, 0xc00
	s_addc_u32 s51, s51, 0
	s_add_i32 s52, s41, -10
	s_cmp_lt_i32 s52, 0
	s_cbranch_scc1 .Lcv_z20_zero
	v_lshlrev_b32_e32 v148, 16, v234
	v_and_b32_e32 v149, 0xffff0000, v234
	v_lshlrev_b32_e32 v150, 16, v235
	v_and_b32_e32 v151, 0xffff0000, v235
	v_lshlrev_b32_e32 v152, 16, v236
	v_and_b32_e32 v153, 0xffff0000, v236
	v_lshlrev_b32_e32 v154, 16, v237
	v_and_b32_e32 v155, 0xffff0000, v237
	v_lshlrev_b32_e32 v156, 16, v238
	v_and_b32_e32 v157, 0xffff0000, v238
	v_lshlrev_b32_e32 v158, 16, v239
	v_and_b32_e32 v159, 0xffff0000, v239
	s_branch .Lcv_z20_done

.Lcv_z20_done:
	s_add_i32 s52, s41, -6
	s_max_i32 s52, s52, 0
	s_mulk_i32 s52, 0x600
	v_add_u32_e32 v196, s52, v3
	global_load_dwordx2 v[234:235], v196, s[38:39]
	global_load_dwordx2 v[236:237], v196, s[38:39] offset:512
	global_load_dwordx2 v[238:239], v196, s[38:39] offset:1024
	s_waitcnt vmcnt(9)
	v_pk_fma_f32 v[4:5], v[160:161], v[222:223], v[4:5]
	v_pk_fma_f32 v[6:7], v[162:163], v[224:225], v[6:7]
	v_pk_fma_f32 v[8:9], v[164:165], v[226:227], v[8:9]
	v_pk_fma_f32 v[10:11], v[166:167], v[228:229], v[10:11]
	v_pk_fma_f32 v[12:13], v[168:169], v[230:231], v[12:13]
	v_pk_fma_f32 v[14:15], v[170:171], v[232:233], v[14:15]
	v_pk_fma_f32 v[16:17], v[172:173], v[222:223], v[16:17]
	v_pk_fma_f32 v[18:19], v[174:175], v[224:225], v[18:19]
	v_pk_fma_f32 v[20:21], v[176:177], v[226:227], v[20:21]
	v_pk_fma_f32 v[22:23], v[178:179], v[228:229], v[22:23]
	v_pk_fma_f32 v[24:25], v[180:181], v[230:231], v[24:25]
	v_pk_fma_f32 v[26:27], v[182:183], v[232:233], v[26:27]
	v_pk_fma_f32 v[28:29], v[184:185], v[222:223], v[28:29]
	v_pk_fma_f32 v[30:31], v[186:187], v[224:225], v[30:31]
	v_pk_fma_f32 v[32:33], v[188:189], v[226:227], v[32:33]
	v_pk_fma_f32 v[34:35], v[190:191], v[228:229], v[34:35]
	v_pk_fma_f32 v[36:37], v[192:193], v[230:231], v[36:37]
	v_pk_fma_f32 v[38:39], v[194:195], v[232:233], v[38:39]
	v_pk_fma_f32 v[40:41], v[100:101], v[222:223], v[40:41]
	v_pk_fma_f32 v[42:43], v[102:103], v[224:225], v[42:43]
	v_pk_fma_f32 v[44:45], v[104:105], v[226:227], v[44:45]
	v_pk_fma_f32 v[46:47], v[106:107], v[228:229], v[46:47]
	v_pk_fma_f32 v[48:49], v[108:109], v[230:231], v[48:49]
	v_pk_fma_f32 v[50:51], v[110:111], v[232:233], v[50:51]
	v_pk_fma_f32 v[52:53], v[112:113], v[222:223], v[52:53]
	v_pk_fma_f32 v[54:55], v[114:115], v[224:225], v[54:55]
	v_pk_fma_f32 v[56:57], v[116:117], v[226:227], v[56:57]
	v_pk_fma_f32 v[58:59], v[118:119], v[228:229], v[58:59]
	v_pk_fma_f32 v[60:61], v[120:121], v[230:231], v[60:61]
	v_pk_fma_f32 v[62:63], v[122:123], v[232:233], v[62:63]
	v_pk_fma_f32 v[64:65], v[124:125], v[222:223], v[64:65]
	v_pk_fma_f32 v[66:67], v[126:127], v[224:225], v[66:67]
	v_pk_fma_f32 v[68:69], v[128:129], v[226:227], v[68:69]
	v_pk_fma_f32 v[70:71], v[130:131], v[228:229], v[70:71]
	v_pk_fma_f32 v[72:73], v[132:133], v[230:231], v[72:73]
	v_pk_fma_f32 v[74:75], v[134:135], v[232:233], v[74:75]
	v_pk_fma_f32 v[76:77], v[136:137], v[222:223], v[76:77]
	v_pk_fma_f32 v[78:79], v[138:139], v[224:225], v[78:79]
	v_pk_fma_f32 v[80:81], v[140:141], v[226:227], v[80:81]
	v_pk_fma_f32 v[82:83], v[142:143], v[228:229], v[82:83]
	v_pk_fma_f32 v[84:85], v[144:145], v[230:231], v[84:85]
	v_pk_fma_f32 v[86:87], v[146:147], v[232:233], v[86:87]
	v_pk_fma_f32 v[88:89], v[148:149], v[222:223], v[88:89]
	v_pk_fma_f32 v[90:91], v[150:151], v[224:225], v[90:91]
	v_pk_fma_f32 v[92:93], v[152:153], v[226:227], v[92:93]
	v_pk_fma_f32 v[94:95], v[154:155], v[228:229], v[94:95]
	v_pk_fma_f32 v[96:97], v[156:157], v[230:231], v[96:97]
	v_pk_fma_f32 v[98:99], v[158:159], v[232:233], v[98:99]
	global_load_dwordx4 v[222:225], v2, s[50:51]
	global_load_dwordx4 v[226:229], v2, s[50:51] offset:1024
	global_load_dwordx4 v[230:233], v2, s[50:51] offset:2048
	s_add_u32 s50, s50, 0xc00
	s_addc_u32 s51, s51, 0
	s_add_i32 s52, s41, -9
	s_cmp_lt_i32 s52, 0
	s_cbranch_scc1 .Lcv_z21_zero
	v_lshlrev_b32_e32 v160, 16, v240
	v_and_b32_e32 v161, 0xffff0000, v240
	v_lshlrev_b32_e32 v162, 16, v241
	v_and_b32_e32 v163, 0xffff0000, v241
	v_lshlrev_b32_e32 v164, 16, v242
	v_and_b32_e32 v165, 0xffff0000, v242
	v_lshlrev_b32_e32 v166, 16, v243
	v_and_b32_e32 v167, 0xffff0000, v243
	v_lshlrev_b32_e32 v168, 16, v244
	v_and_b32_e32 v169, 0xffff0000, v244
	v_lshlrev_b32_e32 v170, 16, v245
	v_and_b32_e32 v171, 0xffff0000, v245
	s_branch .Lcv_z21_done

.Lcv_z21_done:
	s_add_i32 s52, s41, -5
	s_max_i32 s52, s52, 0
	s_mulk_i32 s52, 0x600
	v_add_u32_e32 v196, s52, v3
	global_load_dwordx2 v[240:241], v196, s[38:39]
	global_load_dwordx2 v[242:243], v196, s[38:39] offset:512
	global_load_dwordx2 v[244:245], v196, s[38:39] offset:1024
	s_waitcnt vmcnt(9)
	v_pk_fma_f32 v[4:5], v[172:173], v[210:211], v[4:5]
	v_pk_fma_f32 v[6:7], v[174:175], v[212:213], v[6:7]
	v_pk_fma_f32 v[8:9], v[176:177], v[214:215], v[8:9]
	v_pk_fma_f32 v[10:11], v[178:179], v[216:217], v[10:11]
	v_pk_fma_f32 v[12:13], v[180:181], v[218:219], v[12:13]
	v_pk_fma_f32 v[14:15], v[182:183], v[220:221], v[14:15]
	v_pk_fma_f32 v[16:17], v[184:185], v[210:211], v[16:17]
	v_pk_fma_f32 v[18:19], v[186:187], v[212:213], v[18:19]
	v_pk_fma_f32 v[20:21], v[188:189], v[214:215], v[20:21]
	v_pk_fma_f32 v[22:23], v[190:191], v[216:217], v[22:23]
	v_pk_fma_f32 v[24:25], v[192:193], v[218:219], v[24:25]
	v_pk_fma_f32 v[26:27], v[194:195], v[220:221], v[26:27]
	v_pk_fma_f32 v[28:29], v[100:101], v[210:211], v[28:29]
	v_pk_fma_f32 v[30:31], v[102:103], v[212:213], v[30:31]
	v_pk_fma_f32 v[32:33], v[104:105], v[214:215], v[32:33]
	v_pk_fma_f32 v[34:35], v[106:107], v[216:217], v[34:35]
	v_pk_fma_f32 v[36:37], v[108:109], v[218:219], v[36:37]
	v_pk_fma_f32 v[38:39], v[110:111], v[220:221], v[38:39]
	v_pk_fma_f32 v[40:41], v[112:113], v[210:211], v[40:41]
	v_pk_fma_f32 v[42:43], v[114:115], v[212:213], v[42:43]
	v_pk_fma_f32 v[44:45], v[116:117], v[214:215], v[44:45]
	v_pk_fma_f32 v[46:47], v[118:119], v[216:217], v[46:47]
	v_pk_fma_f32 v[48:49], v[120:121], v[218:219], v[48:49]
	v_pk_fma_f32 v[50:51], v[122:123], v[220:221], v[50:51]
	v_pk_fma_f32 v[52:53], v[124:125], v[210:211], v[52:53]
	v_pk_fma_f32 v[54:55], v[126:127], v[212:213], v[54:55]
	v_pk_fma_f32 v[56:57], v[128:129], v[214:215], v[56:57]
	v_pk_fma_f32 v[58:59], v[130:131], v[216:217], v[58:59]
	v_pk_fma_f32 v[60:61], v[132:133], v[218:219], v[60:61]
	v_pk_fma_f32 v[62:63], v[134:135], v[220:221], v[62:63]
	v_pk_fma_f32 v[64:65], v[136:137], v[210:211], v[64:65]
	v_pk_fma_f32 v[66:67], v[138:139], v[212:213], v[66:67]
	v_pk_fma_f32 v[68:69], v[140:141], v[214:215], v[68:69]
	v_pk_fma_f32 v[70:71], v[142:143], v[216:217], v[70:71]
	v_pk_fma_f32 v[72:73], v[144:145], v[218:219], v[72:73]
	v_pk_fma_f32 v[74:75], v[146:147], v[220:221], v[74:75]
	v_pk_fma_f32 v[76:77], v[148:149], v[210:211], v[76:77]
	v_pk_fma_f32 v[78:79], v[150:151], v[212:213], v[78:79]
	v_pk_fma_f32 v[80:81], v[152:153], v[214:215], v[80:81]
	v_pk_fma_f32 v[82:83], v[154:155], v[216:217], v[82:83]
	v_pk_fma_f32 v[84:85], v[156:157], v[218:219], v[84:85]
	v_pk_fma_f32 v[86:87], v[158:159], v[220:221], v[86:87]
	v_pk_fma_f32 v[88:89], v[160:161], v[210:211], v[88:89]
	v_pk_fma_f32 v[90:91], v[162:163], v[212:213], v[90:91]
	v_pk_fma_f32 v[92:93], v[164:165], v[214:215], v[92:93]
	v_pk_fma_f32 v[94:95], v[166:167], v[216:217], v[94:95]
	v_pk_fma_f32 v[96:97], v[168:169], v[218:219], v[96:97]
	v_pk_fma_f32 v[98:99], v[170:171], v[220:221], v[98:99]
	global_load_dwordx4 v[210:213], v2, s[50:51]
	global_load_dwordx4 v[214:217], v2, s[50:51] offset:1024
	global_load_dwordx4 v[218:221], v2, s[50:51] offset:2048
	s_add_u32 s50, s50, 0xc00
	s_addc_u32 s51, s51, 0
	s_add_i32 s52, s41, -8
	s_cmp_lt_i32 s52, 0
	s_cbranch_scc1 .Lcv_z22_zero
	v_lshlrev_b32_e32 v172, 16, v246
	v_and_b32_e32 v173, 0xffff0000, v246
	v_lshlrev_b32_e32 v174, 16, v247
	v_and_b32_e32 v175, 0xffff0000, v247
	v_lshlrev_b32_e32 v176, 16, v248
	v_and_b32_e32 v177, 0xffff0000, v248
	v_lshlrev_b32_e32 v178, 16, v249
	v_and_b32_e32 v179, 0xffff0000, v249
	v_lshlrev_b32_e32 v180, 16, v250
	v_and_b32_e32 v181, 0xffff0000, v250
	v_lshlrev_b32_e32 v182, 16, v251
	v_and_b32_e32 v183, 0xffff0000, v251
	s_branch .Lcv_z22_done

.Lcv_z22_done:
	s_add_i32 s52, s41, -4
	s_max_i32 s52, s52, 0
	s_mulk_i32 s52, 0x600
	v_add_u32_e32 v196, s52, v3
	global_load_dwordx2 v[246:247], v196, s[38:39]
	global_load_dwordx2 v[248:249], v196, s[38:39] offset:512
	global_load_dwordx2 v[250:251], v196, s[38:39] offset:1024
	s_waitcnt vmcnt(9)
	v_pk_fma_f32 v[4:5], v[184:185], v[222:223], v[4:5]
	v_pk_fma_f32 v[6:7], v[186:187], v[224:225], v[6:7]
	v_pk_fma_f32 v[8:9], v[188:189], v[226:227], v[8:9]
	v_pk_fma_f32 v[10:11], v[190:191], v[228:229], v[10:11]
	v_pk_fma_f32 v[12:13], v[192:193], v[230:231], v[12:13]
	v_pk_fma_f32 v[14:15], v[194:195], v[232:233], v[14:15]
	v_pk_fma_f32 v[16:17], v[100:101], v[222:223], v[16:17]
	v_pk_fma_f32 v[18:19], v[102:103], v[224:225], v[18:19]
	v_pk_fma_f32 v[20:21], v[104:105], v[226:227], v[20:21]
	v_pk_fma_f32 v[22:23], v[106:107], v[228:229], v[22:23]
	v_pk_fma_f32 v[24:25], v[108:109], v[230:231], v[24:25]
	v_pk_fma_f32 v[26:27], v[110:111], v[232:233], v[26:27]
	v_pk_fma_f32 v[28:29], v[112:113], v[222:223], v[28:29]
	v_pk_fma_f32 v[30:31], v[114:115], v[224:225], v[30:31]
	v_pk_fma_f32 v[32:33], v[116:117], v[226:227], v[32:33]
	v_pk_fma_f32 v[34:35], v[118:119], v[228:229], v[34:35]
	v_pk_fma_f32 v[36:37], v[120:121], v[230:231], v[36:37]
	v_pk_fma_f32 v[38:39], v[122:123], v[232:233], v[38:39]
	v_pk_fma_f32 v[40:41], v[124:125], v[222:223], v[40:41]
	v_pk_fma_f32 v[42:43], v[126:127], v[224:225], v[42:43]
	v_pk_fma_f32 v[44:45], v[128:129], v[226:227], v[44:45]
	v_pk_fma_f32 v[46:47], v[130:131], v[228:229], v[46:47]
	v_pk_fma_f32 v[48:49], v[132:133], v[230:231], v[48:49]
	v_pk_fma_f32 v[50:51], v[134:135], v[232:233], v[50:51]
	v_pk_fma_f32 v[52:53], v[136:137], v[222:223], v[52:53]
	v_pk_fma_f32 v[54:55], v[138:139], v[224:225], v[54:55]
	v_pk_fma_f32 v[56:57], v[140:141], v[226:227], v[56:57]
	v_pk_fma_f32 v[58:59], v[142:143], v[228:229], v[58:59]
	v_pk_fma_f32 v[60:61], v[144:145], v[230:231], v[60:61]
	v_pk_fma_f32 v[62:63], v[146:147], v[232:233], v[62:63]
	v_pk_fma_f32 v[64:65], v[148:149], v[222:223], v[64:65]
	v_pk_fma_f32 v[66:67], v[150:151], v[224:225], v[66:67]
	v_pk_fma_f32 v[68:69], v[152:153], v[226:227], v[68:69]
	v_pk_fma_f32 v[70:71], v[154:155], v[228:229], v[70:71]
	v_pk_fma_f32 v[72:73], v[156:157], v[230:231], v[72:73]
	v_pk_fma_f32 v[74:75], v[158:159], v[232:233], v[74:75]
	v_pk_fma_f32 v[76:77], v[160:161], v[222:223], v[76:77]
	v_pk_fma_f32 v[78:79], v[162:163], v[224:225], v[78:79]
	v_pk_fma_f32 v[80:81], v[164:165], v[226:227], v[80:81]
	v_pk_fma_f32 v[82:83], v[166:167], v[228:229], v[82:83]
	v_pk_fma_f32 v[84:85], v[168:169], v[230:231], v[84:85]
	v_pk_fma_f32 v[86:87], v[170:171], v[232:233], v[86:87]
	v_pk_fma_f32 v[88:89], v[172:173], v[222:223], v[88:89]
	v_pk_fma_f32 v[90:91], v[174:175], v[224:225], v[90:91]
	v_pk_fma_f32 v[92:93], v[176:177], v[226:227], v[92:93]
	v_pk_fma_f32 v[94:95], v[178:179], v[228:229], v[94:95]
	v_pk_fma_f32 v[96:97], v[180:181], v[230:231], v[96:97]
	v_pk_fma_f32 v[98:99], v[182:183], v[232:233], v[98:99]
	global_load_dwordx4 v[222:225], v2, s[50:51]
	global_load_dwordx4 v[226:229], v2, s[50:51] offset:1024
	global_load_dwordx4 v[230:233], v2, s[50:51] offset:2048
	s_add_u32 s50, s50, 0xc00
	s_addc_u32 s51, s51, 0
	s_add_i32 s52, s41, -7
	s_cmp_lt_i32 s52, 0
	s_cbranch_scc1 .Lcv_z23_zero
	v_lshlrev_b32_e32 v184, 16, v204
	v_and_b32_e32 v185, 0xffff0000, v204
	v_lshlrev_b32_e32 v186, 16, v205
	v_and_b32_e32 v187, 0xffff0000, v205
	v_lshlrev_b32_e32 v188, 16, v206
	v_and_b32_e32 v189, 0xffff0000, v206
	v_lshlrev_b32_e32 v190, 16, v207
	v_and_b32_e32 v191, 0xffff0000, v207
	v_lshlrev_b32_e32 v192, 16, v252
	v_and_b32_e32 v193, 0xffff0000, v252
	v_lshlrev_b32_e32 v194, 16, v253
	v_and_b32_e32 v195, 0xffff0000, v253
	s_branch .Lcv_z23_done

.Lcv_z23_done:
	s_add_i32 s52, s41, -3
	s_max_i32 s52, s52, 0
	s_mulk_i32 s52, 0x600
	v_add_u32_e32 v196, s52, v3
	global_load_dwordx2 v[204:205], v196, s[38:39]
	global_load_dwordx2 v[206:207], v196, s[38:39] offset:512
	global_load_dwordx2 v[252:253], v196, s[38:39] offset:1024
	s_waitcnt vmcnt(9)
	v_pk_fma_f32 v[4:5], v[100:101], v[210:211], v[4:5]
	v_pk_fma_f32 v[6:7], v[102:103], v[212:213], v[6:7]
	v_pk_fma_f32 v[8:9], v[104:105], v[214:215], v[8:9]
	v_pk_fma_f32 v[10:11], v[106:107], v[216:217], v[10:11]
	v_pk_fma_f32 v[12:13], v[108:109], v[218:219], v[12:13]
	v_pk_fma_f32 v[14:15], v[110:111], v[220:221], v[14:15]
	v_pk_fma_f32 v[16:17], v[112:113], v[210:211], v[16:17]
	v_pk_fma_f32 v[18:19], v[114:115], v[212:213], v[18:19]
	v_pk_fma_f32 v[20:21], v[116:117], v[214:215], v[20:21]
	v_pk_fma_f32 v[22:23], v[118:119], v[216:217], v[22:23]
	v_pk_fma_f32 v[24:25], v[120:121], v[218:219], v[24:25]
	v_pk_fma_f32 v[26:27], v[122:123], v[220:221], v[26:27]
	v_pk_fma_f32 v[28:29], v[124:125], v[210:211], v[28:29]
	v_pk_fma_f32 v[30:31], v[126:127], v[212:213], v[30:31]
	v_pk_fma_f32 v[32:33], v[128:129], v[214:215], v[32:33]
	v_pk_fma_f32 v[34:35], v[130:131], v[216:217], v[34:35]
	v_pk_fma_f32 v[36:37], v[132:133], v[218:219], v[36:37]
	v_pk_fma_f32 v[38:39], v[134:135], v[220:221], v[38:39]
	v_pk_fma_f32 v[40:41], v[136:137], v[210:211], v[40:41]
	v_pk_fma_f32 v[42:43], v[138:139], v[212:213], v[42:43]
	v_pk_fma_f32 v[44:45], v[140:141], v[214:215], v[44:45]
	v_pk_fma_f32 v[46:47], v[142:143], v[216:217], v[46:47]
	v_pk_fma_f32 v[48:49], v[144:145], v[218:219], v[48:49]
	v_pk_fma_f32 v[50:51], v[146:147], v[220:221], v[50:51]
	v_pk_fma_f32 v[52:53], v[148:149], v[210:211], v[52:53]
	v_pk_fma_f32 v[54:55], v[150:151], v[212:213], v[54:55]
	v_pk_fma_f32 v[56:57], v[152:153], v[214:215], v[56:57]
	v_pk_fma_f32 v[58:59], v[154:155], v[216:217], v[58:59]
	v_pk_fma_f32 v[60:61], v[156:157], v[218:219], v[60:61]
	v_pk_fma_f32 v[62:63], v[158:159], v[220:221], v[62:63]
	v_pk_fma_f32 v[64:65], v[160:161], v[210:211], v[64:65]
	v_pk_fma_f32 v[66:67], v[162:163], v[212:213], v[66:67]
	v_pk_fma_f32 v[68:69], v[164:165], v[214:215], v[68:69]
	v_pk_fma_f32 v[70:71], v[166:167], v[216:217], v[70:71]
	v_pk_fma_f32 v[72:73], v[168:169], v[218:219], v[72:73]
	v_pk_fma_f32 v[74:75], v[170:171], v[220:221], v[74:75]
	v_pk_fma_f32 v[76:77], v[172:173], v[210:211], v[76:77]
	v_pk_fma_f32 v[78:79], v[174:175], v[212:213], v[78:79]
	v_pk_fma_f32 v[80:81], v[176:177], v[214:215], v[80:81]
	v_pk_fma_f32 v[82:83], v[178:179], v[216:217], v[82:83]
	v_pk_fma_f32 v[84:85], v[180:181], v[218:219], v[84:85]
	v_pk_fma_f32 v[86:87], v[182:183], v[220:221], v[86:87]
	v_pk_fma_f32 v[88:89], v[184:185], v[210:211], v[88:89]
	v_pk_fma_f32 v[90:91], v[186:187], v[212:213], v[90:91]
	v_pk_fma_f32 v[92:93], v[188:189], v[214:215], v[92:93]
	v_pk_fma_f32 v[94:95], v[190:191], v[216:217], v[94:95]
	v_pk_fma_f32 v[96:97], v[192:193], v[218:219], v[96:97]
	v_pk_fma_f32 v[98:99], v[194:195], v[220:221], v[98:99]
	global_load_dwordx4 v[210:213], v2, s[50:51]
	global_load_dwordx4 v[214:217], v2, s[50:51] offset:1024
	global_load_dwordx4 v[218:221], v2, s[50:51] offset:2048
	s_add_u32 s50, s50, 0xc00
	s_addc_u32 s51, s51, 0
	s_add_i32 s52, s41, -6
	s_cmp_lt_i32 s52, 0
	s_cbranch_scc1 .Lcv_z24_zero
	v_lshlrev_b32_e32 v100, 16, v234
	v_and_b32_e32 v101, 0xffff0000, v234
	v_lshlrev_b32_e32 v102, 16, v235
	v_and_b32_e32 v103, 0xffff0000, v235
	v_lshlrev_b32_e32 v104, 16, v236
	v_and_b32_e32 v105, 0xffff0000, v236
	v_lshlrev_b32_e32 v106, 16, v237
	v_and_b32_e32 v107, 0xffff0000, v237
	v_lshlrev_b32_e32 v108, 16, v238
	v_and_b32_e32 v109, 0xffff0000, v238
	v_lshlrev_b32_e32 v110, 16, v239
	v_and_b32_e32 v111, 0xffff0000, v239
	s_branch .Lcv_z24_done

.Lcv_z24_done:
	s_add_i32 s52, s41, -2
	s_max_i32 s52, s52, 0
	s_mulk_i32 s52, 0x600
	v_add_u32_e32 v196, s52, v3
	global_load_dwordx2 v[234:235], v196, s[38:39]
	global_load_dwordx2 v[236:237], v196, s[38:39] offset:512
	global_load_dwordx2 v[238:239], v196, s[38:39] offset:1024
	s_waitcnt vmcnt(9)
	v_pk_fma_f32 v[4:5], v[112:113], v[222:223], v[4:5]
	v_pk_fma_f32 v[6:7], v[114:115], v[224:225], v[6:7]
	v_pk_fma_f32 v[8:9], v[116:117], v[226:227], v[8:9]
	v_pk_fma_f32 v[10:11], v[118:119], v[228:229], v[10:11]
	v_pk_fma_f32 v[12:13], v[120:121], v[230:231], v[12:13]
	v_pk_fma_f32 v[14:15], v[122:123], v[232:233], v[14:15]
	v_pk_fma_f32 v[16:17], v[124:125], v[222:223], v[16:17]
	v_pk_fma_f32 v[18:19], v[126:127], v[224:225], v[18:19]
	v_pk_fma_f32 v[20:21], v[128:129], v[226:227], v[20:21]
	v_pk_fma_f32 v[22:23], v[130:131], v[228:229], v[22:23]
	v_pk_fma_f32 v[24:25], v[132:133], v[230:231], v[24:25]
	v_pk_fma_f32 v[26:27], v[134:135], v[232:233], v[26:27]
	v_pk_fma_f32 v[28:29], v[136:137], v[222:223], v[28:29]
	v_pk_fma_f32 v[30:31], v[138:139], v[224:225], v[30:31]
	v_pk_fma_f32 v[32:33], v[140:141], v[226:227], v[32:33]
	v_pk_fma_f32 v[34:35], v[142:143], v[228:229], v[34:35]
	v_pk_fma_f32 v[36:37], v[144:145], v[230:231], v[36:37]
	v_pk_fma_f32 v[38:39], v[146:147], v[232:233], v[38:39]
	v_pk_fma_f32 v[40:41], v[148:149], v[222:223], v[40:41]
	v_pk_fma_f32 v[42:43], v[150:151], v[224:225], v[42:43]
	v_pk_fma_f32 v[44:45], v[152:153], v[226:227], v[44:45]
	v_pk_fma_f32 v[46:47], v[154:155], v[228:229], v[46:47]
	v_pk_fma_f32 v[48:49], v[156:157], v[230:231], v[48:49]
	v_pk_fma_f32 v[50:51], v[158:159], v[232:233], v[50:51]
	v_pk_fma_f32 v[52:53], v[160:161], v[222:223], v[52:53]
	v_pk_fma_f32 v[54:55], v[162:163], v[224:225], v[54:55]
	v_pk_fma_f32 v[56:57], v[164:165], v[226:227], v[56:57]
	v_pk_fma_f32 v[58:59], v[166:167], v[228:229], v[58:59]
	v_pk_fma_f32 v[60:61], v[168:169], v[230:231], v[60:61]
	v_pk_fma_f32 v[62:63], v[170:171], v[232:233], v[62:63]
	v_pk_fma_f32 v[64:65], v[172:173], v[222:223], v[64:65]
	v_pk_fma_f32 v[66:67], v[174:175], v[224:225], v[66:67]
	v_pk_fma_f32 v[68:69], v[176:177], v[226:227], v[68:69]
	v_pk_fma_f32 v[70:71], v[178:179], v[228:229], v[70:71]
	v_pk_fma_f32 v[72:73], v[180:181], v[230:231], v[72:73]
	v_pk_fma_f32 v[74:75], v[182:183], v[232:233], v[74:75]
	v_pk_fma_f32 v[76:77], v[184:185], v[222:223], v[76:77]
	v_pk_fma_f32 v[78:79], v[186:187], v[224:225], v[78:79]
	v_pk_fma_f32 v[80:81], v[188:189], v[226:227], v[80:81]
	v_pk_fma_f32 v[82:83], v[190:191], v[228:229], v[82:83]
	v_pk_fma_f32 v[84:85], v[192:193], v[230:231], v[84:85]
	v_pk_fma_f32 v[86:87], v[194:195], v[232:233], v[86:87]
	v_pk_fma_f32 v[88:89], v[100:101], v[222:223], v[88:89]
	v_pk_fma_f32 v[90:91], v[102:103], v[224:225], v[90:91]
	v_pk_fma_f32 v[92:93], v[104:105], v[226:227], v[92:93]
	v_pk_fma_f32 v[94:95], v[106:107], v[228:229], v[94:95]
	v_pk_fma_f32 v[96:97], v[108:109], v[230:231], v[96:97]
	v_pk_fma_f32 v[98:99], v[110:111], v[232:233], v[98:99]
	global_load_dwordx4 v[222:225], v2, s[50:51]
	global_load_dwordx4 v[226:229], v2, s[50:51] offset:1024
	global_load_dwordx4 v[230:233], v2, s[50:51] offset:2048
	s_add_u32 s50, s50, 0xc00
	s_addc_u32 s51, s51, 0
	s_add_i32 s52, s41, -5
	s_cmp_lt_i32 s52, 0
	s_cbranch_scc1 .Lcv_z25_zero
	v_lshlrev_b32_e32 v112, 16, v240
	v_and_b32_e32 v113, 0xffff0000, v240
	v_lshlrev_b32_e32 v114, 16, v241
	v_and_b32_e32 v115, 0xffff0000, v241
	v_lshlrev_b32_e32 v116, 16, v242
	v_and_b32_e32 v117, 0xffff0000, v242
	v_lshlrev_b32_e32 v118, 16, v243
	v_and_b32_e32 v119, 0xffff0000, v243
	v_lshlrev_b32_e32 v120, 16, v244
	v_and_b32_e32 v121, 0xffff0000, v244
	v_lshlrev_b32_e32 v122, 16, v245
	v_and_b32_e32 v123, 0xffff0000, v245
	s_branch .Lcv_z25_done

.Lcv_z25_done:
	s_add_i32 s52, s41, -1
	s_max_i32 s52, s52, 0
	s_mulk_i32 s52, 0x600
	v_add_u32_e32 v196, s52, v3
	global_load_dwordx2 v[240:241], v196, s[38:39]
	global_load_dwordx2 v[242:243], v196, s[38:39] offset:512
	global_load_dwordx2 v[244:245], v196, s[38:39] offset:1024
	s_waitcnt vmcnt(9)
	v_pk_fma_f32 v[4:5], v[124:125], v[210:211], v[4:5]
	v_pk_fma_f32 v[6:7], v[126:127], v[212:213], v[6:7]
	v_pk_fma_f32 v[8:9], v[128:129], v[214:215], v[8:9]
	v_pk_fma_f32 v[10:11], v[130:131], v[216:217], v[10:11]
	v_pk_fma_f32 v[12:13], v[132:133], v[218:219], v[12:13]
	v_pk_fma_f32 v[14:15], v[134:135], v[220:221], v[14:15]
	v_pk_fma_f32 v[16:17], v[136:137], v[210:211], v[16:17]
	v_pk_fma_f32 v[18:19], v[138:139], v[212:213], v[18:19]
	v_pk_fma_f32 v[20:21], v[140:141], v[214:215], v[20:21]
	v_pk_fma_f32 v[22:23], v[142:143], v[216:217], v[22:23]
	v_pk_fma_f32 v[24:25], v[144:145], v[218:219], v[24:25]
	v_pk_fma_f32 v[26:27], v[146:147], v[220:221], v[26:27]
	v_pk_fma_f32 v[28:29], v[148:149], v[210:211], v[28:29]
	v_pk_fma_f32 v[30:31], v[150:151], v[212:213], v[30:31]
	v_pk_fma_f32 v[32:33], v[152:153], v[214:215], v[32:33]
	v_pk_fma_f32 v[34:35], v[154:155], v[216:217], v[34:35]
	v_pk_fma_f32 v[36:37], v[156:157], v[218:219], v[36:37]
	v_pk_fma_f32 v[38:39], v[158:159], v[220:221], v[38:39]
	v_pk_fma_f32 v[40:41], v[160:161], v[210:211], v[40:41]
	v_pk_fma_f32 v[42:43], v[162:163], v[212:213], v[42:43]
	v_pk_fma_f32 v[44:45], v[164:165], v[214:215], v[44:45]
	v_pk_fma_f32 v[46:47], v[166:167], v[216:217], v[46:47]
	v_pk_fma_f32 v[48:49], v[168:169], v[218:219], v[48:49]
	v_pk_fma_f32 v[50:51], v[170:171], v[220:221], v[50:51]
	v_pk_fma_f32 v[52:53], v[172:173], v[210:211], v[52:53]
	v_pk_fma_f32 v[54:55], v[174:175], v[212:213], v[54:55]
	v_pk_fma_f32 v[56:57], v[176:177], v[214:215], v[56:57]
	v_pk_fma_f32 v[58:59], v[178:179], v[216:217], v[58:59]
	v_pk_fma_f32 v[60:61], v[180:181], v[218:219], v[60:61]
	v_pk_fma_f32 v[62:63], v[182:183], v[220:221], v[62:63]
	v_pk_fma_f32 v[64:65], v[184:185], v[210:211], v[64:65]
	v_pk_fma_f32 v[66:67], v[186:187], v[212:213], v[66:67]
	v_pk_fma_f32 v[68:69], v[188:189], v[214:215], v[68:69]
	v_pk_fma_f32 v[70:71], v[190:191], v[216:217], v[70:71]
	v_pk_fma_f32 v[72:73], v[192:193], v[218:219], v[72:73]
	v_pk_fma_f32 v[74:75], v[194:195], v[220:221], v[74:75]
	v_pk_fma_f32 v[76:77], v[100:101], v[210:211], v[76:77]
	v_pk_fma_f32 v[78:79], v[102:103], v[212:213], v[78:79]
	v_pk_fma_f32 v[80:81], v[104:105], v[214:215], v[80:81]
	v_pk_fma_f32 v[82:83], v[106:107], v[216:217], v[82:83]
	v_pk_fma_f32 v[84:85], v[108:109], v[218:219], v[84:85]
	v_pk_fma_f32 v[86:87], v[110:111], v[220:221], v[86:87]
	v_pk_fma_f32 v[88:89], v[112:113], v[210:211], v[88:89]
	v_pk_fma_f32 v[90:91], v[114:115], v[212:213], v[90:91]
	v_pk_fma_f32 v[92:93], v[116:117], v[214:215], v[92:93]
	v_pk_fma_f32 v[94:95], v[118:119], v[216:217], v[94:95]
	v_pk_fma_f32 v[96:97], v[120:121], v[218:219], v[96:97]
	v_pk_fma_f32 v[98:99], v[122:123], v[220:221], v[98:99]
	global_load_dwordx4 v[210:213], v2, s[50:51]
	global_load_dwordx4 v[214:217], v2, s[50:51] offset:1024
	global_load_dwordx4 v[218:221], v2, s[50:51] offset:2048
	s_add_u32 s50, s50, 0xc00
	s_addc_u32 s51, s51, 0
	s_add_i32 s52, s41, -4
	s_cmp_lt_i32 s52, 0
	s_cbranch_scc1 .Lcv_z26_zero
	v_lshlrev_b32_e32 v124, 16, v246
	v_and_b32_e32 v125, 0xffff0000, v246
	v_lshlrev_b32_e32 v126, 16, v247
	v_and_b32_e32 v127, 0xffff0000, v247
	v_lshlrev_b32_e32 v128, 16, v248
	v_and_b32_e32 v129, 0xffff0000, v248
	v_lshlrev_b32_e32 v130, 16, v249
	v_and_b32_e32 v131, 0xffff0000, v249
	v_lshlrev_b32_e32 v132, 16, v250
	v_and_b32_e32 v133, 0xffff0000, v250
	v_lshlrev_b32_e32 v134, 16, v251
	v_and_b32_e32 v135, 0xffff0000, v251
	s_branch .Lcv_z26_done

.Lcv_z26_done:
	s_add_i32 s52, s41, 0
	s_mulk_i32 s52, 0x600
	v_add_u32_e32 v196, s52, v3
	global_load_dwordx2 v[246:247], v196, s[38:39]
	global_load_dwordx2 v[248:249], v196, s[38:39] offset:512
	global_load_dwordx2 v[250:251], v196, s[38:39] offset:1024
	s_waitcnt vmcnt(9)
	v_pk_fma_f32 v[4:5], v[136:137], v[222:223], v[4:5]
	v_pk_fma_f32 v[6:7], v[138:139], v[224:225], v[6:7]
	v_pk_fma_f32 v[8:9], v[140:141], v[226:227], v[8:9]
	v_pk_fma_f32 v[10:11], v[142:143], v[228:229], v[10:11]
	v_pk_fma_f32 v[12:13], v[144:145], v[230:231], v[12:13]
	v_pk_fma_f32 v[14:15], v[146:147], v[232:233], v[14:15]
	v_pk_fma_f32 v[16:17], v[148:149], v[222:223], v[16:17]
	v_pk_fma_f32 v[18:19], v[150:151], v[224:225], v[18:19]
	v_pk_fma_f32 v[20:21], v[152:153], v[226:227], v[20:21]
	v_pk_fma_f32 v[22:23], v[154:155], v[228:229], v[22:23]
	v_pk_fma_f32 v[24:25], v[156:157], v[230:231], v[24:25]
	v_pk_fma_f32 v[26:27], v[158:159], v[232:233], v[26:27]
	v_pk_fma_f32 v[28:29], v[160:161], v[222:223], v[28:29]
	v_pk_fma_f32 v[30:31], v[162:163], v[224:225], v[30:31]
	v_pk_fma_f32 v[32:33], v[164:165], v[226:227], v[32:33]
	v_pk_fma_f32 v[34:35], v[166:167], v[228:229], v[34:35]
	v_pk_fma_f32 v[36:37], v[168:169], v[230:231], v[36:37]
	v_pk_fma_f32 v[38:39], v[170:171], v[232:233], v[38:39]
	v_pk_fma_f32 v[40:41], v[172:173], v[222:223], v[40:41]
	v_pk_fma_f32 v[42:43], v[174:175], v[224:225], v[42:43]
	v_pk_fma_f32 v[44:45], v[176:177], v[226:227], v[44:45]
	v_pk_fma_f32 v[46:47], v[178:179], v[228:229], v[46:47]
	v_pk_fma_f32 v[48:49], v[180:181], v[230:231], v[48:49]
	v_pk_fma_f32 v[50:51], v[182:183], v[232:233], v[50:51]
	v_pk_fma_f32 v[52:53], v[184:185], v[222:223], v[52:53]
	v_pk_fma_f32 v[54:55], v[186:187], v[224:225], v[54:55]
	v_pk_fma_f32 v[56:57], v[188:189], v[226:227], v[56:57]
	v_pk_fma_f32 v[58:59], v[190:191], v[228:229], v[58:59]
	v_pk_fma_f32 v[60:61], v[192:193], v[230:231], v[60:61]
	v_pk_fma_f32 v[62:63], v[194:195], v[232:233], v[62:63]
	v_pk_fma_f32 v[64:65], v[100:101], v[222:223], v[64:65]
	v_pk_fma_f32 v[66:67], v[102:103], v[224:225], v[66:67]
	v_pk_fma_f32 v[68:69], v[104:105], v[226:227], v[68:69]
	v_pk_fma_f32 v[70:71], v[106:107], v[228:229], v[70:71]
	v_pk_fma_f32 v[72:73], v[108:109], v[230:231], v[72:73]
	v_pk_fma_f32 v[74:75], v[110:111], v[232:233], v[74:75]
	v_pk_fma_f32 v[76:77], v[112:113], v[222:223], v[76:77]
	v_pk_fma_f32 v[78:79], v[114:115], v[224:225], v[78:79]
	v_pk_fma_f32 v[80:81], v[116:117], v[226:227], v[80:81]
	v_pk_fma_f32 v[82:83], v[118:119], v[228:229], v[82:83]
	v_pk_fma_f32 v[84:85], v[120:121], v[230:231], v[84:85]
	v_pk_fma_f32 v[86:87], v[122:123], v[232:233], v[86:87]
	v_pk_fma_f32 v[88:89], v[124:125], v[222:223], v[88:89]
	v_pk_fma_f32 v[90:91], v[126:127], v[224:225], v[90:91]
	v_pk_fma_f32 v[92:93], v[128:129], v[226:227], v[92:93]
	v_pk_fma_f32 v[94:95], v[130:131], v[228:229], v[94:95]
	v_pk_fma_f32 v[96:97], v[132:133], v[230:231], v[96:97]
	v_pk_fma_f32 v[98:99], v[134:135], v[232:233], v[98:99]
	global_load_dwordx4 v[222:225], v2, s[50:51]
	global_load_dwordx4 v[226:229], v2, s[50:51] offset:1024
	global_load_dwordx4 v[230:233], v2, s[50:51] offset:2048
	s_add_u32 s50, s50, 0xc00
	s_addc_u32 s51, s51, 0
	s_add_i32 s52, s41, -3
	s_cmp_lt_i32 s52, 0
	s_cbranch_scc1 .Lcv_z27_zero
	v_lshlrev_b32_e32 v136, 16, v204
	v_and_b32_e32 v137, 0xffff0000, v204
	v_lshlrev_b32_e32 v138, 16, v205
	v_and_b32_e32 v139, 0xffff0000, v205
	v_lshlrev_b32_e32 v140, 16, v206
	v_and_b32_e32 v141, 0xffff0000, v206
	v_lshlrev_b32_e32 v142, 16, v207
	v_and_b32_e32 v143, 0xffff0000, v207
	v_lshlrev_b32_e32 v144, 16, v252
	v_and_b32_e32 v145, 0xffff0000, v252
	v_lshlrev_b32_e32 v146, 16, v253
	v_and_b32_e32 v147, 0xffff0000, v253
	s_branch .Lcv_z27_done

.Lcv_z27_done:
	s_add_i32 s52, s41, 1
	s_mulk_i32 s52, 0x600
	v_add_u32_e32 v196, s52, v3
	global_load_dwordx2 v[204:205], v196, s[38:39]
	global_load_dwordx2 v[206:207], v196, s[38:39] offset:512
	global_load_dwordx2 v[252:253], v196, s[38:39] offset:1024
	s_waitcnt vmcnt(9)
	v_pk_fma_f32 v[4:5], v[148:149], v[210:211], v[4:5]
	v_pk_fma_f32 v[6:7], v[150:151], v[212:213], v[6:7]
	v_pk_fma_f32 v[8:9], v[152:153], v[214:215], v[8:9]
	v_pk_fma_f32 v[10:11], v[154:155], v[216:217], v[10:11]
	v_pk_fma_f32 v[12:13], v[156:157], v[218:219], v[12:13]
	v_pk_fma_f32 v[14:15], v[158:159], v[220:221], v[14:15]
	v_pk_fma_f32 v[16:17], v[160:161], v[210:211], v[16:17]
	v_pk_fma_f32 v[18:19], v[162:163], v[212:213], v[18:19]
	v_pk_fma_f32 v[20:21], v[164:165], v[214:215], v[20:21]
	v_pk_fma_f32 v[22:23], v[166:167], v[216:217], v[22:23]
	v_pk_fma_f32 v[24:25], v[168:169], v[218:219], v[24:25]
	v_pk_fma_f32 v[26:27], v[170:171], v[220:221], v[26:27]
	v_pk_fma_f32 v[28:29], v[172:173], v[210:211], v[28:29]
	v_pk_fma_f32 v[30:31], v[174:175], v[212:213], v[30:31]
	v_pk_fma_f32 v[32:33], v[176:177], v[214:215], v[32:33]
	v_pk_fma_f32 v[34:35], v[178:179], v[216:217], v[34:35]
	v_pk_fma_f32 v[36:37], v[180:181], v[218:219], v[36:37]
	v_pk_fma_f32 v[38:39], v[182:183], v[220:221], v[38:39]
	v_pk_fma_f32 v[40:41], v[184:185], v[210:211], v[40:41]
	v_pk_fma_f32 v[42:43], v[186:187], v[212:213], v[42:43]
	v_pk_fma_f32 v[44:45], v[188:189], v[214:215], v[44:45]
	v_pk_fma_f32 v[46:47], v[190:191], v[216:217], v[46:47]
	v_pk_fma_f32 v[48:49], v[192:193], v[218:219], v[48:49]
	v_pk_fma_f32 v[50:51], v[194:195], v[220:221], v[50:51]
	v_pk_fma_f32 v[52:53], v[100:101], v[210:211], v[52:53]
	v_pk_fma_f32 v[54:55], v[102:103], v[212:213], v[54:55]
	v_pk_fma_f32 v[56:57], v[104:105], v[214:215], v[56:57]
	v_pk_fma_f32 v[58:59], v[106:107], v[216:217], v[58:59]
	v_pk_fma_f32 v[60:61], v[108:109], v[218:219], v[60:61]
	v_pk_fma_f32 v[62:63], v[110:111], v[220:221], v[62:63]
	v_pk_fma_f32 v[64:65], v[112:113], v[210:211], v[64:65]
	v_pk_fma_f32 v[66:67], v[114:115], v[212:213], v[66:67]
	v_pk_fma_f32 v[68:69], v[116:117], v[214:215], v[68:69]
	v_pk_fma_f32 v[70:71], v[118:119], v[216:217], v[70:71]
	v_pk_fma_f32 v[72:73], v[120:121], v[218:219], v[72:73]
	v_pk_fma_f32 v[74:75], v[122:123], v[220:221], v[74:75]
	v_pk_fma_f32 v[76:77], v[124:125], v[210:211], v[76:77]
	v_pk_fma_f32 v[78:79], v[126:127], v[212:213], v[78:79]
	v_pk_fma_f32 v[80:81], v[128:129], v[214:215], v[80:81]
	v_pk_fma_f32 v[82:83], v[130:131], v[216:217], v[82:83]
	v_pk_fma_f32 v[84:85], v[132:133], v[218:219], v[84:85]
	v_pk_fma_f32 v[86:87], v[134:135], v[220:221], v[86:87]
	v_pk_fma_f32 v[88:89], v[136:137], v[210:211], v[88:89]
	v_pk_fma_f32 v[90:91], v[138:139], v[212:213], v[90:91]
	v_pk_fma_f32 v[92:93], v[140:141], v[214:215], v[92:93]
	v_pk_fma_f32 v[94:95], v[142:143], v[216:217], v[94:95]
	v_pk_fma_f32 v[96:97], v[144:145], v[218:219], v[96:97]
	v_pk_fma_f32 v[98:99], v[146:147], v[220:221], v[98:99]
	global_load_dwordx4 v[210:213], v2, s[50:51]
	global_load_dwordx4 v[214:217], v2, s[50:51] offset:1024
	global_load_dwordx4 v[218:221], v2, s[50:51] offset:2048
	s_add_u32 s50, s50, 0xc00
	s_addc_u32 s51, s51, 0
	s_add_i32 s52, s41, -2
	s_cmp_lt_i32 s52, 0
	s_cbranch_scc1 .Lcv_z28_zero
	v_lshlrev_b32_e32 v148, 16, v234
	v_and_b32_e32 v149, 0xffff0000, v234
	v_lshlrev_b32_e32 v150, 16, v235
	v_and_b32_e32 v151, 0xffff0000, v235
	v_lshlrev_b32_e32 v152, 16, v236
	v_and_b32_e32 v153, 0xffff0000, v236
	v_lshlrev_b32_e32 v154, 16, v237
	v_and_b32_e32 v155, 0xffff0000, v237
	v_lshlrev_b32_e32 v156, 16, v238
	v_and_b32_e32 v157, 0xffff0000, v238
	v_lshlrev_b32_e32 v158, 16, v239
	v_and_b32_e32 v159, 0xffff0000, v239
	s_branch .Lcv_z28_done

.Lcv_z28_done:
	s_add_i32 s52, s41, 2
	s_mulk_i32 s52, 0x600
	v_add_u32_e32 v196, s52, v3
	global_load_dwordx2 v[234:235], v196, s[38:39]
	global_load_dwordx2 v[236:237], v196, s[38:39] offset:512
	global_load_dwordx2 v[238:239], v196, s[38:39] offset:1024
	s_waitcnt vmcnt(9)
	v_pk_fma_f32 v[4:5], v[160:161], v[222:223], v[4:5]
	v_pk_fma_f32 v[6:7], v[162:163], v[224:225], v[6:7]
	v_pk_fma_f32 v[8:9], v[164:165], v[226:227], v[8:9]
	v_pk_fma_f32 v[10:11], v[166:167], v[228:229], v[10:11]
	v_pk_fma_f32 v[12:13], v[168:169], v[230:231], v[12:13]
	v_pk_fma_f32 v[14:15], v[170:171], v[232:233], v[14:15]
	v_pk_fma_f32 v[16:17], v[172:173], v[222:223], v[16:17]
	v_pk_fma_f32 v[18:19], v[174:175], v[224:225], v[18:19]
	v_pk_fma_f32 v[20:21], v[176:177], v[226:227], v[20:21]
	v_pk_fma_f32 v[22:23], v[178:179], v[228:229], v[22:23]
	v_pk_fma_f32 v[24:25], v[180:181], v[230:231], v[24:25]
	v_pk_fma_f32 v[26:27], v[182:183], v[232:233], v[26:27]
	v_pk_fma_f32 v[28:29], v[184:185], v[222:223], v[28:29]
	v_pk_fma_f32 v[30:31], v[186:187], v[224:225], v[30:31]
	v_pk_fma_f32 v[32:33], v[188:189], v[226:227], v[32:33]
	v_pk_fma_f32 v[34:35], v[190:191], v[228:229], v[34:35]
	v_pk_fma_f32 v[36:37], v[192:193], v[230:231], v[36:37]
	v_pk_fma_f32 v[38:39], v[194:195], v[232:233], v[38:39]
	v_pk_fma_f32 v[40:41], v[100:101], v[222:223], v[40:41]
	v_pk_fma_f32 v[42:43], v[102:103], v[224:225], v[42:43]
	v_pk_fma_f32 v[44:45], v[104:105], v[226:227], v[44:45]
	v_pk_fma_f32 v[46:47], v[106:107], v[228:229], v[46:47]
	v_pk_fma_f32 v[48:49], v[108:109], v[230:231], v[48:49]
	v_pk_fma_f32 v[50:51], v[110:111], v[232:233], v[50:51]
	v_pk_fma_f32 v[52:53], v[112:113], v[222:223], v[52:53]
	v_pk_fma_f32 v[54:55], v[114:115], v[224:225], v[54:55]
	v_pk_fma_f32 v[56:57], v[116:117], v[226:227], v[56:57]
	v_pk_fma_f32 v[58:59], v[118:119], v[228:229], v[58:59]
	v_pk_fma_f32 v[60:61], v[120:121], v[230:231], v[60:61]
	v_pk_fma_f32 v[62:63], v[122:123], v[232:233], v[62:63]
	v_pk_fma_f32 v[64:65], v[124:125], v[222:223], v[64:65]
	v_pk_fma_f32 v[66:67], v[126:127], v[224:225], v[66:67]
	v_pk_fma_f32 v[68:69], v[128:129], v[226:227], v[68:69]
	v_pk_fma_f32 v[70:71], v[130:131], v[228:229], v[70:71]
	v_pk_fma_f32 v[72:73], v[132:133], v[230:231], v[72:73]
	v_pk_fma_f32 v[74:75], v[134:135], v[232:233], v[74:75]
	v_pk_fma_f32 v[76:77], v[136:137], v[222:223], v[76:77]
	v_pk_fma_f32 v[78:79], v[138:139], v[224:225], v[78:79]
	v_pk_fma_f32 v[80:81], v[140:141], v[226:227], v[80:81]
	v_pk_fma_f32 v[82:83], v[142:143], v[228:229], v[82:83]
	v_pk_fma_f32 v[84:85], v[144:145], v[230:231], v[84:85]
	v_pk_fma_f32 v[86:87], v[146:147], v[232:233], v[86:87]
	v_pk_fma_f32 v[88:89], v[148:149], v[222:223], v[88:89]
	v_pk_fma_f32 v[90:91], v[150:151], v[224:225], v[90:91]
	v_pk_fma_f32 v[92:93], v[152:153], v[226:227], v[92:93]
	v_pk_fma_f32 v[94:95], v[154:155], v[228:229], v[94:95]
	v_pk_fma_f32 v[96:97], v[156:157], v[230:231], v[96:97]
	v_pk_fma_f32 v[98:99], v[158:159], v[232:233], v[98:99]
	global_load_dwordx4 v[222:225], v2, s[50:51]
	global_load_dwordx4 v[226:229], v2, s[50:51] offset:1024
	global_load_dwordx4 v[230:233], v2, s[50:51] offset:2048
	s_add_u32 s50, s50, 0xc00
	s_addc_u32 s51, s51, 0
	s_add_i32 s52, s41, -1
	s_cmp_lt_i32 s52, 0
	s_cbranch_scc1 .Lcv_z29_zero
	v_lshlrev_b32_e32 v160, 16, v240
	v_and_b32_e32 v161, 0xffff0000, v240
	v_lshlrev_b32_e32 v162, 16, v241
	v_and_b32_e32 v163, 0xffff0000, v241
	v_lshlrev_b32_e32 v164, 16, v242
	v_and_b32_e32 v165, 0xffff0000, v242
	v_lshlrev_b32_e32 v166, 16, v243
	v_and_b32_e32 v167, 0xffff0000, v243
	v_lshlrev_b32_e32 v168, 16, v244
	v_and_b32_e32 v169, 0xffff0000, v244
	v_lshlrev_b32_e32 v170, 16, v245
	v_and_b32_e32 v171, 0xffff0000, v245
	s_branch .Lcv_z29_done

.Lcv_z29_done:
	s_add_i32 s52, s41, 3
	s_mulk_i32 s52, 0x600
	v_add_u32_e32 v196, s52, v3
	global_load_dwordx2 v[240:241], v196, s[38:39]
	global_load_dwordx2 v[242:243], v196, s[38:39] offset:512
	global_load_dwordx2 v[244:245], v196, s[38:39] offset:1024
	s_waitcnt vmcnt(9)
	v_pk_fma_f32 v[4:5], v[172:173], v[210:211], v[4:5]
	v_pk_fma_f32 v[6:7], v[174:175], v[212:213], v[6:7]
	v_pk_fma_f32 v[8:9], v[176:177], v[214:215], v[8:9]
	v_pk_fma_f32 v[10:11], v[178:179], v[216:217], v[10:11]
	v_pk_fma_f32 v[12:13], v[180:181], v[218:219], v[12:13]
	v_pk_fma_f32 v[14:15], v[182:183], v[220:221], v[14:15]
	v_pk_fma_f32 v[16:17], v[184:185], v[210:211], v[16:17]
	v_pk_fma_f32 v[18:19], v[186:187], v[212:213], v[18:19]
	v_pk_fma_f32 v[20:21], v[188:189], v[214:215], v[20:21]
	v_pk_fma_f32 v[22:23], v[190:191], v[216:217], v[22:23]
	v_pk_fma_f32 v[24:25], v[192:193], v[218:219], v[24:25]
	v_pk_fma_f32 v[26:27], v[194:195], v[220:221], v[26:27]
	v_pk_fma_f32 v[28:29], v[100:101], v[210:211], v[28:29]
	v_pk_fma_f32 v[30:31], v[102:103], v[212:213], v[30:31]
	v_pk_fma_f32 v[32:33], v[104:105], v[214:215], v[32:33]
	v_pk_fma_f32 v[34:35], v[106:107], v[216:217], v[34:35]
	v_pk_fma_f32 v[36:37], v[108:109], v[218:219], v[36:37]
	v_pk_fma_f32 v[38:39], v[110:111], v[220:221], v[38:39]
	v_pk_fma_f32 v[40:41], v[112:113], v[210:211], v[40:41]
	v_pk_fma_f32 v[42:43], v[114:115], v[212:213], v[42:43]
	v_pk_fma_f32 v[44:45], v[116:117], v[214:215], v[44:45]
	v_pk_fma_f32 v[46:47], v[118:119], v[216:217], v[46:47]
	v_pk_fma_f32 v[48:49], v[120:121], v[218:219], v[48:49]
	v_pk_fma_f32 v[50:51], v[122:123], v[220:221], v[50:51]
	v_pk_fma_f32 v[52:53], v[124:125], v[210:211], v[52:53]
	v_pk_fma_f32 v[54:55], v[126:127], v[212:213], v[54:55]
	v_pk_fma_f32 v[56:57], v[128:129], v[214:215], v[56:57]
	v_pk_fma_f32 v[58:59], v[130:131], v[216:217], v[58:59]
	v_pk_fma_f32 v[60:61], v[132:133], v[218:219], v[60:61]
	v_pk_fma_f32 v[62:63], v[134:135], v[220:221], v[62:63]
	v_pk_fma_f32 v[64:65], v[136:137], v[210:211], v[64:65]
	v_pk_fma_f32 v[66:67], v[138:139], v[212:213], v[66:67]
	v_pk_fma_f32 v[68:69], v[140:141], v[214:215], v[68:69]
	v_pk_fma_f32 v[70:71], v[142:143], v[216:217], v[70:71]
	v_pk_fma_f32 v[72:73], v[144:145], v[218:219], v[72:73]
	v_pk_fma_f32 v[74:75], v[146:147], v[220:221], v[74:75]
	v_pk_fma_f32 v[76:77], v[148:149], v[210:211], v[76:77]
	v_pk_fma_f32 v[78:79], v[150:151], v[212:213], v[78:79]
	v_pk_fma_f32 v[80:81], v[152:153], v[214:215], v[80:81]
	v_pk_fma_f32 v[82:83], v[154:155], v[216:217], v[82:83]
	v_pk_fma_f32 v[84:85], v[156:157], v[218:219], v[84:85]
	v_pk_fma_f32 v[86:87], v[158:159], v[220:221], v[86:87]
	v_pk_fma_f32 v[88:89], v[160:161], v[210:211], v[88:89]
	v_pk_fma_f32 v[90:91], v[162:163], v[212:213], v[90:91]
	v_pk_fma_f32 v[92:93], v[164:165], v[214:215], v[92:93]
	v_pk_fma_f32 v[94:95], v[166:167], v[216:217], v[94:95]
	v_pk_fma_f32 v[96:97], v[168:169], v[218:219], v[96:97]
	v_pk_fma_f32 v[98:99], v[170:171], v[220:221], v[98:99]
	global_load_dwordx4 v[210:213], v2, s[50:51]
	global_load_dwordx4 v[214:217], v2, s[50:51] offset:1024
	global_load_dwordx4 v[218:221], v2, s[50:51] offset:2048
	s_add_u32 s50, s50, 0xc00
	s_addc_u32 s51, s51, 0
	v_lshlrev_b32_e32 v172, 16, v246
	v_and_b32_e32 v173, 0xffff0000, v246
	v_lshlrev_b32_e32 v174, 16, v247
	v_and_b32_e32 v175, 0xffff0000, v247
	v_lshlrev_b32_e32 v176, 16, v248
	v_and_b32_e32 v177, 0xffff0000, v248
	v_lshlrev_b32_e32 v178, 16, v249
	v_and_b32_e32 v179, 0xffff0000, v249
	v_lshlrev_b32_e32 v180, 16, v250
	v_and_b32_e32 v181, 0xffff0000, v250
	v_lshlrev_b32_e32 v182, 16, v251
	v_and_b32_e32 v183, 0xffff0000, v251
	s_add_i32 s52, s41, 4
	s_mulk_i32 s52, 0x600
	v_add_u32_e32 v196, s52, v3
	global_load_dwordx2 v[246:247], v196, s[38:39]
	global_load_dwordx2 v[248:249], v196, s[38:39] offset:512
	global_load_dwordx2 v[250:251], v196, s[38:39] offset:1024
	s_waitcnt vmcnt(9)
	v_pk_fma_f32 v[4:5], v[184:185], v[222:223], v[4:5]
	v_pk_fma_f32 v[6:7], v[186:187], v[224:225], v[6:7]
	v_pk_fma_f32 v[8:9], v[188:189], v[226:227], v[8:9]
	v_pk_fma_f32 v[10:11], v[190:191], v[228:229], v[10:11]
	v_pk_fma_f32 v[12:13], v[192:193], v[230:231], v[12:13]
	v_pk_fma_f32 v[14:15], v[194:195], v[232:233], v[14:15]
	v_pk_fma_f32 v[16:17], v[100:101], v[222:223], v[16:17]
	v_pk_fma_f32 v[18:19], v[102:103], v[224:225], v[18:19]
	v_pk_fma_f32 v[20:21], v[104:105], v[226:227], v[20:21]
	v_pk_fma_f32 v[22:23], v[106:107], v[228:229], v[22:23]
	v_pk_fma_f32 v[24:25], v[108:109], v[230:231], v[24:25]
	v_pk_fma_f32 v[26:27], v[110:111], v[232:233], v[26:27]
	v_pk_fma_f32 v[28:29], v[112:113], v[222:223], v[28:29]
	v_pk_fma_f32 v[30:31], v[114:115], v[224:225], v[30:31]
	v_pk_fma_f32 v[32:33], v[116:117], v[226:227], v[32:33]
	v_pk_fma_f32 v[34:35], v[118:119], v[228:229], v[34:35]
	v_pk_fma_f32 v[36:37], v[120:121], v[230:231], v[36:37]
	v_pk_fma_f32 v[38:39], v[122:123], v[232:233], v[38:39]
	v_pk_fma_f32 v[40:41], v[124:125], v[222:223], v[40:41]
	v_pk_fma_f32 v[42:43], v[126:127], v[224:225], v[42:43]
	v_pk_fma_f32 v[44:45], v[128:129], v[226:227], v[44:45]
	v_pk_fma_f32 v[46:47], v[130:131], v[228:229], v[46:47]
	v_pk_fma_f32 v[48:49], v[132:133], v[230:231], v[48:49]
	v_pk_fma_f32 v[50:51], v[134:135], v[232:233], v[50:51]
	v_pk_fma_f32 v[52:53], v[136:137], v[222:223], v[52:53]
	v_pk_fma_f32 v[54:55], v[138:139], v[224:225], v[54:55]
	v_pk_fma_f32 v[56:57], v[140:141], v[226:227], v[56:57]
	v_pk_fma_f32 v[58:59], v[142:143], v[228:229], v[58:59]
	v_pk_fma_f32 v[60:61], v[144:145], v[230:231], v[60:61]
	v_pk_fma_f32 v[62:63], v[146:147], v[232:233], v[62:63]
	v_pk_fma_f32 v[64:65], v[148:149], v[222:223], v[64:65]
	v_pk_fma_f32 v[66:67], v[150:151], v[224:225], v[66:67]
	v_pk_fma_f32 v[68:69], v[152:153], v[226:227], v[68:69]
	v_pk_fma_f32 v[70:71], v[154:155], v[228:229], v[70:71]
	v_pk_fma_f32 v[72:73], v[156:157], v[230:231], v[72:73]
	v_pk_fma_f32 v[74:75], v[158:159], v[232:233], v[74:75]
	v_pk_fma_f32 v[76:77], v[160:161], v[222:223], v[76:77]
	v_pk_fma_f32 v[78:79], v[162:163], v[224:225], v[78:79]
	v_pk_fma_f32 v[80:81], v[164:165], v[226:227], v[80:81]
	v_pk_fma_f32 v[82:83], v[166:167], v[228:229], v[82:83]
	v_pk_fma_f32 v[84:85], v[168:169], v[230:231], v[84:85]
	v_pk_fma_f32 v[86:87], v[170:171], v[232:233], v[86:87]
	v_pk_fma_f32 v[88:89], v[172:173], v[222:223], v[88:89]
	v_pk_fma_f32 v[90:91], v[174:175], v[224:225], v[90:91]
	v_pk_fma_f32 v[92:93], v[176:177], v[226:227], v[92:93]
	v_pk_fma_f32 v[94:95], v[178:179], v[228:229], v[94:95]
	v_pk_fma_f32 v[96:97], v[180:181], v[230:231], v[96:97]
	v_pk_fma_f32 v[98:99], v[182:183], v[232:233], v[98:99]
	global_load_dwordx4 v[222:225], v2, s[50:51]
	global_load_dwordx4 v[226:229], v2, s[50:51] offset:1024
	global_load_dwordx4 v[230:233], v2, s[50:51] offset:2048
	s_add_u32 s50, s50, 0xc00
	s_addc_u32 s51, s51, 0
	v_lshlrev_b32_e32 v184, 16, v204
	v_and_b32_e32 v185, 0xffff0000, v204
	v_lshlrev_b32_e32 v186, 16, v205
	v_and_b32_e32 v187, 0xffff0000, v205
	v_lshlrev_b32_e32 v188, 16, v206
	v_and_b32_e32 v189, 0xffff0000, v206
	v_lshlrev_b32_e32 v190, 16, v207
	v_and_b32_e32 v191, 0xffff0000, v207
	v_lshlrev_b32_e32 v192, 16, v252
	v_and_b32_e32 v193, 0xffff0000, v252
	v_lshlrev_b32_e32 v194, 16, v253
	v_and_b32_e32 v195, 0xffff0000, v253
	s_add_i32 s52, s41, 5
	s_mulk_i32 s52, 0x600
	v_add_u32_e32 v196, s52, v3
	global_load_dwordx2 v[204:205], v196, s[38:39]
	global_load_dwordx2 v[206:207], v196, s[38:39] offset:512
	global_load_dwordx2 v[252:253], v196, s[38:39] offset:1024
	s_waitcnt vmcnt(9)
	v_pk_fma_f32 v[4:5], v[100:101], v[210:211], v[4:5]
	v_pk_fma_f32 v[6:7], v[102:103], v[212:213], v[6:7]
	v_pk_fma_f32 v[8:9], v[104:105], v[214:215], v[8:9]
	v_pk_fma_f32 v[10:11], v[106:107], v[216:217], v[10:11]
	v_pk_fma_f32 v[12:13], v[108:109], v[218:219], v[12:13]
	v_pk_fma_f32 v[14:15], v[110:111], v[220:221], v[14:15]
	v_pk_fma_f32 v[16:17], v[112:113], v[210:211], v[16:17]
	v_pk_fma_f32 v[18:19], v[114:115], v[212:213], v[18:19]
	v_pk_fma_f32 v[20:21], v[116:117], v[214:215], v[20:21]
	v_pk_fma_f32 v[22:23], v[118:119], v[216:217], v[22:23]
	v_pk_fma_f32 v[24:25], v[120:121], v[218:219], v[24:25]
	v_pk_fma_f32 v[26:27], v[122:123], v[220:221], v[26:27]
	v_pk_fma_f32 v[28:29], v[124:125], v[210:211], v[28:29]
	v_pk_fma_f32 v[30:31], v[126:127], v[212:213], v[30:31]
	v_pk_fma_f32 v[32:33], v[128:129], v[214:215], v[32:33]
	v_pk_fma_f32 v[34:35], v[130:131], v[216:217], v[34:35]
	v_pk_fma_f32 v[36:37], v[132:133], v[218:219], v[36:37]
	v_pk_fma_f32 v[38:39], v[134:135], v[220:221], v[38:39]
	v_pk_fma_f32 v[40:41], v[136:137], v[210:211], v[40:41]
	v_pk_fma_f32 v[42:43], v[138:139], v[212:213], v[42:43]
	v_pk_fma_f32 v[44:45], v[140:141], v[214:215], v[44:45]
	v_pk_fma_f32 v[46:47], v[142:143], v[216:217], v[46:47]
	v_pk_fma_f32 v[48:49], v[144:145], v[218:219], v[48:49]
	v_pk_fma_f32 v[50:51], v[146:147], v[220:221], v[50:51]
	v_pk_fma_f32 v[52:53], v[148:149], v[210:211], v[52:53]
	v_pk_fma_f32 v[54:55], v[150:151], v[212:213], v[54:55]
	v_pk_fma_f32 v[56:57], v[152:153], v[214:215], v[56:57]
	v_pk_fma_f32 v[58:59], v[154:155], v[216:217], v[58:59]
	v_pk_fma_f32 v[60:61], v[156:157], v[218:219], v[60:61]
	v_pk_fma_f32 v[62:63], v[158:159], v[220:221], v[62:63]
	v_pk_fma_f32 v[64:65], v[160:161], v[210:211], v[64:65]
	v_pk_fma_f32 v[66:67], v[162:163], v[212:213], v[66:67]
	v_pk_fma_f32 v[68:69], v[164:165], v[214:215], v[68:69]
	v_pk_fma_f32 v[70:71], v[166:167], v[216:217], v[70:71]
	v_pk_fma_f32 v[72:73], v[168:169], v[218:219], v[72:73]
	v_pk_fma_f32 v[74:75], v[170:171], v[220:221], v[74:75]
	v_pk_fma_f32 v[76:77], v[172:173], v[210:211], v[76:77]
	v_pk_fma_f32 v[78:79], v[174:175], v[212:213], v[78:79]
	v_pk_fma_f32 v[80:81], v[176:177], v[214:215], v[80:81]
	v_pk_fma_f32 v[82:83], v[178:179], v[216:217], v[82:83]
	v_pk_fma_f32 v[84:85], v[180:181], v[218:219], v[84:85]
	v_pk_fma_f32 v[86:87], v[182:183], v[220:221], v[86:87]
	v_pk_fma_f32 v[88:89], v[184:185], v[210:211], v[88:89]
	v_pk_fma_f32 v[90:91], v[186:187], v[212:213], v[90:91]
	v_pk_fma_f32 v[92:93], v[188:189], v[214:215], v[92:93]
	v_pk_fma_f32 v[94:95], v[190:191], v[216:217], v[94:95]
	v_pk_fma_f32 v[96:97], v[192:193], v[218:219], v[96:97]
	v_pk_fma_f32 v[98:99], v[194:195], v[220:221], v[98:99]
	global_load_dwordx4 v[210:213], v2, s[50:51]
	global_load_dwordx4 v[214:217], v2, s[50:51] offset:1024
	global_load_dwordx4 v[218:221], v2, s[50:51] offset:2048
	s_add_u32 s50, s50, 0xc00
	s_addc_u32 s51, s51, 0
	v_lshlrev_b32_e32 v100, 16, v234
	v_and_b32_e32 v101, 0xffff0000, v234
	v_lshlrev_b32_e32 v102, 16, v235
	v_and_b32_e32 v103, 0xffff0000, v235
	v_lshlrev_b32_e32 v104, 16, v236
	v_and_b32_e32 v105, 0xffff0000, v236
	v_lshlrev_b32_e32 v106, 16, v237
	v_and_b32_e32 v107, 0xffff0000, v237
	v_lshlrev_b32_e32 v108, 16, v238
	v_and_b32_e32 v109, 0xffff0000, v238
	v_lshlrev_b32_e32 v110, 16, v239
	v_and_b32_e32 v111, 0xffff0000, v239
	s_add_i32 s52, s41, 6
	s_mulk_i32 s52, 0x600
	v_add_u32_e32 v196, s52, v3
	global_load_dwordx2 v[234:235], v196, s[38:39]
	global_load_dwordx2 v[236:237], v196, s[38:39] offset:512
	global_load_dwordx2 v[238:239], v196, s[38:39] offset:1024
	s_waitcnt vmcnt(9)
	v_pk_fma_f32 v[4:5], v[112:113], v[222:223], v[4:5]
	v_pk_fma_f32 v[6:7], v[114:115], v[224:225], v[6:7]
	v_pk_fma_f32 v[8:9], v[116:117], v[226:227], v[8:9]
	v_pk_fma_f32 v[10:11], v[118:119], v[228:229], v[10:11]
	v_pk_fma_f32 v[12:13], v[120:121], v[230:231], v[12:13]
	v_pk_fma_f32 v[14:15], v[122:123], v[232:233], v[14:15]
	v_pk_fma_f32 v[16:17], v[124:125], v[222:223], v[16:17]
	v_pk_fma_f32 v[18:19], v[126:127], v[224:225], v[18:19]
	v_pk_fma_f32 v[20:21], v[128:129], v[226:227], v[20:21]
	v_pk_fma_f32 v[22:23], v[130:131], v[228:229], v[22:23]
	v_pk_fma_f32 v[24:25], v[132:133], v[230:231], v[24:25]
	v_pk_fma_f32 v[26:27], v[134:135], v[232:233], v[26:27]
	v_pk_fma_f32 v[28:29], v[136:137], v[222:223], v[28:29]
	v_pk_fma_f32 v[30:31], v[138:139], v[224:225], v[30:31]
	v_pk_fma_f32 v[32:33], v[140:141], v[226:227], v[32:33]
	v_pk_fma_f32 v[34:35], v[142:143], v[228:229], v[34:35]
	v_pk_fma_f32 v[36:37], v[144:145], v[230:231], v[36:37]
	v_pk_fma_f32 v[38:39], v[146:147], v[232:233], v[38:39]
	v_pk_fma_f32 v[40:41], v[148:149], v[222:223], v[40:41]
	v_pk_fma_f32 v[42:43], v[150:151], v[224:225], v[42:43]
	v_pk_fma_f32 v[44:45], v[152:153], v[226:227], v[44:45]
	v_pk_fma_f32 v[46:47], v[154:155], v[228:229], v[46:47]
	v_pk_fma_f32 v[48:49], v[156:157], v[230:231], v[48:49]
	v_pk_fma_f32 v[50:51], v[158:159], v[232:233], v[50:51]
	v_pk_fma_f32 v[52:53], v[160:161], v[222:223], v[52:53]
	v_pk_fma_f32 v[54:55], v[162:163], v[224:225], v[54:55]
	v_pk_fma_f32 v[56:57], v[164:165], v[226:227], v[56:57]
	v_pk_fma_f32 v[58:59], v[166:167], v[228:229], v[58:59]
	v_pk_fma_f32 v[60:61], v[168:169], v[230:231], v[60:61]
	v_pk_fma_f32 v[62:63], v[170:171], v[232:233], v[62:63]
	v_pk_fma_f32 v[64:65], v[172:173], v[222:223], v[64:65]
	v_pk_fma_f32 v[66:67], v[174:175], v[224:225], v[66:67]
	v_pk_fma_f32 v[68:69], v[176:177], v[226:227], v[68:69]
	v_pk_fma_f32 v[70:71], v[178:179], v[228:229], v[70:71]
	v_pk_fma_f32 v[72:73], v[180:181], v[230:231], v[72:73]
	v_pk_fma_f32 v[74:75], v[182:183], v[232:233], v[74:75]
	v_pk_fma_f32 v[76:77], v[184:185], v[222:223], v[76:77]
	v_pk_fma_f32 v[78:79], v[186:187], v[224:225], v[78:79]
	v_pk_fma_f32 v[80:81], v[188:189], v[226:227], v[80:81]
	v_pk_fma_f32 v[82:83], v[190:191], v[228:229], v[82:83]
	v_pk_fma_f32 v[84:85], v[192:193], v[230:231], v[84:85]
	v_pk_fma_f32 v[86:87], v[194:195], v[232:233], v[86:87]
	v_pk_fma_f32 v[88:89], v[100:101], v[222:223], v[88:89]
	v_pk_fma_f32 v[90:91], v[102:103], v[224:225], v[90:91]
	v_pk_fma_f32 v[92:93], v[104:105], v[226:227], v[92:93]
	v_pk_fma_f32 v[94:95], v[106:107], v[228:229], v[94:95]
	v_pk_fma_f32 v[96:97], v[108:109], v[230:231], v[96:97]
	v_pk_fma_f32 v[98:99], v[110:111], v[232:233], v[98:99]
	global_load_dwordx4 v[222:225], v2, s[50:51]
	global_load_dwordx4 v[226:229], v2, s[50:51] offset:1024
	global_load_dwordx4 v[230:233], v2, s[50:51] offset:2048
	s_add_u32 s50, s50, 0xc00
	s_addc_u32 s51, s51, 0
	v_lshlrev_b32_e32 v112, 16, v240
	v_and_b32_e32 v113, 0xffff0000, v240
	v_lshlrev_b32_e32 v114, 16, v241
	v_and_b32_e32 v115, 0xffff0000, v241
	v_lshlrev_b32_e32 v116, 16, v242
	v_and_b32_e32 v117, 0xffff0000, v242
	v_lshlrev_b32_e32 v118, 16, v243
	v_and_b32_e32 v119, 0xffff0000, v243
	v_lshlrev_b32_e32 v120, 16, v244
	v_and_b32_e32 v121, 0xffff0000, v244
	v_lshlrev_b32_e32 v122, 16, v245
	v_and_b32_e32 v123, 0xffff0000, v245
	s_add_i32 s52, s41, 7
	s_mulk_i32 s52, 0x600
	v_add_u32_e32 v196, s52, v3
	global_load_dwordx2 v[240:241], v196, s[38:39]
	global_load_dwordx2 v[242:243], v196, s[38:39] offset:512
	global_load_dwordx2 v[244:245], v196, s[38:39] offset:1024
	s_waitcnt vmcnt(9)
	v_pk_fma_f32 v[4:5], v[124:125], v[210:211], v[4:5]
	v_pk_fma_f32 v[6:7], v[126:127], v[212:213], v[6:7]
	v_pk_fma_f32 v[8:9], v[128:129], v[214:215], v[8:9]
	v_pk_fma_f32 v[10:11], v[130:131], v[216:217], v[10:11]
	v_pk_fma_f32 v[12:13], v[132:133], v[218:219], v[12:13]
	v_pk_fma_f32 v[14:15], v[134:135], v[220:221], v[14:15]
	v_pk_fma_f32 v[16:17], v[136:137], v[210:211], v[16:17]
	v_pk_fma_f32 v[18:19], v[138:139], v[212:213], v[18:19]
	v_pk_fma_f32 v[20:21], v[140:141], v[214:215], v[20:21]
	v_pk_fma_f32 v[22:23], v[142:143], v[216:217], v[22:23]
	v_pk_fma_f32 v[24:25], v[144:145], v[218:219], v[24:25]
	v_pk_fma_f32 v[26:27], v[146:147], v[220:221], v[26:27]
	v_pk_fma_f32 v[28:29], v[148:149], v[210:211], v[28:29]
	v_pk_fma_f32 v[30:31], v[150:151], v[212:213], v[30:31]
	v_pk_fma_f32 v[32:33], v[152:153], v[214:215], v[32:33]
	v_pk_fma_f32 v[34:35], v[154:155], v[216:217], v[34:35]
	v_pk_fma_f32 v[36:37], v[156:157], v[218:219], v[36:37]
	v_pk_fma_f32 v[38:39], v[158:159], v[220:221], v[38:39]
	v_pk_fma_f32 v[40:41], v[160:161], v[210:211], v[40:41]
	v_pk_fma_f32 v[42:43], v[162:163], v[212:213], v[42:43]
	v_pk_fma_f32 v[44:45], v[164:165], v[214:215], v[44:45]
	v_pk_fma_f32 v[46:47], v[166:167], v[216:217], v[46:47]
	v_pk_fma_f32 v[48:49], v[168:169], v[218:219], v[48:49]
	v_pk_fma_f32 v[50:51], v[170:171], v[220:221], v[50:51]
	v_pk_fma_f32 v[52:53], v[172:173], v[210:211], v[52:53]
	v_pk_fma_f32 v[54:55], v[174:175], v[212:213], v[54:55]
	v_pk_fma_f32 v[56:57], v[176:177], v[214:215], v[56:57]
	v_pk_fma_f32 v[58:59], v[178:179], v[216:217], v[58:59]
	v_pk_fma_f32 v[60:61], v[180:181], v[218:219], v[60:61]
	v_pk_fma_f32 v[62:63], v[182:183], v[220:221], v[62:63]
	v_pk_fma_f32 v[64:65], v[184:185], v[210:211], v[64:65]
	v_pk_fma_f32 v[66:67], v[186:187], v[212:213], v[66:67]
	v_pk_fma_f32 v[68:69], v[188:189], v[214:215], v[68:69]
	v_pk_fma_f32 v[70:71], v[190:191], v[216:217], v[70:71]
	v_pk_fma_f32 v[72:73], v[192:193], v[218:219], v[72:73]
	v_pk_fma_f32 v[74:75], v[194:195], v[220:221], v[74:75]
	v_pk_fma_f32 v[76:77], v[100:101], v[210:211], v[76:77]
	v_pk_fma_f32 v[78:79], v[102:103], v[212:213], v[78:79]
	v_pk_fma_f32 v[80:81], v[104:105], v[214:215], v[80:81]
	v_pk_fma_f32 v[82:83], v[106:107], v[216:217], v[82:83]
	v_pk_fma_f32 v[84:85], v[108:109], v[218:219], v[84:85]
	v_pk_fma_f32 v[86:87], v[110:111], v[220:221], v[86:87]
	v_pk_fma_f32 v[88:89], v[112:113], v[210:211], v[88:89]
	v_pk_fma_f32 v[90:91], v[114:115], v[212:213], v[90:91]
	v_pk_fma_f32 v[92:93], v[116:117], v[214:215], v[92:93]
	v_pk_fma_f32 v[94:95], v[118:119], v[216:217], v[94:95]
	v_pk_fma_f32 v[96:97], v[120:121], v[218:219], v[96:97]
	v_pk_fma_f32 v[98:99], v[122:123], v[220:221], v[98:99]
	global_load_dwordx4 v[210:213], v2, s[50:51]
	global_load_dwordx4 v[214:217], v2, s[50:51] offset:1024
	global_load_dwordx4 v[218:221], v2, s[50:51] offset:2048
	s_add_u32 s50, s50, 0xc00
	s_addc_u32 s51, s51, 0
	v_lshlrev_b32_e32 v124, 16, v246
	v_and_b32_e32 v125, 0xffff0000, v246
	v_lshlrev_b32_e32 v126, 16, v247
	v_and_b32_e32 v127, 0xffff0000, v247
	v_lshlrev_b32_e32 v128, 16, v248
	v_and_b32_e32 v129, 0xffff0000, v248
	v_lshlrev_b32_e32 v130, 16, v249
	v_and_b32_e32 v131, 0xffff0000, v249
	v_lshlrev_b32_e32 v132, 16, v250
	v_and_b32_e32 v133, 0xffff0000, v250
	v_lshlrev_b32_e32 v134, 16, v251
	v_and_b32_e32 v135, 0xffff0000, v251
	s_waitcnt vmcnt(6)
	v_pk_fma_f32 v[4:5], v[136:137], v[222:223], v[4:5]
	v_pk_fma_f32 v[6:7], v[138:139], v[224:225], v[6:7]
	v_pk_fma_f32 v[8:9], v[140:141], v[226:227], v[8:9]
	v_pk_fma_f32 v[10:11], v[142:143], v[228:229], v[10:11]
	v_pk_fma_f32 v[12:13], v[144:145], v[230:231], v[12:13]
	v_pk_fma_f32 v[14:15], v[146:147], v[232:233], v[14:15]
	v_pk_fma_f32 v[16:17], v[148:149], v[222:223], v[16:17]
	v_pk_fma_f32 v[18:19], v[150:151], v[224:225], v[18:19]
	v_pk_fma_f32 v[20:21], v[152:153], v[226:227], v[20:21]
	v_pk_fma_f32 v[22:23], v[154:155], v[228:229], v[22:23]
	v_pk_fma_f32 v[24:25], v[156:157], v[230:231], v[24:25]
	v_pk_fma_f32 v[26:27], v[158:159], v[232:233], v[26:27]
	v_pk_fma_f32 v[28:29], v[160:161], v[222:223], v[28:29]
	v_pk_fma_f32 v[30:31], v[162:163], v[224:225], v[30:31]
	v_pk_fma_f32 v[32:33], v[164:165], v[226:227], v[32:33]
	v_pk_fma_f32 v[34:35], v[166:167], v[228:229], v[34:35]
	v_pk_fma_f32 v[36:37], v[168:169], v[230:231], v[36:37]
	v_pk_fma_f32 v[38:39], v[170:171], v[232:233], v[38:39]
	v_pk_fma_f32 v[40:41], v[172:173], v[222:223], v[40:41]
	v_pk_fma_f32 v[42:43], v[174:175], v[224:225], v[42:43]
	v_pk_fma_f32 v[44:45], v[176:177], v[226:227], v[44:45]
	v_pk_fma_f32 v[46:47], v[178:179], v[228:229], v[46:47]
	v_pk_fma_f32 v[48:49], v[180:181], v[230:231], v[48:49]
	v_pk_fma_f32 v[50:51], v[182:183], v[232:233], v[50:51]
	v_pk_fma_f32 v[52:53], v[184:185], v[222:223], v[52:53]
	v_pk_fma_f32 v[54:55], v[186:187], v[224:225], v[54:55]
	v_pk_fma_f32 v[56:57], v[188:189], v[226:227], v[56:57]
	v_pk_fma_f32 v[58:59], v[190:191], v[228:229], v[58:59]
	v_pk_fma_f32 v[60:61], v[192:193], v[230:231], v[60:61]
	v_pk_fma_f32 v[62:63], v[194:195], v[232:233], v[62:63]
	v_pk_fma_f32 v[64:65], v[100:101], v[222:223], v[64:65]
	v_pk_fma_f32 v[66:67], v[102:103], v[224:225], v[66:67]
	v_pk_fma_f32 v[68:69], v[104:105], v[226:227], v[68:69]
	v_pk_fma_f32 v[70:71], v[106:107], v[228:229], v[70:71]
	v_pk_fma_f32 v[72:73], v[108:109], v[230:231], v[72:73]
	v_pk_fma_f32 v[74:75], v[110:111], v[232:233], v[74:75]
	v_pk_fma_f32 v[76:77], v[112:113], v[222:223], v[76:77]
	v_pk_fma_f32 v[78:79], v[114:115], v[224:225], v[78:79]
	v_pk_fma_f32 v[80:81], v[116:117], v[226:227], v[80:81]
	v_pk_fma_f32 v[82:83], v[118:119], v[228:229], v[82:83]
	v_pk_fma_f32 v[84:85], v[120:121], v[230:231], v[84:85]
	v_pk_fma_f32 v[86:87], v[122:123], v[232:233], v[86:87]
	v_pk_fma_f32 v[88:89], v[124:125], v[222:223], v[88:89]
	v_pk_fma_f32 v[90:91], v[126:127], v[224:225], v[90:91]
	v_pk_fma_f32 v[92:93], v[128:129], v[226:227], v[92:93]
	v_pk_fma_f32 v[94:95], v[130:131], v[228:229], v[94:95]
	v_pk_fma_f32 v[96:97], v[132:133], v[230:231], v[96:97]
	v_pk_fma_f32 v[98:99], v[134:135], v[232:233], v[98:99]
	global_load_dwordx4 v[222:225], v2, s[50:51]
	global_load_dwordx4 v[226:229], v2, s[50:51] offset:1024
	global_load_dwordx4 v[230:233], v2, s[50:51] offset:2048
	s_add_u32 s50, s50, 0xc00
	s_addc_u32 s51, s51, 0
	v_lshlrev_b32_e32 v136, 16, v204
	v_and_b32_e32 v137, 0xffff0000, v204
	v_lshlrev_b32_e32 v138, 16, v205
	v_and_b32_e32 v139, 0xffff0000, v205
	v_lshlrev_b32_e32 v140, 16, v206
	v_and_b32_e32 v141, 0xffff0000, v206
	v_lshlrev_b32_e32 v142, 16, v207
	v_and_b32_e32 v143, 0xffff0000, v207
	v_lshlrev_b32_e32 v144, 16, v252
	v_and_b32_e32 v145, 0xffff0000, v252
	v_lshlrev_b32_e32 v146, 16, v253
	v_and_b32_e32 v147, 0xffff0000, v253
	s_waitcnt vmcnt(3)
	v_pk_fma_f32 v[4:5], v[148:149], v[210:211], v[4:5]
	v_pk_fma_f32 v[6:7], v[150:151], v[212:213], v[6:7]
	v_pk_fma_f32 v[8:9], v[152:153], v[214:215], v[8:9]
	v_pk_fma_f32 v[10:11], v[154:155], v[216:217], v[10:11]
	v_pk_fma_f32 v[12:13], v[156:157], v[218:219], v[12:13]
	v_pk_fma_f32 v[14:15], v[158:159], v[220:221], v[14:15]
	v_pk_fma_f32 v[16:17], v[160:161], v[210:211], v[16:17]
	v_pk_fma_f32 v[18:19], v[162:163], v[212:213], v[18:19]
	v_pk_fma_f32 v[20:21], v[164:165], v[214:215], v[20:21]
	v_pk_fma_f32 v[22:23], v[166:167], v[216:217], v[22:23]
	v_pk_fma_f32 v[24:25], v[168:169], v[218:219], v[24:25]
	v_pk_fma_f32 v[26:27], v[170:171], v[220:221], v[26:27]
	v_pk_fma_f32 v[28:29], v[172:173], v[210:211], v[28:29]
	v_pk_fma_f32 v[30:31], v[174:175], v[212:213], v[30:31]
	v_pk_fma_f32 v[32:33], v[176:177], v[214:215], v[32:33]
	v_pk_fma_f32 v[34:35], v[178:179], v[216:217], v[34:35]
	v_pk_fma_f32 v[36:37], v[180:181], v[218:219], v[36:37]
	v_pk_fma_f32 v[38:39], v[182:183], v[220:221], v[38:39]
	v_pk_fma_f32 v[40:41], v[184:185], v[210:211], v[40:41]
	v_pk_fma_f32 v[42:43], v[186:187], v[212:213], v[42:43]
	v_pk_fma_f32 v[44:45], v[188:189], v[214:215], v[44:45]
	v_pk_fma_f32 v[46:47], v[190:191], v[216:217], v[46:47]
	v_pk_fma_f32 v[48:49], v[192:193], v[218:219], v[48:49]
	v_pk_fma_f32 v[50:51], v[194:195], v[220:221], v[50:51]
	v_pk_fma_f32 v[52:53], v[100:101], v[210:211], v[52:53]
	v_pk_fma_f32 v[54:55], v[102:103], v[212:213], v[54:55]
	v_pk_fma_f32 v[56:57], v[104:105], v[214:215], v[56:57]
	v_pk_fma_f32 v[58:59], v[106:107], v[216:217], v[58:59]
	v_pk_fma_f32 v[60:61], v[108:109], v[218:219], v[60:61]
	v_pk_fma_f32 v[62:63], v[110:111], v[220:221], v[62:63]
	v_pk_fma_f32 v[64:65], v[112:113], v[210:211], v[64:65]
	v_pk_fma_f32 v[66:67], v[114:115], v[212:213], v[66:67]
	v_pk_fma_f32 v[68:69], v[116:117], v[214:215], v[68:69]
	v_pk_fma_f32 v[70:71], v[118:119], v[216:217], v[70:71]
	v_pk_fma_f32 v[72:73], v[120:121], v[218:219], v[72:73]
	v_pk_fma_f32 v[74:75], v[122:123], v[220:221], v[74:75]
	v_pk_fma_f32 v[76:77], v[124:125], v[210:211], v[76:77]
	v_pk_fma_f32 v[78:79], v[126:127], v[212:213], v[78:79]
	v_pk_fma_f32 v[80:81], v[128:129], v[214:215], v[80:81]
	v_pk_fma_f32 v[82:83], v[130:131], v[216:217], v[82:83]
	v_pk_fma_f32 v[84:85], v[132:133], v[218:219], v[84:85]
	v_pk_fma_f32 v[86:87], v[134:135], v[220:221], v[86:87]
	v_pk_fma_f32 v[88:89], v[136:137], v[210:211], v[88:89]
	v_pk_fma_f32 v[90:91], v[138:139], v[212:213], v[90:91]
	v_pk_fma_f32 v[92:93], v[140:141], v[214:215], v[92:93]
	v_pk_fma_f32 v[94:95], v[142:143], v[216:217], v[94:95]
	v_pk_fma_f32 v[96:97], v[144:145], v[218:219], v[96:97]
	v_pk_fma_f32 v[98:99], v[146:147], v[220:221], v[98:99]
	global_load_dwordx4 v[210:213], v2, s[50:51]
	global_load_dwordx4 v[214:217], v2, s[50:51] offset:1024
	global_load_dwordx4 v[218:221], v2, s[50:51] offset:2048
	s_add_u32 s50, s50, 0xc00
	s_addc_u32 s51, s51, 0
	v_lshlrev_b32_e32 v148, 16, v234
	v_and_b32_e32 v149, 0xffff0000, v234
	v_lshlrev_b32_e32 v150, 16, v235
	v_and_b32_e32 v151, 0xffff0000, v235
	v_lshlrev_b32_e32 v152, 16, v236
	v_and_b32_e32 v153, 0xffff0000, v236
	v_lshlrev_b32_e32 v154, 16, v237
	v_and_b32_e32 v155, 0xffff0000, v237
	v_lshlrev_b32_e32 v156, 16, v238
	v_and_b32_e32 v157, 0xffff0000, v238
	v_lshlrev_b32_e32 v158, 16, v239
	v_and_b32_e32 v159, 0xffff0000, v239
	s_waitcnt vmcnt(3)
	v_pk_fma_f32 v[4:5], v[160:161], v[222:223], v[4:5]
	v_pk_fma_f32 v[6:7], v[162:163], v[224:225], v[6:7]
	v_pk_fma_f32 v[8:9], v[164:165], v[226:227], v[8:9]
	v_pk_fma_f32 v[10:11], v[166:167], v[228:229], v[10:11]
	v_pk_fma_f32 v[12:13], v[168:169], v[230:231], v[12:13]
	v_pk_fma_f32 v[14:15], v[170:171], v[232:233], v[14:15]
	v_pk_fma_f32 v[16:17], v[172:173], v[222:223], v[16:17]
	v_pk_fma_f32 v[18:19], v[174:175], v[224:225], v[18:19]
	v_pk_fma_f32 v[20:21], v[176:177], v[226:227], v[20:21]
	v_pk_fma_f32 v[22:23], v[178:179], v[228:229], v[22:23]
	v_pk_fma_f32 v[24:25], v[180:181], v[230:231], v[24:25]
	v_pk_fma_f32 v[26:27], v[182:183], v[232:233], v[26:27]
	v_pk_fma_f32 v[28:29], v[184:185], v[222:223], v[28:29]
	v_pk_fma_f32 v[30:31], v[186:187], v[224:225], v[30:31]
	v_pk_fma_f32 v[32:33], v[188:189], v[226:227], v[32:33]
	v_pk_fma_f32 v[34:35], v[190:191], v[228:229], v[34:35]
	v_pk_fma_f32 v[36:37], v[192:193], v[230:231], v[36:37]
	v_pk_fma_f32 v[38:39], v[194:195], v[232:233], v[38:39]
	v_pk_fma_f32 v[40:41], v[100:101], v[222:223], v[40:41]
	v_pk_fma_f32 v[42:43], v[102:103], v[224:225], v[42:43]
	v_pk_fma_f32 v[44:45], v[104:105], v[226:227], v[44:45]
	v_pk_fma_f32 v[46:47], v[106:107], v[228:229], v[46:47]
	v_pk_fma_f32 v[48:49], v[108:109], v[230:231], v[48:49]
	v_pk_fma_f32 v[50:51], v[110:111], v[232:233], v[50:51]
	v_pk_fma_f32 v[52:53], v[112:113], v[222:223], v[52:53]
	v_pk_fma_f32 v[54:55], v[114:115], v[224:225], v[54:55]
	v_pk_fma_f32 v[56:57], v[116:117], v[226:227], v[56:57]
	v_pk_fma_f32 v[58:59], v[118:119], v[228:229], v[58:59]
	v_pk_fma_f32 v[60:61], v[120:121], v[230:231], v[60:61]
	v_pk_fma_f32 v[62:63], v[122:123], v[232:233], v[62:63]
	v_pk_fma_f32 v[64:65], v[124:125], v[222:223], v[64:65]
	v_pk_fma_f32 v[66:67], v[126:127], v[224:225], v[66:67]
	v_pk_fma_f32 v[68:69], v[128:129], v[226:227], v[68:69]
	v_pk_fma_f32 v[70:71], v[130:131], v[228:229], v[70:71]
	v_pk_fma_f32 v[72:73], v[132:133], v[230:231], v[72:73]
	v_pk_fma_f32 v[74:75], v[134:135], v[232:233], v[74:75]
	v_pk_fma_f32 v[76:77], v[136:137], v[222:223], v[76:77]
	v_pk_fma_f32 v[78:79], v[138:139], v[224:225], v[78:79]
	v_pk_fma_f32 v[80:81], v[140:141], v[226:227], v[80:81]
	v_pk_fma_f32 v[82:83], v[142:143], v[228:229], v[82:83]
	v_pk_fma_f32 v[84:85], v[144:145], v[230:231], v[84:85]
	v_pk_fma_f32 v[86:87], v[146:147], v[232:233], v[86:87]
	v_pk_fma_f32 v[88:89], v[148:149], v[222:223], v[88:89]
	v_pk_fma_f32 v[90:91], v[150:151], v[224:225], v[90:91]
	v_pk_fma_f32 v[92:93], v[152:153], v[226:227], v[92:93]
	v_pk_fma_f32 v[94:95], v[154:155], v[228:229], v[94:95]
	v_pk_fma_f32 v[96:97], v[156:157], v[230:231], v[96:97]
	v_pk_fma_f32 v[98:99], v[158:159], v[232:233], v[98:99]
	v_lshlrev_b32_e32 v160, 16, v240
	v_and_b32_e32 v161, 0xffff0000, v240
	v_lshlrev_b32_e32 v162, 16, v241
	v_and_b32_e32 v163, 0xffff0000, v241
	v_lshlrev_b32_e32 v164, 16, v242
	v_and_b32_e32 v165, 0xffff0000, v242
	v_lshlrev_b32_e32 v166, 16, v243
	v_and_b32_e32 v167, 0xffff0000, v243
	v_lshlrev_b32_e32 v168, 16, v244
	v_and_b32_e32 v169, 0xffff0000, v244
	v_lshlrev_b32_e32 v170, 16, v245
	v_and_b32_e32 v171, 0xffff0000, v245
	global_load_dwordx4 v[222:225], v2, s[66:67]
	global_load_dwordx4 v[226:229], v2, s[66:67] offset:1024
	global_load_dwordx4 v[230:233], v2, s[66:67] offset:2048
	global_load_dwordx4 v[234:237], v2, s[42:43]
	global_load_dwordx4 v[238:241], v2, s[42:43] offset:1024
	global_load_dwordx4 v[242:245], v2, s[42:43] offset:2048
	s_waitcnt vmcnt(6)
	v_pk_fma_f32 v[4:5], v[172:173], v[210:211], v[4:5]
	v_pk_fma_f32 v[6:7], v[174:175], v[212:213], v[6:7]
	v_pk_fma_f32 v[8:9], v[176:177], v[214:215], v[8:9]
	v_pk_fma_f32 v[10:11], v[178:179], v[216:217], v[10:11]
	v_pk_fma_f32 v[12:13], v[180:181], v[218:219], v[12:13]
	v_pk_fma_f32 v[14:15], v[182:183], v[220:221], v[14:15]
	v_pk_fma_f32 v[16:17], v[184:185], v[210:211], v[16:17]
	v_pk_fma_f32 v[18:19], v[186:187], v[212:213], v[18:19]
	v_pk_fma_f32 v[20:21], v[188:189], v[214:215], v[20:21]
	v_pk_fma_f32 v[22:23], v[190:191], v[216:217], v[22:23]
	v_pk_fma_f32 v[24:25], v[192:193], v[218:219], v[24:25]
	v_pk_fma_f32 v[26:27], v[194:195], v[220:221], v[26:27]
	v_pk_fma_f32 v[28:29], v[100:101], v[210:211], v[28:29]
	v_pk_fma_f32 v[30:31], v[102:103], v[212:213], v[30:31]
	v_pk_fma_f32 v[32:33], v[104:105], v[214:215], v[32:33]
	v_pk_fma_f32 v[34:35], v[106:107], v[216:217], v[34:35]
	v_pk_fma_f32 v[36:37], v[108:109], v[218:219], v[36:37]
	v_pk_fma_f32 v[38:39], v[110:111], v[220:221], v[38:39]
	v_pk_fma_f32 v[40:41], v[112:113], v[210:211], v[40:41]
	v_pk_fma_f32 v[42:43], v[114:115], v[212:213], v[42:43]
	v_pk_fma_f32 v[44:45], v[116:117], v[214:215], v[44:45]
	v_pk_fma_f32 v[46:47], v[118:119], v[216:217], v[46:47]
	v_pk_fma_f32 v[48:49], v[120:121], v[218:219], v[48:49]
	v_pk_fma_f32 v[50:51], v[122:123], v[220:221], v[50:51]
	v_pk_fma_f32 v[52:53], v[124:125], v[210:211], v[52:53]
	v_pk_fma_f32 v[54:55], v[126:127], v[212:213], v[54:55]
	v_pk_fma_f32 v[56:57], v[128:129], v[214:215], v[56:57]
	v_pk_fma_f32 v[58:59], v[130:131], v[216:217], v[58:59]
	v_pk_fma_f32 v[60:61], v[132:133], v[218:219], v[60:61]
	v_pk_fma_f32 v[62:63], v[134:135], v[220:221], v[62:63]
	v_pk_fma_f32 v[64:65], v[136:137], v[210:211], v[64:65]
	v_pk_fma_f32 v[66:67], v[138:139], v[212:213], v[66:67]
	v_pk_fma_f32 v[68:69], v[140:141], v[214:215], v[68:69]
	v_pk_fma_f32 v[70:71], v[142:143], v[216:217], v[70:71]
	v_pk_fma_f32 v[72:73], v[144:145], v[218:219], v[72:73]
	v_pk_fma_f32 v[74:75], v[146:147], v[220:221], v[74:75]
	v_pk_fma_f32 v[76:77], v[148:149], v[210:211], v[76:77]
	v_pk_fma_f32 v[78:79], v[150:151], v[212:213], v[78:79]
	v_pk_fma_f32 v[80:81], v[152:153], v[214:215], v[80:81]
	v_pk_fma_f32 v[82:83], v[154:155], v[216:217], v[82:83]
	v_pk_fma_f32 v[84:85], v[156:157], v[218:219], v[84:85]
	v_pk_fma_f32 v[86:87], v[158:159], v[220:221], v[86:87]
	v_pk_fma_f32 v[88:89], v[160:161], v[210:211], v[88:89]
	v_pk_fma_f32 v[90:91], v[162:163], v[212:213], v[90:91]
	v_pk_fma_f32 v[92:93], v[164:165], v[214:215], v[92:93]
	v_pk_fma_f32 v[94:95], v[166:167], v[216:217], v[94:95]
	v_pk_fma_f32 v[96:97], v[168:169], v[218:219], v[96:97]
	v_pk_fma_f32 v[98:99], v[170:171], v[220:221], v[98:99]
	s_waitcnt vmcnt(0)
	v_mov_b32_e32 v197, 0x3727c5ac
	v_add_f32_e32 v100, v4, v5
	v_add_f32_e32 v100, v100, v6
	v_add_f32_e32 v100, v100, v7
	v_add_f32_e32 v100, v100, v8
	v_add_f32_e32 v100, v100, v9
	v_add_f32_e32 v100, v100, v10
	v_add_f32_e32 v100, v100, v11
	v_add_f32_e32 v100, v100, v12
	v_add_f32_e32 v100, v100, v13
	v_add_f32_e32 v100, v100, v14
	v_add_f32_e32 v100, v100, v15
	s_nop 1
	v_add_f32_dpp v100, v100, v100 row_shr:1 row_mask:0xf bank_mask:0xf bound_ctrl:1
	s_nop 1
	v_add_f32_dpp v100, v100, v100 row_shr:2 row_mask:0xf bank_mask:0xf bound_ctrl:1
	s_nop 1
	v_add_f32_dpp v100, v100, v100 row_shr:4 row_mask:0xf bank_mask:0xf bound_ctrl:1
	s_nop 1
	v_add_f32_dpp v100, v100, v100 row_shr:8 row_mask:0xf bank_mask:0xf bound_ctrl:1
	s_nop 1
	v_add_f32_dpp v100, v100, v100 row_bcast:15 row_mask:0xa bank_mask:0xf
	s_nop 1
	v_add_f32_dpp v100, v100, v100 row_bcast:31 row_mask:0xc bank_mask:0xf
	s_nop 0
	v_readlane_b32 s53, v100, 63
	s_nop 1
	v_mov_b32_e32 v101, s53
	v_fmac_f32_e32 v4, 0xbaaaaaab, v101
	v_fmac_f32_e32 v5, 0xbaaaaaab, v101
	v_fmac_f32_e32 v6, 0xbaaaaaab, v101
	v_fmac_f32_e32 v7, 0xbaaaaaab, v101
	v_fmac_f32_e32 v8, 0xbaaaaaab, v101
	v_fmac_f32_e32 v9, 0xbaaaaaab, v101
	v_fmac_f32_e32 v10, 0xbaaaaaab, v101
	v_fmac_f32_e32 v11, 0xbaaaaaab, v101
	v_fmac_f32_e32 v12, 0xbaaaaaab, v101
	v_fmac_f32_e32 v13, 0xbaaaaaab, v101
	v_fmac_f32_e32 v14, 0xbaaaaaab, v101
	v_fmac_f32_e32 v15, 0xbaaaaaab, v101
	v_mul_f32_e32 v102, v4, v4
	v_fmac_f32_e32 v102, v5, v5
	v_fmac_f32_e32 v102, v6, v6
	v_fmac_f32_e32 v102, v7, v7
	v_fmac_f32_e32 v102, v8, v8
	v_fmac_f32_e32 v102, v9, v9
	v_fmac_f32_e32 v102, v10, v10
	v_fmac_f32_e32 v102, v11, v11
	v_fmac_f32_e32 v102, v12, v12
	v_fmac_f32_e32 v102, v13, v13
	v_fmac_f32_e32 v102, v14, v14
	v_fmac_f32_e32 v102, v15, v15
	s_nop 1
	v_add_f32_dpp v102, v102, v102 row_shr:1 row_mask:0xf bank_mask:0xf bound_ctrl:1
	s_nop 1
	v_add_f32_dpp v102, v102, v102 row_shr:2 row_mask:0xf bank_mask:0xf bound_ctrl:1
	s_nop 1
	v_add_f32_dpp v102, v102, v102 row_shr:4 row_mask:0xf bank_mask:0xf bound_ctrl:1
	s_nop 1
	v_add_f32_dpp v102, v102, v102 row_shr:8 row_mask:0xf bank_mask:0xf bound_ctrl:1
	s_nop 1
	v_add_f32_dpp v102, v102, v102 row_bcast:15 row_mask:0xa bank_mask:0xf
	s_nop 1
	v_add_f32_dpp v102, v102, v102 row_bcast:31 row_mask:0xc bank_mask:0xf
	s_nop 0
	v_readlane_b32 s53, v102, 63
	s_nop 1
	v_mov_b32_e32 v101, s53
	v_fmamk_f32 v101, v101, 0x3aaaaaab, v197
	v_rsq_f32_e32 v103, v101
	s_nop 0
	v_mul_f32_e32 v4, v4, v103
	v_mul_f32_e32 v5, v5, v103
	v_mul_f32_e32 v6, v6, v103
	v_mul_f32_e32 v7, v7, v103
	v_mul_f32_e32 v8, v8, v103
	v_mul_f32_e32 v9, v9, v103
	v_mul_f32_e32 v10, v10, v103
	v_mul_f32_e32 v11, v11, v103
	v_mul_f32_e32 v12, v12, v103
	v_mul_f32_e32 v13, v13, v103
	v_mul_f32_e32 v14, v14, v103
	v_mul_f32_e32 v15, v15, v103
	v_fma_f32 v4, v222, v4, v234
	v_fma_f32 v5, v223, v5, v235
	v_fma_f32 v6, v224, v6, v236
	v_fma_f32 v7, v225, v7, v237
	v_fma_f32 v8, v226, v8, v238
	v_fma_f32 v9, v227, v9, v239
	v_fma_f32 v10, v228, v10, v240
	v_fma_f32 v11, v229, v11, v241
	v_fma_f32 v12, v230, v12, v242
	v_fma_f32 v13, v231, v13, v243
	v_fma_f32 v14, v232, v14, v244
	v_fma_f32 v15, v233, v15, v245
	s_lshl_b32 s52, s41, 11
	s_add_i32 s52, s52, 0
	v_add_u32_e32 v196, s52, v3
	v_mul_f32_e32 v108, 0xbfb8aa3b, v4
	v_exp_f32_e32 v109, v108
	s_nop 0
	v_add_f32_e32 v110, 1.0, v109
	v_div_scale_f32 v111, s[54:55], v110, v110, 1.0
	v_rcp_f32_e32 v112, v111
	v_div_scale_f32 v113, vcc, 1.0, v110, 1.0
	v_fma_f32 v115, -v111, v112, 1.0
	v_fmac_f32_e32 v112, v115, v112
	v_mul_f32_e32 v114, v113, v112
	v_fma_f32 v115, -v111, v114, v113
	v_fmac_f32_e32 v114, v115, v112
	v_fma_f32 v115, -v111, v114, v113
	v_div_fmas_f32 v115, v115, v112, v114
	v_div_fixup_f32 v115, v115, v110, 1.0
	v_mul_f32_e32 v120, v4, v115
	v_mul_f32_e32 v108, 0xbfb8aa3b, v5
	v_exp_f32_e32 v109, v108
	s_nop 0
	v_add_f32_e32 v110, 1.0, v109
	v_div_scale_f32 v111, s[54:55], v110, v110, 1.0
	v_rcp_f32_e32 v112, v111
	v_div_scale_f32 v113, vcc, 1.0, v110, 1.0
	v_fma_f32 v115, -v111, v112, 1.0
	v_fmac_f32_e32 v112, v115, v112
	v_mul_f32_e32 v114, v113, v112
	v_fma_f32 v115, -v111, v114, v113
	v_fmac_f32_e32 v114, v115, v112
	v_fma_f32 v115, -v111, v114, v113
	v_div_fmas_f32 v115, v115, v112, v114
	v_div_fixup_f32 v115, v115, v110, 1.0
	v_mul_f32_e32 v121, v5, v115
	v_mul_f32_e32 v108, 0xbfb8aa3b, v6
	v_exp_f32_e32 v109, v108
	s_nop 0
	v_add_f32_e32 v110, 1.0, v109
	v_div_scale_f32 v111, s[54:55], v110, v110, 1.0
	v_rcp_f32_e32 v112, v111
	v_div_scale_f32 v113, vcc, 1.0, v110, 1.0
	v_fma_f32 v115, -v111, v112, 1.0
	v_fmac_f32_e32 v112, v115, v112
	v_mul_f32_e32 v114, v113, v112
	v_fma_f32 v115, -v111, v114, v113
	v_fmac_f32_e32 v114, v115, v112
	v_fma_f32 v115, -v111, v114, v113
	v_div_fmas_f32 v115, v115, v112, v114
	v_div_fixup_f32 v115, v115, v110, 1.0
	v_mul_f32_e32 v122, v6, v115
	v_mul_f32_e32 v108, 0xbfb8aa3b, v7
	v_exp_f32_e32 v109, v108
	s_nop 0
	v_add_f32_e32 v110, 1.0, v109
	v_div_scale_f32 v111, s[54:55], v110, v110, 1.0
	v_rcp_f32_e32 v112, v111
	v_div_scale_f32 v113, vcc, 1.0, v110, 1.0
	v_fma_f32 v115, -v111, v112, 1.0
	v_fmac_f32_e32 v112, v115, v112
	v_mul_f32_e32 v114, v113, v112
	v_fma_f32 v115, -v111, v114, v113
	v_fmac_f32_e32 v114, v115, v112
	v_fma_f32 v115, -v111, v114, v113
	v_div_fmas_f32 v115, v115, v112, v114
	v_div_fixup_f32 v115, v115, v110, 1.0
	v_mul_f32_e32 v123, v7, v115
	v_cvt_pk_bf16_f32 v124, v120, v121
	v_cvt_pk_bf16_f32 v125, v122, v123
	global_store_dwordx2 v196, v[124:125], s[44:45]
	v_mul_f32_e32 v108, 0xbfb8aa3b, v8
	v_exp_f32_e32 v109, v108
	s_nop 0
	v_add_f32_e32 v110, 1.0, v109
	v_div_scale_f32 v111, s[54:55], v110, v110, 1.0
	v_rcp_f32_e32 v112, v111
	v_div_scale_f32 v113, vcc, 1.0, v110, 1.0
	v_fma_f32 v115, -v111, v112, 1.0
	v_fmac_f32_e32 v112, v115, v112
	v_mul_f32_e32 v114, v113, v112
	v_fma_f32 v115, -v111, v114, v113
	v_fmac_f32_e32 v114, v115, v112
	v_fma_f32 v115, -v111, v114, v113
	v_div_fmas_f32 v115, v115, v112, v114
	v_div_fixup_f32 v115, v115, v110, 1.0
	v_mul_f32_e32 v120, v8, v115
	v_mul_f32_e32 v108, 0xbfb8aa3b, v9
	v_exp_f32_e32 v109, v108
	s_nop 0
	v_add_f32_e32 v110, 1.0, v109
	v_div_scale_f32 v111, s[54:55], v110, v110, 1.0
	v_rcp_f32_e32 v112, v111
	v_div_scale_f32 v113, vcc, 1.0, v110, 1.0
	v_fma_f32 v115, -v111, v112, 1.0
	v_fmac_f32_e32 v112, v115, v112
	v_mul_f32_e32 v114, v113, v112
	v_fma_f32 v115, -v111, v114, v113
	v_fmac_f32_e32 v114, v115, v112
	v_fma_f32 v115, -v111, v114, v113
	v_div_fmas_f32 v115, v115, v112, v114
	v_div_fixup_f32 v115, v115, v110, 1.0
	v_mul_f32_e32 v121, v9, v115
	v_mul_f32_e32 v108, 0xbfb8aa3b, v10
	v_exp_f32_e32 v109, v108
	s_nop 0
	v_add_f32_e32 v110, 1.0, v109
	v_div_scale_f32 v111, s[54:55], v110, v110, 1.0
	v_rcp_f32_e32 v112, v111
	v_div_scale_f32 v113, vcc, 1.0, v110, 1.0
	v_fma_f32 v115, -v111, v112, 1.0
	v_fmac_f32_e32 v112, v115, v112
	v_mul_f32_e32 v114, v113, v112
	v_fma_f32 v115, -v111, v114, v113
	v_fmac_f32_e32 v114, v115, v112
	v_fma_f32 v115, -v111, v114, v113
	v_div_fmas_f32 v115, v115, v112, v114
	v_div_fixup_f32 v115, v115, v110, 1.0
	v_mul_f32_e32 v122, v10, v115
	v_mul_f32_e32 v108, 0xbfb8aa3b, v11
	v_exp_f32_e32 v109, v108
	s_nop 0
	v_add_f32_e32 v110, 1.0, v109
	v_div_scale_f32 v111, s[54:55], v110, v110, 1.0
	v_rcp_f32_e32 v112, v111
	v_div_scale_f32 v113, vcc, 1.0, v110, 1.0
	v_fma_f32 v115, -v111, v112, 1.0
	v_fmac_f32_e32 v112, v115, v112
	v_mul_f32_e32 v114, v113, v112
	v_fma_f32 v115, -v111, v114, v113
	v_fmac_f32_e32 v114, v115, v112
	v_fma_f32 v115, -v111, v114, v113
	v_div_fmas_f32 v115, v115, v112, v114
	v_div_fixup_f32 v115, v115, v110, 1.0
	v_mul_f32_e32 v123, v11, v115
	v_cvt_pk_bf16_f32 v124, v120, v121
	v_cvt_pk_bf16_f32 v125, v122, v123
	global_store_dwordx2 v196, v[124:125], s[44:45] offset:512
	v_mul_f32_e32 v108, 0xbfb8aa3b, v12
	v_exp_f32_e32 v109, v108
	s_nop 0
	v_add_f32_e32 v110, 1.0, v109
	v_div_scale_f32 v111, s[54:55], v110, v110, 1.0
	v_rcp_f32_e32 v112, v111
	v_div_scale_f32 v113, vcc, 1.0, v110, 1.0
	v_fma_f32 v115, -v111, v112, 1.0
	v_fmac_f32_e32 v112, v115, v112
	v_mul_f32_e32 v114, v113, v112
	v_fma_f32 v115, -v111, v114, v113
	v_fmac_f32_e32 v114, v115, v112
	v_fma_f32 v115, -v111, v114, v113
	v_div_fmas_f32 v115, v115, v112, v114
	v_div_fixup_f32 v115, v115, v110, 1.0
	v_mul_f32_e32 v120, v12, v115
	v_mul_f32_e32 v108, 0xbfb8aa3b, v13
	v_exp_f32_e32 v109, v108
	s_nop 0
	v_add_f32_e32 v110, 1.0, v109
	v_div_scale_f32 v111, s[54:55], v110, v110, 1.0
	v_rcp_f32_e32 v112, v111
	v_div_scale_f32 v113, vcc, 1.0, v110, 1.0
	v_fma_f32 v115, -v111, v112, 1.0
	v_fmac_f32_e32 v112, v115, v112
	v_mul_f32_e32 v114, v113, v112
	v_fma_f32 v115, -v111, v114, v113
	v_fmac_f32_e32 v114, v115, v112
	v_fma_f32 v115, -v111, v114, v113
	v_div_fmas_f32 v115, v115, v112, v114
	v_div_fixup_f32 v115, v115, v110, 1.0
	v_mul_f32_e32 v121, v13, v115
	v_mul_f32_e32 v108, 0xbfb8aa3b, v14
	v_exp_f32_e32 v109, v108
	s_nop 0
	v_add_f32_e32 v110, 1.0, v109
	v_div_scale_f32 v111, s[54:55], v110, v110, 1.0
	v_rcp_f32_e32 v112, v111
	v_div_scale_f32 v113, vcc, 1.0, v110, 1.0
	v_fma_f32 v115, -v111, v112, 1.0
	v_fmac_f32_e32 v112, v115, v112
	v_mul_f32_e32 v114, v113, v112
	v_fma_f32 v115, -v111, v114, v113
	v_fmac_f32_e32 v114, v115, v112
	v_fma_f32 v115, -v111, v114, v113
	v_div_fmas_f32 v115, v115, v112, v114
	v_div_fixup_f32 v115, v115, v110, 1.0
	v_mul_f32_e32 v122, v14, v115
	v_mul_f32_e32 v108, 0xbfb8aa3b, v15
	v_exp_f32_e32 v109, v108
	s_nop 0
	v_add_f32_e32 v110, 1.0, v109
	v_div_scale_f32 v111, s[54:55], v110, v110, 1.0
	v_rcp_f32_e32 v112, v111
	v_div_scale_f32 v113, vcc, 1.0, v110, 1.0
	v_fma_f32 v115, -v111, v112, 1.0
	v_fmac_f32_e32 v112, v115, v112
	v_mul_f32_e32 v114, v113, v112
	v_fma_f32 v115, -v111, v114, v113
	v_fmac_f32_e32 v114, v115, v112
	v_fma_f32 v115, -v111, v114, v113
	v_div_fmas_f32 v115, v115, v112, v114
	v_div_fixup_f32 v115, v115, v110, 1.0
	v_mul_f32_e32 v123, v15, v115
	v_cvt_pk_bf16_f32 v124, v120, v121
	v_cvt_pk_bf16_f32 v125, v122, v123
	global_store_dwordx2 v196, v[124:125], s[44:45] offset:1024
	v_add_f32_e32 v100, v16, v17
	v_add_f32_e32 v100, v100, v18
	v_add_f32_e32 v100, v100, v19
	v_add_f32_e32 v100, v100, v20
	v_add_f32_e32 v100, v100, v21
	v_add_f32_e32 v100, v100, v22
	v_add_f32_e32 v100, v100, v23
	v_add_f32_e32 v100, v100, v24
	v_add_f32_e32 v100, v100, v25
	v_add_f32_e32 v100, v100, v26
	v_add_f32_e32 v100, v100, v27
	s_nop 1
	v_add_f32_dpp v100, v100, v100 row_shr:1 row_mask:0xf bank_mask:0xf bound_ctrl:1
	s_nop 1
	v_add_f32_dpp v100, v100, v100 row_shr:2 row_mask:0xf bank_mask:0xf bound_ctrl:1
	s_nop 1
	v_add_f32_dpp v100, v100, v100 row_shr:4 row_mask:0xf bank_mask:0xf bound_ctrl:1
	s_nop 1
	v_add_f32_dpp v100, v100, v100 row_shr:8 row_mask:0xf bank_mask:0xf bound_ctrl:1
	s_nop 1
	v_add_f32_dpp v100, v100, v100 row_bcast:15 row_mask:0xa bank_mask:0xf
	s_nop 1
	v_add_f32_dpp v100, v100, v100 row_bcast:31 row_mask:0xc bank_mask:0xf
	s_nop 0
	v_readlane_b32 s53, v100, 63
	s_nop 1
	v_mov_b32_e32 v101, s53
	v_fmac_f32_e32 v16, 0xbaaaaaab, v101
	v_fmac_f32_e32 v17, 0xbaaaaaab, v101
	v_fmac_f32_e32 v18, 0xbaaaaaab, v101
	v_fmac_f32_e32 v19, 0xbaaaaaab, v101
	v_fmac_f32_e32 v20, 0xbaaaaaab, v101
	v_fmac_f32_e32 v21, 0xbaaaaaab, v101
	v_fmac_f32_e32 v22, 0xbaaaaaab, v101
	v_fmac_f32_e32 v23, 0xbaaaaaab, v101
	v_fmac_f32_e32 v24, 0xbaaaaaab, v101
	v_fmac_f32_e32 v25, 0xbaaaaaab, v101
	v_fmac_f32_e32 v26, 0xbaaaaaab, v101
	v_fmac_f32_e32 v27, 0xbaaaaaab, v101
	v_mul_f32_e32 v102, v16, v16
	v_fmac_f32_e32 v102, v17, v17
	v_fmac_f32_e32 v102, v18, v18
	v_fmac_f32_e32 v102, v19, v19
	v_fmac_f32_e32 v102, v20, v20
	v_fmac_f32_e32 v102, v21, v21
	v_fmac_f32_e32 v102, v22, v22
	v_fmac_f32_e32 v102, v23, v23
	v_fmac_f32_e32 v102, v24, v24
	v_fmac_f32_e32 v102, v25, v25
	v_fmac_f32_e32 v102, v26, v26
	v_fmac_f32_e32 v102, v27, v27
	s_nop 1
	v_add_f32_dpp v102, v102, v102 row_shr:1 row_mask:0xf bank_mask:0xf bound_ctrl:1
	s_nop 1
	v_add_f32_dpp v102, v102, v102 row_shr:2 row_mask:0xf bank_mask:0xf bound_ctrl:1
	s_nop 1
	v_add_f32_dpp v102, v102, v102 row_shr:4 row_mask:0xf bank_mask:0xf bound_ctrl:1
	s_nop 1
	v_add_f32_dpp v102, v102, v102 row_shr:8 row_mask:0xf bank_mask:0xf bound_ctrl:1
	s_nop 1
	v_add_f32_dpp v102, v102, v102 row_bcast:15 row_mask:0xa bank_mask:0xf
	s_nop 1
	v_add_f32_dpp v102, v102, v102 row_bcast:31 row_mask:0xc bank_mask:0xf
	s_nop 0
	v_readlane_b32 s53, v102, 63
	s_nop 1
	v_mov_b32_e32 v101, s53
	v_fmamk_f32 v101, v101, 0x3aaaaaab, v197
	v_rsq_f32_e32 v103, v101
	s_nop 0
	v_mul_f32_e32 v16, v16, v103
	v_mul_f32_e32 v17, v17, v103
	v_mul_f32_e32 v18, v18, v103
	v_mul_f32_e32 v19, v19, v103
	v_mul_f32_e32 v20, v20, v103
	v_mul_f32_e32 v21, v21, v103
	v_mul_f32_e32 v22, v22, v103
	v_mul_f32_e32 v23, v23, v103
	v_mul_f32_e32 v24, v24, v103
	v_mul_f32_e32 v25, v25, v103
	v_mul_f32_e32 v26, v26, v103
	v_mul_f32_e32 v27, v27, v103
	v_fma_f32 v16, v222, v16, v234
	v_fma_f32 v17, v223, v17, v235
	v_fma_f32 v18, v224, v18, v236
	v_fma_f32 v19, v225, v19, v237
	v_fma_f32 v20, v226, v20, v238
	v_fma_f32 v21, v227, v21, v239
	v_fma_f32 v22, v228, v22, v240
	v_fma_f32 v23, v229, v23, v241
	v_fma_f32 v24, v230, v24, v242
	v_fma_f32 v25, v231, v25, v243
	v_fma_f32 v26, v232, v26, v244
	v_fma_f32 v27, v233, v27, v245
	s_lshl_b32 s52, s41, 11
	s_add_i32 s52, s52, 2048
	v_add_u32_e32 v196, s52, v3
	v_mul_f32_e32 v108, 0xbfb8aa3b, v16
	v_exp_f32_e32 v109, v108
	s_nop 0
	v_add_f32_e32 v110, 1.0, v109
	v_div_scale_f32 v111, s[54:55], v110, v110, 1.0
	v_rcp_f32_e32 v112, v111
	v_div_scale_f32 v113, vcc, 1.0, v110, 1.0
	v_fma_f32 v115, -v111, v112, 1.0
	v_fmac_f32_e32 v112, v115, v112
	v_mul_f32_e32 v114, v113, v112
	v_fma_f32 v115, -v111, v114, v113
	v_fmac_f32_e32 v114, v115, v112
	v_fma_f32 v115, -v111, v114, v113
	v_div_fmas_f32 v115, v115, v112, v114
	v_div_fixup_f32 v115, v115, v110, 1.0
	v_mul_f32_e32 v120, v16, v115
	v_mul_f32_e32 v108, 0xbfb8aa3b, v17
	v_exp_f32_e32 v109, v108
	s_nop 0
	v_add_f32_e32 v110, 1.0, v109
	v_div_scale_f32 v111, s[54:55], v110, v110, 1.0
	v_rcp_f32_e32 v112, v111
	v_div_scale_f32 v113, vcc, 1.0, v110, 1.0
	v_fma_f32 v115, -v111, v112, 1.0
	v_fmac_f32_e32 v112, v115, v112
	v_mul_f32_e32 v114, v113, v112
	v_fma_f32 v115, -v111, v114, v113
	v_fmac_f32_e32 v114, v115, v112
	v_fma_f32 v115, -v111, v114, v113
	v_div_fmas_f32 v115, v115, v112, v114
	v_div_fixup_f32 v115, v115, v110, 1.0
	v_mul_f32_e32 v121, v17, v115
	v_mul_f32_e32 v108, 0xbfb8aa3b, v18
	v_exp_f32_e32 v109, v108
	s_nop 0
	v_add_f32_e32 v110, 1.0, v109
	v_div_scale_f32 v111, s[54:55], v110, v110, 1.0
	v_rcp_f32_e32 v112, v111
	v_div_scale_f32 v113, vcc, 1.0, v110, 1.0
	v_fma_f32 v115, -v111, v112, 1.0
	v_fmac_f32_e32 v112, v115, v112
	v_mul_f32_e32 v114, v113, v112
	v_fma_f32 v115, -v111, v114, v113
	v_fmac_f32_e32 v114, v115, v112
	v_fma_f32 v115, -v111, v114, v113
	v_div_fmas_f32 v115, v115, v112, v114
	v_div_fixup_f32 v115, v115, v110, 1.0
	v_mul_f32_e32 v122, v18, v115
	v_mul_f32_e32 v108, 0xbfb8aa3b, v19
	v_exp_f32_e32 v109, v108
	s_nop 0
	v_add_f32_e32 v110, 1.0, v109
	v_div_scale_f32 v111, s[54:55], v110, v110, 1.0
	v_rcp_f32_e32 v112, v111
	v_div_scale_f32 v113, vcc, 1.0, v110, 1.0
	v_fma_f32 v115, -v111, v112, 1.0
	v_fmac_f32_e32 v112, v115, v112
	v_mul_f32_e32 v114, v113, v112
	v_fma_f32 v115, -v111, v114, v113
	v_fmac_f32_e32 v114, v115, v112
	v_fma_f32 v115, -v111, v114, v113
	v_div_fmas_f32 v115, v115, v112, v114
	v_div_fixup_f32 v115, v115, v110, 1.0
	v_mul_f32_e32 v123, v19, v115
	v_cvt_pk_bf16_f32 v124, v120, v121
	v_cvt_pk_bf16_f32 v125, v122, v123
	global_store_dwordx2 v196, v[124:125], s[44:45]
	v_mul_f32_e32 v108, 0xbfb8aa3b, v20
	v_exp_f32_e32 v109, v108
	s_nop 0
	v_add_f32_e32 v110, 1.0, v109
	v_div_scale_f32 v111, s[54:55], v110, v110, 1.0
	v_rcp_f32_e32 v112, v111
	v_div_scale_f32 v113, vcc, 1.0, v110, 1.0
	v_fma_f32 v115, -v111, v112, 1.0
	v_fmac_f32_e32 v112, v115, v112
	v_mul_f32_e32 v114, v113, v112
	v_fma_f32 v115, -v111, v114, v113
	v_fmac_f32_e32 v114, v115, v112
	v_fma_f32 v115, -v111, v114, v113
	v_div_fmas_f32 v115, v115, v112, v114
	v_div_fixup_f32 v115, v115, v110, 1.0
	v_mul_f32_e32 v120, v20, v115
	v_mul_f32_e32 v108, 0xbfb8aa3b, v21
	v_exp_f32_e32 v109, v108
	s_nop 0
	v_add_f32_e32 v110, 1.0, v109
	v_div_scale_f32 v111, s[54:55], v110, v110, 1.0
	v_rcp_f32_e32 v112, v111
	v_div_scale_f32 v113, vcc, 1.0, v110, 1.0
	v_fma_f32 v115, -v111, v112, 1.0
	v_fmac_f32_e32 v112, v115, v112
	v_mul_f32_e32 v114, v113, v112
	v_fma_f32 v115, -v111, v114, v113
	v_fmac_f32_e32 v114, v115, v112
	v_fma_f32 v115, -v111, v114, v113
	v_div_fmas_f32 v115, v115, v112, v114
	v_div_fixup_f32 v115, v115, v110, 1.0
	v_mul_f32_e32 v121, v21, v115
	v_mul_f32_e32 v108, 0xbfb8aa3b, v22
	v_exp_f32_e32 v109, v108
	s_nop 0
	v_add_f32_e32 v110, 1.0, v109
	v_div_scale_f32 v111, s[54:55], v110, v110, 1.0
	v_rcp_f32_e32 v112, v111
	v_div_scale_f32 v113, vcc, 1.0, v110, 1.0
	v_fma_f32 v115, -v111, v112, 1.0
	v_fmac_f32_e32 v112, v115, v112
	v_mul_f32_e32 v114, v113, v112
	v_fma_f32 v115, -v111, v114, v113
	v_fmac_f32_e32 v114, v115, v112
	v_fma_f32 v115, -v111, v114, v113
	v_div_fmas_f32 v115, v115, v112, v114
	v_div_fixup_f32 v115, v115, v110, 1.0
	v_mul_f32_e32 v122, v22, v115
	v_mul_f32_e32 v108, 0xbfb8aa3b, v23
	v_exp_f32_e32 v109, v108
	s_nop 0
	v_add_f32_e32 v110, 1.0, v109
	v_div_scale_f32 v111, s[54:55], v110, v110, 1.0
	v_rcp_f32_e32 v112, v111
	v_div_scale_f32 v113, vcc, 1.0, v110, 1.0
	v_fma_f32 v115, -v111, v112, 1.0
	v_fmac_f32_e32 v112, v115, v112
	v_mul_f32_e32 v114, v113, v112
	v_fma_f32 v115, -v111, v114, v113
	v_fmac_f32_e32 v114, v115, v112
	v_fma_f32 v115, -v111, v114, v113
	v_div_fmas_f32 v115, v115, v112, v114
	v_div_fixup_f32 v115, v115, v110, 1.0
	v_mul_f32_e32 v123, v23, v115
	v_cvt_pk_bf16_f32 v124, v120, v121
	v_cvt_pk_bf16_f32 v125, v122, v123
	global_store_dwordx2 v196, v[124:125], s[44:45] offset:512
	v_mul_f32_e32 v108, 0xbfb8aa3b, v24
	v_exp_f32_e32 v109, v108
	s_nop 0
	v_add_f32_e32 v110, 1.0, v109
	v_div_scale_f32 v111, s[54:55], v110, v110, 1.0
	v_rcp_f32_e32 v112, v111
	v_div_scale_f32 v113, vcc, 1.0, v110, 1.0
	v_fma_f32 v115, -v111, v112, 1.0
	v_fmac_f32_e32 v112, v115, v112
	v_mul_f32_e32 v114, v113, v112
	v_fma_f32 v115, -v111, v114, v113
	v_fmac_f32_e32 v114, v115, v112
	v_fma_f32 v115, -v111, v114, v113
	v_div_fmas_f32 v115, v115, v112, v114
	v_div_fixup_f32 v115, v115, v110, 1.0
	v_mul_f32_e32 v120, v24, v115
	v_mul_f32_e32 v108, 0xbfb8aa3b, v25
	v_exp_f32_e32 v109, v108
	s_nop 0
	v_add_f32_e32 v110, 1.0, v109
	v_div_scale_f32 v111, s[54:55], v110, v110, 1.0
	v_rcp_f32_e32 v112, v111
	v_div_scale_f32 v113, vcc, 1.0, v110, 1.0
	v_fma_f32 v115, -v111, v112, 1.0
	v_fmac_f32_e32 v112, v115, v112
	v_mul_f32_e32 v114, v113, v112
	v_fma_f32 v115, -v111, v114, v113
	v_fmac_f32_e32 v114, v115, v112
	v_fma_f32 v115, -v111, v114, v113
	v_div_fmas_f32 v115, v115, v112, v114
	v_div_fixup_f32 v115, v115, v110, 1.0
	v_mul_f32_e32 v121, v25, v115
	v_mul_f32_e32 v108, 0xbfb8aa3b, v26
	v_exp_f32_e32 v109, v108
	s_nop 0
	v_add_f32_e32 v110, 1.0, v109
	v_div_scale_f32 v111, s[54:55], v110, v110, 1.0
	v_rcp_f32_e32 v112, v111
	v_div_scale_f32 v113, vcc, 1.0, v110, 1.0
	v_fma_f32 v115, -v111, v112, 1.0
	v_fmac_f32_e32 v112, v115, v112
	v_mul_f32_e32 v114, v113, v112
	v_fma_f32 v115, -v111, v114, v113
	v_fmac_f32_e32 v114, v115, v112
	v_fma_f32 v115, -v111, v114, v113
	v_div_fmas_f32 v115, v115, v112, v114
	v_div_fixup_f32 v115, v115, v110, 1.0
	v_mul_f32_e32 v122, v26, v115
	v_mul_f32_e32 v108, 0xbfb8aa3b, v27
	v_exp_f32_e32 v109, v108
	s_nop 0
	v_add_f32_e32 v110, 1.0, v109
	v_div_scale_f32 v111, s[54:55], v110, v110, 1.0
	v_rcp_f32_e32 v112, v111
	v_div_scale_f32 v113, vcc, 1.0, v110, 1.0
	v_fma_f32 v115, -v111, v112, 1.0
	v_fmac_f32_e32 v112, v115, v112
	v_mul_f32_e32 v114, v113, v112
	v_fma_f32 v115, -v111, v114, v113
	v_fmac_f32_e32 v114, v115, v112
	v_fma_f32 v115, -v111, v114, v113
	v_div_fmas_f32 v115, v115, v112, v114
	v_div_fixup_f32 v115, v115, v110, 1.0
	v_mul_f32_e32 v123, v27, v115
	v_cvt_pk_bf16_f32 v124, v120, v121
	v_cvt_pk_bf16_f32 v125, v122, v123
	global_store_dwordx2 v196, v[124:125], s[44:45] offset:1024
	v_add_f32_e32 v100, v28, v29
	v_add_f32_e32 v100, v100, v30
	v_add_f32_e32 v100, v100, v31
	v_add_f32_e32 v100, v100, v32
	v_add_f32_e32 v100, v100, v33
	v_add_f32_e32 v100, v100, v34
	v_add_f32_e32 v100, v100, v35
	v_add_f32_e32 v100, v100, v36
	v_add_f32_e32 v100, v100, v37
	v_add_f32_e32 v100, v100, v38
	v_add_f32_e32 v100, v100, v39
	s_nop 1
	v_add_f32_dpp v100, v100, v100 row_shr:1 row_mask:0xf bank_mask:0xf bound_ctrl:1
	s_nop 1
	v_add_f32_dpp v100, v100, v100 row_shr:2 row_mask:0xf bank_mask:0xf bound_ctrl:1
	s_nop 1
	v_add_f32_dpp v100, v100, v100 row_shr:4 row_mask:0xf bank_mask:0xf bound_ctrl:1
	s_nop 1
	v_add_f32_dpp v100, v100, v100 row_shr:8 row_mask:0xf bank_mask:0xf bound_ctrl:1
	s_nop 1
	v_add_f32_dpp v100, v100, v100 row_bcast:15 row_mask:0xa bank_mask:0xf
	s_nop 1
	v_add_f32_dpp v100, v100, v100 row_bcast:31 row_mask:0xc bank_mask:0xf
	s_nop 0
	v_readlane_b32 s53, v100, 63
	s_nop 1
	v_mov_b32_e32 v101, s53
	v_fmac_f32_e32 v28, 0xbaaaaaab, v101
	v_fmac_f32_e32 v29, 0xbaaaaaab, v101
	v_fmac_f32_e32 v30, 0xbaaaaaab, v101
	v_fmac_f32_e32 v31, 0xbaaaaaab, v101
	v_fmac_f32_e32 v32, 0xbaaaaaab, v101
	v_fmac_f32_e32 v33, 0xbaaaaaab, v101
	v_fmac_f32_e32 v34, 0xbaaaaaab, v101
	v_fmac_f32_e32 v35, 0xbaaaaaab, v101
	v_fmac_f32_e32 v36, 0xbaaaaaab, v101
	v_fmac_f32_e32 v37, 0xbaaaaaab, v101
	v_fmac_f32_e32 v38, 0xbaaaaaab, v101
	v_fmac_f32_e32 v39, 0xbaaaaaab, v101
	v_mul_f32_e32 v102, v28, v28
	v_fmac_f32_e32 v102, v29, v29
	v_fmac_f32_e32 v102, v30, v30
	v_fmac_f32_e32 v102, v31, v31
	v_fmac_f32_e32 v102, v32, v32
	v_fmac_f32_e32 v102, v33, v33
	v_fmac_f32_e32 v102, v34, v34
	v_fmac_f32_e32 v102, v35, v35
	v_fmac_f32_e32 v102, v36, v36
	v_fmac_f32_e32 v102, v37, v37
	v_fmac_f32_e32 v102, v38, v38
	v_fmac_f32_e32 v102, v39, v39
	s_nop 1
	v_add_f32_dpp v102, v102, v102 row_shr:1 row_mask:0xf bank_mask:0xf bound_ctrl:1
	s_nop 1
	v_add_f32_dpp v102, v102, v102 row_shr:2 row_mask:0xf bank_mask:0xf bound_ctrl:1
	s_nop 1
	v_add_f32_dpp v102, v102, v102 row_shr:4 row_mask:0xf bank_mask:0xf bound_ctrl:1
	s_nop 1
	v_add_f32_dpp v102, v102, v102 row_shr:8 row_mask:0xf bank_mask:0xf bound_ctrl:1
	s_nop 1
	v_add_f32_dpp v102, v102, v102 row_bcast:15 row_mask:0xa bank_mask:0xf
	s_nop 1
	v_add_f32_dpp v102, v102, v102 row_bcast:31 row_mask:0xc bank_mask:0xf
	s_nop 0
	v_readlane_b32 s53, v102, 63
	s_nop 1
	v_mov_b32_e32 v101, s53
	v_fmamk_f32 v101, v101, 0x3aaaaaab, v197
	v_rsq_f32_e32 v103, v101
	s_nop 0
	v_mul_f32_e32 v28, v28, v103
	v_mul_f32_e32 v29, v29, v103
	v_mul_f32_e32 v30, v30, v103
	v_mul_f32_e32 v31, v31, v103
	v_mul_f32_e32 v32, v32, v103
	v_mul_f32_e32 v33, v33, v103
	v_mul_f32_e32 v34, v34, v103
	v_mul_f32_e32 v35, v35, v103
	v_mul_f32_e32 v36, v36, v103
	v_mul_f32_e32 v37, v37, v103
	v_mul_f32_e32 v38, v38, v103
	v_mul_f32_e32 v39, v39, v103
	v_fma_f32 v28, v222, v28, v234
	v_fma_f32 v29, v223, v29, v235
	v_fma_f32 v30, v224, v30, v236
	v_fma_f32 v31, v225, v31, v237
	v_fma_f32 v32, v226, v32, v238
	v_fma_f32 v33, v227, v33, v239
	v_fma_f32 v34, v228, v34, v240
	v_fma_f32 v35, v229, v35, v241
	v_fma_f32 v36, v230, v36, v242
	v_fma_f32 v37, v231, v37, v243
	v_fma_f32 v38, v232, v38, v244
	v_fma_f32 v39, v233, v39, v245
	s_lshl_b32 s52, s41, 11
	s_add_i32 s52, s52, 4096
	v_add_u32_e32 v196, s52, v3
	v_mul_f32_e32 v108, 0xbfb8aa3b, v28
	v_exp_f32_e32 v109, v108
	s_nop 0
	v_add_f32_e32 v110, 1.0, v109
	v_div_scale_f32 v111, s[54:55], v110, v110, 1.0
	v_rcp_f32_e32 v112, v111
	v_div_scale_f32 v113, vcc, 1.0, v110, 1.0
	v_fma_f32 v115, -v111, v112, 1.0
	v_fmac_f32_e32 v112, v115, v112
	v_mul_f32_e32 v114, v113, v112
	v_fma_f32 v115, -v111, v114, v113
	v_fmac_f32_e32 v114, v115, v112
	v_fma_f32 v115, -v111, v114, v113
	v_div_fmas_f32 v115, v115, v112, v114
	v_div_fixup_f32 v115, v115, v110, 1.0
	v_mul_f32_e32 v120, v28, v115
	v_mul_f32_e32 v108, 0xbfb8aa3b, v29
	v_exp_f32_e32 v109, v108
	s_nop 0
	v_add_f32_e32 v110, 1.0, v109
	v_div_scale_f32 v111, s[54:55], v110, v110, 1.0
	v_rcp_f32_e32 v112, v111
	v_div_scale_f32 v113, vcc, 1.0, v110, 1.0
	v_fma_f32 v115, -v111, v112, 1.0
	v_fmac_f32_e32 v112, v115, v112
	v_mul_f32_e32 v114, v113, v112
	v_fma_f32 v115, -v111, v114, v113
	v_fmac_f32_e32 v114, v115, v112
	v_fma_f32 v115, -v111, v114, v113
	v_div_fmas_f32 v115, v115, v112, v114
	v_div_fixup_f32 v115, v115, v110, 1.0
	v_mul_f32_e32 v121, v29, v115
	v_mul_f32_e32 v108, 0xbfb8aa3b, v30
	v_exp_f32_e32 v109, v108
	s_nop 0
	v_add_f32_e32 v110, 1.0, v109
	v_div_scale_f32 v111, s[54:55], v110, v110, 1.0
	v_rcp_f32_e32 v112, v111
	v_div_scale_f32 v113, vcc, 1.0, v110, 1.0
	v_fma_f32 v115, -v111, v112, 1.0
	v_fmac_f32_e32 v112, v115, v112
	v_mul_f32_e32 v114, v113, v112
	v_fma_f32 v115, -v111, v114, v113
	v_fmac_f32_e32 v114, v115, v112
	v_fma_f32 v115, -v111, v114, v113
	v_div_fmas_f32 v115, v115, v112, v114
	v_div_fixup_f32 v115, v115, v110, 1.0
	v_mul_f32_e32 v122, v30, v115
	v_mul_f32_e32 v108, 0xbfb8aa3b, v31
	v_exp_f32_e32 v109, v108
	s_nop 0
	v_add_f32_e32 v110, 1.0, v109
	v_div_scale_f32 v111, s[54:55], v110, v110, 1.0
	v_rcp_f32_e32 v112, v111
	v_div_scale_f32 v113, vcc, 1.0, v110, 1.0
	v_fma_f32 v115, -v111, v112, 1.0
	v_fmac_f32_e32 v112, v115, v112
	v_mul_f32_e32 v114, v113, v112
	v_fma_f32 v115, -v111, v114, v113
	v_fmac_f32_e32 v114, v115, v112
	v_fma_f32 v115, -v111, v114, v113
	v_div_fmas_f32 v115, v115, v112, v114
	v_div_fixup_f32 v115, v115, v110, 1.0
	v_mul_f32_e32 v123, v31, v115
	v_cvt_pk_bf16_f32 v124, v120, v121
	v_cvt_pk_bf16_f32 v125, v122, v123
	global_store_dwordx2 v196, v[124:125], s[44:45]
	v_mul_f32_e32 v108, 0xbfb8aa3b, v32
	v_exp_f32_e32 v109, v108
	s_nop 0
	v_add_f32_e32 v110, 1.0, v109
	v_div_scale_f32 v111, s[54:55], v110, v110, 1.0
	v_rcp_f32_e32 v112, v111
	v_div_scale_f32 v113, vcc, 1.0, v110, 1.0
	v_fma_f32 v115, -v111, v112, 1.0
	v_fmac_f32_e32 v112, v115, v112
	v_mul_f32_e32 v114, v113, v112
	v_fma_f32 v115, -v111, v114, v113
	v_fmac_f32_e32 v114, v115, v112
	v_fma_f32 v115, -v111, v114, v113
	v_div_fmas_f32 v115, v115, v112, v114
	v_div_fixup_f32 v115, v115, v110, 1.0
	v_mul_f32_e32 v120, v32, v115
	v_mul_f32_e32 v108, 0xbfb8aa3b, v33
	v_exp_f32_e32 v109, v108
	s_nop 0
	v_add_f32_e32 v110, 1.0, v109
	v_div_scale_f32 v111, s[54:55], v110, v110, 1.0
	v_rcp_f32_e32 v112, v111
	v_div_scale_f32 v113, vcc, 1.0, v110, 1.0
	v_fma_f32 v115, -v111, v112, 1.0
	v_fmac_f32_e32 v112, v115, v112
	v_mul_f32_e32 v114, v113, v112
	v_fma_f32 v115, -v111, v114, v113
	v_fmac_f32_e32 v114, v115, v112
	v_fma_f32 v115, -v111, v114, v113
	v_div_fmas_f32 v115, v115, v112, v114
	v_div_fixup_f32 v115, v115, v110, 1.0
	v_mul_f32_e32 v121, v33, v115
	v_mul_f32_e32 v108, 0xbfb8aa3b, v34
	v_exp_f32_e32 v109, v108
	s_nop 0
	v_add_f32_e32 v110, 1.0, v109
	v_div_scale_f32 v111, s[54:55], v110, v110, 1.0
	v_rcp_f32_e32 v112, v111
	v_div_scale_f32 v113, vcc, 1.0, v110, 1.0
	v_fma_f32 v115, -v111, v112, 1.0
	v_fmac_f32_e32 v112, v115, v112
	v_mul_f32_e32 v114, v113, v112
	v_fma_f32 v115, -v111, v114, v113
	v_fmac_f32_e32 v114, v115, v112
	v_fma_f32 v115, -v111, v114, v113
	v_div_fmas_f32 v115, v115, v112, v114
	v_div_fixup_f32 v115, v115, v110, 1.0
	v_mul_f32_e32 v122, v34, v115
	v_mul_f32_e32 v108, 0xbfb8aa3b, v35
	v_exp_f32_e32 v109, v108
	s_nop 0
	v_add_f32_e32 v110, 1.0, v109
	v_div_scale_f32 v111, s[54:55], v110, v110, 1.0
	v_rcp_f32_e32 v112, v111
	v_div_scale_f32 v113, vcc, 1.0, v110, 1.0
	v_fma_f32 v115, -v111, v112, 1.0
	v_fmac_f32_e32 v112, v115, v112
	v_mul_f32_e32 v114, v113, v112
	v_fma_f32 v115, -v111, v114, v113
	v_fmac_f32_e32 v114, v115, v112
	v_fma_f32 v115, -v111, v114, v113
	v_div_fmas_f32 v115, v115, v112, v114
	v_div_fixup_f32 v115, v115, v110, 1.0
	v_mul_f32_e32 v123, v35, v115
	v_cvt_pk_bf16_f32 v124, v120, v121
	v_cvt_pk_bf16_f32 v125, v122, v123
	global_store_dwordx2 v196, v[124:125], s[44:45] offset:512
	v_mul_f32_e32 v108, 0xbfb8aa3b, v36
	v_exp_f32_e32 v109, v108
	s_nop 0
	v_add_f32_e32 v110, 1.0, v109
	v_div_scale_f32 v111, s[54:55], v110, v110, 1.0
	v_rcp_f32_e32 v112, v111
	v_div_scale_f32 v113, vcc, 1.0, v110, 1.0
	v_fma_f32 v115, -v111, v112, 1.0
	v_fmac_f32_e32 v112, v115, v112
	v_mul_f32_e32 v114, v113, v112
	v_fma_f32 v115, -v111, v114, v113
	v_fmac_f32_e32 v114, v115, v112
	v_fma_f32 v115, -v111, v114, v113
	v_div_fmas_f32 v115, v115, v112, v114
	v_div_fixup_f32 v115, v115, v110, 1.0
	v_mul_f32_e32 v120, v36, v115
	v_mul_f32_e32 v108, 0xbfb8aa3b, v37
	v_exp_f32_e32 v109, v108
	s_nop 0
	v_add_f32_e32 v110, 1.0, v109
	v_div_scale_f32 v111, s[54:55], v110, v110, 1.0
	v_rcp_f32_e32 v112, v111
	v_div_scale_f32 v113, vcc, 1.0, v110, 1.0
	v_fma_f32 v115, -v111, v112, 1.0
	v_fmac_f32_e32 v112, v115, v112
	v_mul_f32_e32 v114, v113, v112
	v_fma_f32 v115, -v111, v114, v113
	v_fmac_f32_e32 v114, v115, v112
	v_fma_f32 v115, -v111, v114, v113
	v_div_fmas_f32 v115, v115, v112, v114
	v_div_fixup_f32 v115, v115, v110, 1.0
	v_mul_f32_e32 v121, v37, v115
	v_mul_f32_e32 v108, 0xbfb8aa3b, v38
	v_exp_f32_e32 v109, v108
	s_nop 0
	v_add_f32_e32 v110, 1.0, v109
	v_div_scale_f32 v111, s[54:55], v110, v110, 1.0
	v_rcp_f32_e32 v112, v111
	v_div_scale_f32 v113, vcc, 1.0, v110, 1.0
	v_fma_f32 v115, -v111, v112, 1.0
	v_fmac_f32_e32 v112, v115, v112
	v_mul_f32_e32 v114, v113, v112
	v_fma_f32 v115, -v111, v114, v113
	v_fmac_f32_e32 v114, v115, v112
	v_fma_f32 v115, -v111, v114, v113
	v_div_fmas_f32 v115, v115, v112, v114
	v_div_fixup_f32 v115, v115, v110, 1.0
	v_mul_f32_e32 v122, v38, v115
	v_mul_f32_e32 v108, 0xbfb8aa3b, v39
	v_exp_f32_e32 v109, v108
	s_nop 0
	v_add_f32_e32 v110, 1.0, v109
	v_div_scale_f32 v111, s[54:55], v110, v110, 1.0
	v_rcp_f32_e32 v112, v111
	v_div_scale_f32 v113, vcc, 1.0, v110, 1.0
	v_fma_f32 v115, -v111, v112, 1.0
	v_fmac_f32_e32 v112, v115, v112
	v_mul_f32_e32 v114, v113, v112
	v_fma_f32 v115, -v111, v114, v113
	v_fmac_f32_e32 v114, v115, v112
	v_fma_f32 v115, -v111, v114, v113
	v_div_fmas_f32 v115, v115, v112, v114
	v_div_fixup_f32 v115, v115, v110, 1.0
	v_mul_f32_e32 v123, v39, v115
	v_cvt_pk_bf16_f32 v124, v120, v121
	v_cvt_pk_bf16_f32 v125, v122, v123
	global_store_dwordx2 v196, v[124:125], s[44:45] offset:1024
	v_add_f32_e32 v100, v40, v41
	v_add_f32_e32 v100, v100, v42
	v_add_f32_e32 v100, v100, v43
	v_add_f32_e32 v100, v100, v44
	v_add_f32_e32 v100, v100, v45
	v_add_f32_e32 v100, v100, v46
	v_add_f32_e32 v100, v100, v47
	v_add_f32_e32 v100, v100, v48
	v_add_f32_e32 v100, v100, v49
	v_add_f32_e32 v100, v100, v50
	v_add_f32_e32 v100, v100, v51
	s_nop 1
	v_add_f32_dpp v100, v100, v100 row_shr:1 row_mask:0xf bank_mask:0xf bound_ctrl:1
	s_nop 1
	v_add_f32_dpp v100, v100, v100 row_shr:2 row_mask:0xf bank_mask:0xf bound_ctrl:1
	s_nop 1
	v_add_f32_dpp v100, v100, v100 row_shr:4 row_mask:0xf bank_mask:0xf bound_ctrl:1
	s_nop 1
	v_add_f32_dpp v100, v100, v100 row_shr:8 row_mask:0xf bank_mask:0xf bound_ctrl:1
	s_nop 1
	v_add_f32_dpp v100, v100, v100 row_bcast:15 row_mask:0xa bank_mask:0xf
	s_nop 1
	v_add_f32_dpp v100, v100, v100 row_bcast:31 row_mask:0xc bank_mask:0xf
	s_nop 0
	v_readlane_b32 s53, v100, 63
	s_nop 1
	v_mov_b32_e32 v101, s53
	v_fmac_f32_e32 v40, 0xbaaaaaab, v101
	v_fmac_f32_e32 v41, 0xbaaaaaab, v101
	v_fmac_f32_e32 v42, 0xbaaaaaab, v101
	v_fmac_f32_e32 v43, 0xbaaaaaab, v101
	v_fmac_f32_e32 v44, 0xbaaaaaab, v101
	v_fmac_f32_e32 v45, 0xbaaaaaab, v101
	v_fmac_f32_e32 v46, 0xbaaaaaab, v101
	v_fmac_f32_e32 v47, 0xbaaaaaab, v101
	v_fmac_f32_e32 v48, 0xbaaaaaab, v101
	v_fmac_f32_e32 v49, 0xbaaaaaab, v101
	v_fmac_f32_e32 v50, 0xbaaaaaab, v101
	v_fmac_f32_e32 v51, 0xbaaaaaab, v101
	v_mul_f32_e32 v102, v40, v40
	v_fmac_f32_e32 v102, v41, v41
	v_fmac_f32_e32 v102, v42, v42
	v_fmac_f32_e32 v102, v43, v43
	v_fmac_f32_e32 v102, v44, v44
	v_fmac_f32_e32 v102, v45, v45
	v_fmac_f32_e32 v102, v46, v46
	v_fmac_f32_e32 v102, v47, v47
	v_fmac_f32_e32 v102, v48, v48
	v_fmac_f32_e32 v102, v49, v49
	v_fmac_f32_e32 v102, v50, v50
	v_fmac_f32_e32 v102, v51, v51
	s_nop 1
	v_add_f32_dpp v102, v102, v102 row_shr:1 row_mask:0xf bank_mask:0xf bound_ctrl:1
	s_nop 1
	v_add_f32_dpp v102, v102, v102 row_shr:2 row_mask:0xf bank_mask:0xf bound_ctrl:1
	s_nop 1
	v_add_f32_dpp v102, v102, v102 row_shr:4 row_mask:0xf bank_mask:0xf bound_ctrl:1
	s_nop 1
	v_add_f32_dpp v102, v102, v102 row_shr:8 row_mask:0xf bank_mask:0xf bound_ctrl:1
	s_nop 1
	v_add_f32_dpp v102, v102, v102 row_bcast:15 row_mask:0xa bank_mask:0xf
	s_nop 1
	v_add_f32_dpp v102, v102, v102 row_bcast:31 row_mask:0xc bank_mask:0xf
	s_nop 0
	v_readlane_b32 s53, v102, 63
	s_nop 1
	v_mov_b32_e32 v101, s53
	v_fmamk_f32 v101, v101, 0x3aaaaaab, v197
	v_rsq_f32_e32 v103, v101
	s_nop 0
	v_mul_f32_e32 v40, v40, v103
	v_mul_f32_e32 v41, v41, v103
	v_mul_f32_e32 v42, v42, v103
	v_mul_f32_e32 v43, v43, v103
	v_mul_f32_e32 v44, v44, v103
	v_mul_f32_e32 v45, v45, v103
	v_mul_f32_e32 v46, v46, v103
	v_mul_f32_e32 v47, v47, v103
	v_mul_f32_e32 v48, v48, v103
	v_mul_f32_e32 v49, v49, v103
	v_mul_f32_e32 v50, v50, v103
	v_mul_f32_e32 v51, v51, v103
	v_fma_f32 v40, v222, v40, v234
	v_fma_f32 v41, v223, v41, v235
	v_fma_f32 v42, v224, v42, v236
	v_fma_f32 v43, v225, v43, v237
	v_fma_f32 v44, v226, v44, v238
	v_fma_f32 v45, v227, v45, v239
	v_fma_f32 v46, v228, v46, v240
	v_fma_f32 v47, v229, v47, v241
	v_fma_f32 v48, v230, v48, v242
	v_fma_f32 v49, v231, v49, v243
	v_fma_f32 v50, v232, v50, v244
	v_fma_f32 v51, v233, v51, v245
	s_lshl_b32 s52, s41, 11
	s_add_i32 s52, s52, 6144
	v_add_u32_e32 v196, s52, v3
	v_mul_f32_e32 v108, 0xbfb8aa3b, v40
	v_exp_f32_e32 v109, v108
	s_nop 0
	v_add_f32_e32 v110, 1.0, v109
	v_div_scale_f32 v111, s[54:55], v110, v110, 1.0
	v_rcp_f32_e32 v112, v111
	v_div_scale_f32 v113, vcc, 1.0, v110, 1.0
	v_fma_f32 v115, -v111, v112, 1.0
	v_fmac_f32_e32 v112, v115, v112
	v_mul_f32_e32 v114, v113, v112
	v_fma_f32 v115, -v111, v114, v113
	v_fmac_f32_e32 v114, v115, v112
	v_fma_f32 v115, -v111, v114, v113
	v_div_fmas_f32 v115, v115, v112, v114
	v_div_fixup_f32 v115, v115, v110, 1.0
	v_mul_f32_e32 v120, v40, v115
	v_mul_f32_e32 v108, 0xbfb8aa3b, v41
	v_exp_f32_e32 v109, v108
	s_nop 0
	v_add_f32_e32 v110, 1.0, v109
	v_div_scale_f32 v111, s[54:55], v110, v110, 1.0
	v_rcp_f32_e32 v112, v111
	v_div_scale_f32 v113, vcc, 1.0, v110, 1.0
	v_fma_f32 v115, -v111, v112, 1.0
	v_fmac_f32_e32 v112, v115, v112
	v_mul_f32_e32 v114, v113, v112
	v_fma_f32 v115, -v111, v114, v113
	v_fmac_f32_e32 v114, v115, v112
	v_fma_f32 v115, -v111, v114, v113
	v_div_fmas_f32 v115, v115, v112, v114
	v_div_fixup_f32 v115, v115, v110, 1.0
	v_mul_f32_e32 v121, v41, v115
	v_mul_f32_e32 v108, 0xbfb8aa3b, v42
	v_exp_f32_e32 v109, v108
	s_nop 0
	v_add_f32_e32 v110, 1.0, v109
	v_div_scale_f32 v111, s[54:55], v110, v110, 1.0
	v_rcp_f32_e32 v112, v111
	v_div_scale_f32 v113, vcc, 1.0, v110, 1.0
	v_fma_f32 v115, -v111, v112, 1.0
	v_fmac_f32_e32 v112, v115, v112
	v_mul_f32_e32 v114, v113, v112
	v_fma_f32 v115, -v111, v114, v113
	v_fmac_f32_e32 v114, v115, v112
	v_fma_f32 v115, -v111, v114, v113
	v_div_fmas_f32 v115, v115, v112, v114
	v_div_fixup_f32 v115, v115, v110, 1.0
	v_mul_f32_e32 v122, v42, v115
	v_mul_f32_e32 v108, 0xbfb8aa3b, v43
	v_exp_f32_e32 v109, v108
	s_nop 0
	v_add_f32_e32 v110, 1.0, v109
	v_div_scale_f32 v111, s[54:55], v110, v110, 1.0
	v_rcp_f32_e32 v112, v111
	v_div_scale_f32 v113, vcc, 1.0, v110, 1.0
	v_fma_f32 v115, -v111, v112, 1.0
	v_fmac_f32_e32 v112, v115, v112
	v_mul_f32_e32 v114, v113, v112
	v_fma_f32 v115, -v111, v114, v113
	v_fmac_f32_e32 v114, v115, v112
	v_fma_f32 v115, -v111, v114, v113
	v_div_fmas_f32 v115, v115, v112, v114
	v_div_fixup_f32 v115, v115, v110, 1.0
	v_mul_f32_e32 v123, v43, v115
	v_cvt_pk_bf16_f32 v124, v120, v121
	v_cvt_pk_bf16_f32 v125, v122, v123
	global_store_dwordx2 v196, v[124:125], s[44:45]
	v_mul_f32_e32 v108, 0xbfb8aa3b, v44
	v_exp_f32_e32 v109, v108
	s_nop 0
	v_add_f32_e32 v110, 1.0, v109
	v_div_scale_f32 v111, s[54:55], v110, v110, 1.0
	v_rcp_f32_e32 v112, v111
	v_div_scale_f32 v113, vcc, 1.0, v110, 1.0
	v_fma_f32 v115, -v111, v112, 1.0
	v_fmac_f32_e32 v112, v115, v112
	v_mul_f32_e32 v114, v113, v112
	v_fma_f32 v115, -v111, v114, v113
	v_fmac_f32_e32 v114, v115, v112
	v_fma_f32 v115, -v111, v114, v113
	v_div_fmas_f32 v115, v115, v112, v114
	v_div_fixup_f32 v115, v115, v110, 1.0
	v_mul_f32_e32 v120, v44, v115
	v_mul_f32_e32 v108, 0xbfb8aa3b, v45
	v_exp_f32_e32 v109, v108
	s_nop 0
	v_add_f32_e32 v110, 1.0, v109
	v_div_scale_f32 v111, s[54:55], v110, v110, 1.0
	v_rcp_f32_e32 v112, v111
	v_div_scale_f32 v113, vcc, 1.0, v110, 1.0
	v_fma_f32 v115, -v111, v112, 1.0
	v_fmac_f32_e32 v112, v115, v112
	v_mul_f32_e32 v114, v113, v112
	v_fma_f32 v115, -v111, v114, v113
	v_fmac_f32_e32 v114, v115, v112
	v_fma_f32 v115, -v111, v114, v113
	v_div_fmas_f32 v115, v115, v112, v114
	v_div_fixup_f32 v115, v115, v110, 1.0
	v_mul_f32_e32 v121, v45, v115
	v_mul_f32_e32 v108, 0xbfb8aa3b, v46
	v_exp_f32_e32 v109, v108
	s_nop 0
	v_add_f32_e32 v110, 1.0, v109
	v_div_scale_f32 v111, s[54:55], v110, v110, 1.0
	v_rcp_f32_e32 v112, v111
	v_div_scale_f32 v113, vcc, 1.0, v110, 1.0
	v_fma_f32 v115, -v111, v112, 1.0
	v_fmac_f32_e32 v112, v115, v112
	v_mul_f32_e32 v114, v113, v112
	v_fma_f32 v115, -v111, v114, v113
	v_fmac_f32_e32 v114, v115, v112
	v_fma_f32 v115, -v111, v114, v113
	v_div_fmas_f32 v115, v115, v112, v114
	v_div_fixup_f32 v115, v115, v110, 1.0
	v_mul_f32_e32 v122, v46, v115
	v_mul_f32_e32 v108, 0xbfb8aa3b, v47
	v_exp_f32_e32 v109, v108
	s_nop 0
	v_add_f32_e32 v110, 1.0, v109
	v_div_scale_f32 v111, s[54:55], v110, v110, 1.0
	v_rcp_f32_e32 v112, v111
	v_div_scale_f32 v113, vcc, 1.0, v110, 1.0
	v_fma_f32 v115, -v111, v112, 1.0
	v_fmac_f32_e32 v112, v115, v112
	v_mul_f32_e32 v114, v113, v112
	v_fma_f32 v115, -v111, v114, v113
	v_fmac_f32_e32 v114, v115, v112
	v_fma_f32 v115, -v111, v114, v113
	v_div_fmas_f32 v115, v115, v112, v114
	v_div_fixup_f32 v115, v115, v110, 1.0
	v_mul_f32_e32 v123, v47, v115
	v_cvt_pk_bf16_f32 v124, v120, v121
	v_cvt_pk_bf16_f32 v125, v122, v123
	global_store_dwordx2 v196, v[124:125], s[44:45] offset:512
	v_mul_f32_e32 v108, 0xbfb8aa3b, v48
	v_exp_f32_e32 v109, v108
	s_nop 0
	v_add_f32_e32 v110, 1.0, v109
	v_div_scale_f32 v111, s[54:55], v110, v110, 1.0
	v_rcp_f32_e32 v112, v111
	v_div_scale_f32 v113, vcc, 1.0, v110, 1.0
	v_fma_f32 v115, -v111, v112, 1.0
	v_fmac_f32_e32 v112, v115, v112
	v_mul_f32_e32 v114, v113, v112
	v_fma_f32 v115, -v111, v114, v113
	v_fmac_f32_e32 v114, v115, v112
	v_fma_f32 v115, -v111, v114, v113
	v_div_fmas_f32 v115, v115, v112, v114
	v_div_fixup_f32 v115, v115, v110, 1.0
	v_mul_f32_e32 v120, v48, v115
	v_mul_f32_e32 v108, 0xbfb8aa3b, v49
	v_exp_f32_e32 v109, v108
	s_nop 0
	v_add_f32_e32 v110, 1.0, v109
	v_div_scale_f32 v111, s[54:55], v110, v110, 1.0
	v_rcp_f32_e32 v112, v111
	v_div_scale_f32 v113, vcc, 1.0, v110, 1.0
	v_fma_f32 v115, -v111, v112, 1.0
	v_fmac_f32_e32 v112, v115, v112
	v_mul_f32_e32 v114, v113, v112
	v_fma_f32 v115, -v111, v114, v113
	v_fmac_f32_e32 v114, v115, v112
	v_fma_f32 v115, -v111, v114, v113
	v_div_fmas_f32 v115, v115, v112, v114
	v_div_fixup_f32 v115, v115, v110, 1.0
	v_mul_f32_e32 v121, v49, v115
	v_mul_f32_e32 v108, 0xbfb8aa3b, v50
	v_exp_f32_e32 v109, v108
	s_nop 0
	v_add_f32_e32 v110, 1.0, v109
	v_div_scale_f32 v111, s[54:55], v110, v110, 1.0
	v_rcp_f32_e32 v112, v111
	v_div_scale_f32 v113, vcc, 1.0, v110, 1.0
	v_fma_f32 v115, -v111, v112, 1.0
	v_fmac_f32_e32 v112, v115, v112
	v_mul_f32_e32 v114, v113, v112
	v_fma_f32 v115, -v111, v114, v113
	v_fmac_f32_e32 v114, v115, v112
	v_fma_f32 v115, -v111, v114, v113
	v_div_fmas_f32 v115, v115, v112, v114
	v_div_fixup_f32 v115, v115, v110, 1.0
	v_mul_f32_e32 v122, v50, v115
	v_mul_f32_e32 v108, 0xbfb8aa3b, v51
	v_exp_f32_e32 v109, v108
	s_nop 0
	v_add_f32_e32 v110, 1.0, v109
	v_div_scale_f32 v111, s[54:55], v110, v110, 1.0
	v_rcp_f32_e32 v112, v111
	v_div_scale_f32 v113, vcc, 1.0, v110, 1.0
	v_fma_f32 v115, -v111, v112, 1.0
	v_fmac_f32_e32 v112, v115, v112
	v_mul_f32_e32 v114, v113, v112
	v_fma_f32 v115, -v111, v114, v113
	v_fmac_f32_e32 v114, v115, v112
	v_fma_f32 v115, -v111, v114, v113
	v_div_fmas_f32 v115, v115, v112, v114
	v_div_fixup_f32 v115, v115, v110, 1.0
	v_mul_f32_e32 v123, v51, v115
	v_cvt_pk_bf16_f32 v124, v120, v121
	v_cvt_pk_bf16_f32 v125, v122, v123
	global_store_dwordx2 v196, v[124:125], s[44:45] offset:1024
	v_add_f32_e32 v100, v52, v53
	v_add_f32_e32 v100, v100, v54
	v_add_f32_e32 v100, v100, v55
	v_add_f32_e32 v100, v100, v56
	v_add_f32_e32 v100, v100, v57
	v_add_f32_e32 v100, v100, v58
	v_add_f32_e32 v100, v100, v59
	v_add_f32_e32 v100, v100, v60
	v_add_f32_e32 v100, v100, v61
	v_add_f32_e32 v100, v100, v62
	v_add_f32_e32 v100, v100, v63
	s_nop 1
	v_add_f32_dpp v100, v100, v100 row_shr:1 row_mask:0xf bank_mask:0xf bound_ctrl:1
	s_nop 1
	v_add_f32_dpp v100, v100, v100 row_shr:2 row_mask:0xf bank_mask:0xf bound_ctrl:1
	s_nop 1
	v_add_f32_dpp v100, v100, v100 row_shr:4 row_mask:0xf bank_mask:0xf bound_ctrl:1
	s_nop 1
	v_add_f32_dpp v100, v100, v100 row_shr:8 row_mask:0xf bank_mask:0xf bound_ctrl:1
	s_nop 1
	v_add_f32_dpp v100, v100, v100 row_bcast:15 row_mask:0xa bank_mask:0xf
	s_nop 1
	v_add_f32_dpp v100, v100, v100 row_bcast:31 row_mask:0xc bank_mask:0xf
	s_nop 0
	v_readlane_b32 s53, v100, 63
	s_nop 1
	v_mov_b32_e32 v101, s53
	v_fmac_f32_e32 v52, 0xbaaaaaab, v101
	v_fmac_f32_e32 v53, 0xbaaaaaab, v101
	v_fmac_f32_e32 v54, 0xbaaaaaab, v101
	v_fmac_f32_e32 v55, 0xbaaaaaab, v101
	v_fmac_f32_e32 v56, 0xbaaaaaab, v101
	v_fmac_f32_e32 v57, 0xbaaaaaab, v101
	v_fmac_f32_e32 v58, 0xbaaaaaab, v101
	v_fmac_f32_e32 v59, 0xbaaaaaab, v101
	v_fmac_f32_e32 v60, 0xbaaaaaab, v101
	v_fmac_f32_e32 v61, 0xbaaaaaab, v101
	v_fmac_f32_e32 v62, 0xbaaaaaab, v101
	v_fmac_f32_e32 v63, 0xbaaaaaab, v101
	v_mul_f32_e32 v102, v52, v52
	v_fmac_f32_e32 v102, v53, v53
	v_fmac_f32_e32 v102, v54, v54
	v_fmac_f32_e32 v102, v55, v55
	v_fmac_f32_e32 v102, v56, v56
	v_fmac_f32_e32 v102, v57, v57
	v_fmac_f32_e32 v102, v58, v58
	v_fmac_f32_e32 v102, v59, v59
	v_fmac_f32_e32 v102, v60, v60
	v_fmac_f32_e32 v102, v61, v61
	v_fmac_f32_e32 v102, v62, v62
	v_fmac_f32_e32 v102, v63, v63
	s_nop 1
	v_add_f32_dpp v102, v102, v102 row_shr:1 row_mask:0xf bank_mask:0xf bound_ctrl:1
	s_nop 1
	v_add_f32_dpp v102, v102, v102 row_shr:2 row_mask:0xf bank_mask:0xf bound_ctrl:1
	s_nop 1
	v_add_f32_dpp v102, v102, v102 row_shr:4 row_mask:0xf bank_mask:0xf bound_ctrl:1
	s_nop 1
	v_add_f32_dpp v102, v102, v102 row_shr:8 row_mask:0xf bank_mask:0xf bound_ctrl:1
	s_nop 1
	v_add_f32_dpp v102, v102, v102 row_bcast:15 row_mask:0xa bank_mask:0xf
	s_nop 1
	v_add_f32_dpp v102, v102, v102 row_bcast:31 row_mask:0xc bank_mask:0xf
	s_nop 0
	v_readlane_b32 s53, v102, 63
	s_nop 1
	v_mov_b32_e32 v101, s53
	v_fmamk_f32 v101, v101, 0x3aaaaaab, v197
	v_rsq_f32_e32 v103, v101
	s_nop 0
	v_mul_f32_e32 v52, v52, v103
	v_mul_f32_e32 v53, v53, v103
	v_mul_f32_e32 v54, v54, v103
	v_mul_f32_e32 v55, v55, v103
	v_mul_f32_e32 v56, v56, v103
	v_mul_f32_e32 v57, v57, v103
	v_mul_f32_e32 v58, v58, v103
	v_mul_f32_e32 v59, v59, v103
	v_mul_f32_e32 v60, v60, v103
	v_mul_f32_e32 v61, v61, v103
	v_mul_f32_e32 v62, v62, v103
	v_mul_f32_e32 v63, v63, v103
	v_fma_f32 v52, v222, v52, v234
	v_fma_f32 v53, v223, v53, v235
	v_fma_f32 v54, v224, v54, v236
	v_fma_f32 v55, v225, v55, v237
	v_fma_f32 v56, v226, v56, v238
	v_fma_f32 v57, v227, v57, v239
	v_fma_f32 v58, v228, v58, v240
	v_fma_f32 v59, v229, v59, v241
	v_fma_f32 v60, v230, v60, v242
	v_fma_f32 v61, v231, v61, v243
	v_fma_f32 v62, v232, v62, v244
	v_fma_f32 v63, v233, v63, v245
	s_lshl_b32 s52, s41, 11
	s_add_i32 s52, s52, 8192
	v_add_u32_e32 v196, s52, v3
	v_mul_f32_e32 v108, 0xbfb8aa3b, v52
	v_exp_f32_e32 v109, v108
	s_nop 0
	v_add_f32_e32 v110, 1.0, v109
	v_div_scale_f32 v111, s[54:55], v110, v110, 1.0
	v_rcp_f32_e32 v112, v111
	v_div_scale_f32 v113, vcc, 1.0, v110, 1.0
	v_fma_f32 v115, -v111, v112, 1.0
	v_fmac_f32_e32 v112, v115, v112
	v_mul_f32_e32 v114, v113, v112
	v_fma_f32 v115, -v111, v114, v113
	v_fmac_f32_e32 v114, v115, v112
	v_fma_f32 v115, -v111, v114, v113
	v_div_fmas_f32 v115, v115, v112, v114
	v_div_fixup_f32 v115, v115, v110, 1.0
	v_mul_f32_e32 v120, v52, v115
	v_mul_f32_e32 v108, 0xbfb8aa3b, v53
	v_exp_f32_e32 v109, v108
	s_nop 0
	v_add_f32_e32 v110, 1.0, v109
	v_div_scale_f32 v111, s[54:55], v110, v110, 1.0
	v_rcp_f32_e32 v112, v111
	v_div_scale_f32 v113, vcc, 1.0, v110, 1.0
	v_fma_f32 v115, -v111, v112, 1.0
	v_fmac_f32_e32 v112, v115, v112
	v_mul_f32_e32 v114, v113, v112
	v_fma_f32 v115, -v111, v114, v113
	v_fmac_f32_e32 v114, v115, v112
	v_fma_f32 v115, -v111, v114, v113
	v_div_fmas_f32 v115, v115, v112, v114
	v_div_fixup_f32 v115, v115, v110, 1.0
	v_mul_f32_e32 v121, v53, v115
	v_mul_f32_e32 v108, 0xbfb8aa3b, v54
	v_exp_f32_e32 v109, v108
	s_nop 0
	v_add_f32_e32 v110, 1.0, v109
	v_div_scale_f32 v111, s[54:55], v110, v110, 1.0
	v_rcp_f32_e32 v112, v111
	v_div_scale_f32 v113, vcc, 1.0, v110, 1.0
	v_fma_f32 v115, -v111, v112, 1.0
	v_fmac_f32_e32 v112, v115, v112
	v_mul_f32_e32 v114, v113, v112
	v_fma_f32 v115, -v111, v114, v113
	v_fmac_f32_e32 v114, v115, v112
	v_fma_f32 v115, -v111, v114, v113
	v_div_fmas_f32 v115, v115, v112, v114
	v_div_fixup_f32 v115, v115, v110, 1.0
	v_mul_f32_e32 v122, v54, v115
	v_mul_f32_e32 v108, 0xbfb8aa3b, v55
	v_exp_f32_e32 v109, v108
	s_nop 0
	v_add_f32_e32 v110, 1.0, v109
	v_div_scale_f32 v111, s[54:55], v110, v110, 1.0
	v_rcp_f32_e32 v112, v111
	v_div_scale_f32 v113, vcc, 1.0, v110, 1.0
	v_fma_f32 v115, -v111, v112, 1.0
	v_fmac_f32_e32 v112, v115, v112
	v_mul_f32_e32 v114, v113, v112
	v_fma_f32 v115, -v111, v114, v113
	v_fmac_f32_e32 v114, v115, v112
	v_fma_f32 v115, -v111, v114, v113
	v_div_fmas_f32 v115, v115, v112, v114
	v_div_fixup_f32 v115, v115, v110, 1.0
	v_mul_f32_e32 v123, v55, v115
	v_cvt_pk_bf16_f32 v124, v120, v121
	v_cvt_pk_bf16_f32 v125, v122, v123
	global_store_dwordx2 v196, v[124:125], s[44:45]
	v_mul_f32_e32 v108, 0xbfb8aa3b, v56
	v_exp_f32_e32 v109, v108
	s_nop 0
	v_add_f32_e32 v110, 1.0, v109
	v_div_scale_f32 v111, s[54:55], v110, v110, 1.0
	v_rcp_f32_e32 v112, v111
	v_div_scale_f32 v113, vcc, 1.0, v110, 1.0
	v_fma_f32 v115, -v111, v112, 1.0
	v_fmac_f32_e32 v112, v115, v112
	v_mul_f32_e32 v114, v113, v112
	v_fma_f32 v115, -v111, v114, v113
	v_fmac_f32_e32 v114, v115, v112
	v_fma_f32 v115, -v111, v114, v113
	v_div_fmas_f32 v115, v115, v112, v114
	v_div_fixup_f32 v115, v115, v110, 1.0
	v_mul_f32_e32 v120, v56, v115
	v_mul_f32_e32 v108, 0xbfb8aa3b, v57
	v_exp_f32_e32 v109, v108
	s_nop 0
	v_add_f32_e32 v110, 1.0, v109
	v_div_scale_f32 v111, s[54:55], v110, v110, 1.0
	v_rcp_f32_e32 v112, v111
	v_div_scale_f32 v113, vcc, 1.0, v110, 1.0
	v_fma_f32 v115, -v111, v112, 1.0
	v_fmac_f32_e32 v112, v115, v112
	v_mul_f32_e32 v114, v113, v112
	v_fma_f32 v115, -v111, v114, v113
	v_fmac_f32_e32 v114, v115, v112
	v_fma_f32 v115, -v111, v114, v113
	v_div_fmas_f32 v115, v115, v112, v114
	v_div_fixup_f32 v115, v115, v110, 1.0
	v_mul_f32_e32 v121, v57, v115
	v_mul_f32_e32 v108, 0xbfb8aa3b, v58
	v_exp_f32_e32 v109, v108
	s_nop 0
	v_add_f32_e32 v110, 1.0, v109
	v_div_scale_f32 v111, s[54:55], v110, v110, 1.0
	v_rcp_f32_e32 v112, v111
	v_div_scale_f32 v113, vcc, 1.0, v110, 1.0
	v_fma_f32 v115, -v111, v112, 1.0
	v_fmac_f32_e32 v112, v115, v112
	v_mul_f32_e32 v114, v113, v112
	v_fma_f32 v115, -v111, v114, v113
	v_fmac_f32_e32 v114, v115, v112
	v_fma_f32 v115, -v111, v114, v113
	v_div_fmas_f32 v115, v115, v112, v114
	v_div_fixup_f32 v115, v115, v110, 1.0
	v_mul_f32_e32 v122, v58, v115
	v_mul_f32_e32 v108, 0xbfb8aa3b, v59
	v_exp_f32_e32 v109, v108
	s_nop 0
	v_add_f32_e32 v110, 1.0, v109
	v_div_scale_f32 v111, s[54:55], v110, v110, 1.0
	v_rcp_f32_e32 v112, v111
	v_div_scale_f32 v113, vcc, 1.0, v110, 1.0
	v_fma_f32 v115, -v111, v112, 1.0
	v_fmac_f32_e32 v112, v115, v112
	v_mul_f32_e32 v114, v113, v112
	v_fma_f32 v115, -v111, v114, v113
	v_fmac_f32_e32 v114, v115, v112
	v_fma_f32 v115, -v111, v114, v113
	v_div_fmas_f32 v115, v115, v112, v114
	v_div_fixup_f32 v115, v115, v110, 1.0
	v_mul_f32_e32 v123, v59, v115
	v_cvt_pk_bf16_f32 v124, v120, v121
	v_cvt_pk_bf16_f32 v125, v122, v123
	global_store_dwordx2 v196, v[124:125], s[44:45] offset:512
	v_mul_f32_e32 v108, 0xbfb8aa3b, v60
	v_exp_f32_e32 v109, v108
	s_nop 0
	v_add_f32_e32 v110, 1.0, v109
	v_div_scale_f32 v111, s[54:55], v110, v110, 1.0
	v_rcp_f32_e32 v112, v111
	v_div_scale_f32 v113, vcc, 1.0, v110, 1.0
	v_fma_f32 v115, -v111, v112, 1.0
	v_fmac_f32_e32 v112, v115, v112
	v_mul_f32_e32 v114, v113, v112
	v_fma_f32 v115, -v111, v114, v113
	v_fmac_f32_e32 v114, v115, v112
	v_fma_f32 v115, -v111, v114, v113
	v_div_fmas_f32 v115, v115, v112, v114
	v_div_fixup_f32 v115, v115, v110, 1.0
	v_mul_f32_e32 v120, v60, v115
	v_mul_f32_e32 v108, 0xbfb8aa3b, v61
	v_exp_f32_e32 v109, v108
	s_nop 0
	v_add_f32_e32 v110, 1.0, v109
	v_div_scale_f32 v111, s[54:55], v110, v110, 1.0
	v_rcp_f32_e32 v112, v111
	v_div_scale_f32 v113, vcc, 1.0, v110, 1.0
	v_fma_f32 v115, -v111, v112, 1.0
	v_fmac_f32_e32 v112, v115, v112
	v_mul_f32_e32 v114, v113, v112
	v_fma_f32 v115, -v111, v114, v113
	v_fmac_f32_e32 v114, v115, v112
	v_fma_f32 v115, -v111, v114, v113
	v_div_fmas_f32 v115, v115, v112, v114
	v_div_fixup_f32 v115, v115, v110, 1.0
	v_mul_f32_e32 v121, v61, v115
	v_mul_f32_e32 v108, 0xbfb8aa3b, v62
	v_exp_f32_e32 v109, v108
	s_nop 0
	v_add_f32_e32 v110, 1.0, v109
	v_div_scale_f32 v111, s[54:55], v110, v110, 1.0
	v_rcp_f32_e32 v112, v111
	v_div_scale_f32 v113, vcc, 1.0, v110, 1.0
	v_fma_f32 v115, -v111, v112, 1.0
	v_fmac_f32_e32 v112, v115, v112
	v_mul_f32_e32 v114, v113, v112
	v_fma_f32 v115, -v111, v114, v113
	v_fmac_f32_e32 v114, v115, v112
	v_fma_f32 v115, -v111, v114, v113
	v_div_fmas_f32 v115, v115, v112, v114
	v_div_fixup_f32 v115, v115, v110, 1.0
	v_mul_f32_e32 v122, v62, v115
	v_mul_f32_e32 v108, 0xbfb8aa3b, v63
	v_exp_f32_e32 v109, v108
	s_nop 0
	v_add_f32_e32 v110, 1.0, v109
	v_div_scale_f32 v111, s[54:55], v110, v110, 1.0
	v_rcp_f32_e32 v112, v111
	v_div_scale_f32 v113, vcc, 1.0, v110, 1.0
	v_fma_f32 v115, -v111, v112, 1.0
	v_fmac_f32_e32 v112, v115, v112
	v_mul_f32_e32 v114, v113, v112
	v_fma_f32 v115, -v111, v114, v113
	v_fmac_f32_e32 v114, v115, v112
	v_fma_f32 v115, -v111, v114, v113
	v_div_fmas_f32 v115, v115, v112, v114
	v_div_fixup_f32 v115, v115, v110, 1.0
	v_mul_f32_e32 v123, v63, v115
	v_cvt_pk_bf16_f32 v124, v120, v121
	v_cvt_pk_bf16_f32 v125, v122, v123
	global_store_dwordx2 v196, v[124:125], s[44:45] offset:1024
	v_add_f32_e32 v100, v64, v65
	v_add_f32_e32 v100, v100, v66
	v_add_f32_e32 v100, v100, v67
	v_add_f32_e32 v100, v100, v68
	v_add_f32_e32 v100, v100, v69
	v_add_f32_e32 v100, v100, v70
	v_add_f32_e32 v100, v100, v71
	v_add_f32_e32 v100, v100, v72
	v_add_f32_e32 v100, v100, v73
	v_add_f32_e32 v100, v100, v74
	v_add_f32_e32 v100, v100, v75
	s_nop 1
	v_add_f32_dpp v100, v100, v100 row_shr:1 row_mask:0xf bank_mask:0xf bound_ctrl:1
	s_nop 1
	v_add_f32_dpp v100, v100, v100 row_shr:2 row_mask:0xf bank_mask:0xf bound_ctrl:1
	s_nop 1
	v_add_f32_dpp v100, v100, v100 row_shr:4 row_mask:0xf bank_mask:0xf bound_ctrl:1
	s_nop 1
	v_add_f32_dpp v100, v100, v100 row_shr:8 row_mask:0xf bank_mask:0xf bound_ctrl:1
	s_nop 1
	v_add_f32_dpp v100, v100, v100 row_bcast:15 row_mask:0xa bank_mask:0xf
	s_nop 1
	v_add_f32_dpp v100, v100, v100 row_bcast:31 row_mask:0xc bank_mask:0xf
	s_nop 0
	v_readlane_b32 s53, v100, 63
	s_nop 1
	v_mov_b32_e32 v101, s53
	v_fmac_f32_e32 v64, 0xbaaaaaab, v101
	v_fmac_f32_e32 v65, 0xbaaaaaab, v101
	v_fmac_f32_e32 v66, 0xbaaaaaab, v101
	v_fmac_f32_e32 v67, 0xbaaaaaab, v101
	v_fmac_f32_e32 v68, 0xbaaaaaab, v101
	v_fmac_f32_e32 v69, 0xbaaaaaab, v101
	v_fmac_f32_e32 v70, 0xbaaaaaab, v101
	v_fmac_f32_e32 v71, 0xbaaaaaab, v101
	v_fmac_f32_e32 v72, 0xbaaaaaab, v101
	v_fmac_f32_e32 v73, 0xbaaaaaab, v101
	v_fmac_f32_e32 v74, 0xbaaaaaab, v101
	v_fmac_f32_e32 v75, 0xbaaaaaab, v101
	v_mul_f32_e32 v102, v64, v64
	v_fmac_f32_e32 v102, v65, v65
	v_fmac_f32_e32 v102, v66, v66
	v_fmac_f32_e32 v102, v67, v67
	v_fmac_f32_e32 v102, v68, v68
	v_fmac_f32_e32 v102, v69, v69
	v_fmac_f32_e32 v102, v70, v70
	v_fmac_f32_e32 v102, v71, v71
	v_fmac_f32_e32 v102, v72, v72
	v_fmac_f32_e32 v102, v73, v73
	v_fmac_f32_e32 v102, v74, v74
	v_fmac_f32_e32 v102, v75, v75
	s_nop 1
	v_add_f32_dpp v102, v102, v102 row_shr:1 row_mask:0xf bank_mask:0xf bound_ctrl:1
	s_nop 1
	v_add_f32_dpp v102, v102, v102 row_shr:2 row_mask:0xf bank_mask:0xf bound_ctrl:1
	s_nop 1
	v_add_f32_dpp v102, v102, v102 row_shr:4 row_mask:0xf bank_mask:0xf bound_ctrl:1
	s_nop 1
	v_add_f32_dpp v102, v102, v102 row_shr:8 row_mask:0xf bank_mask:0xf bound_ctrl:1
	s_nop 1
	v_add_f32_dpp v102, v102, v102 row_bcast:15 row_mask:0xa bank_mask:0xf
	s_nop 1
	v_add_f32_dpp v102, v102, v102 row_bcast:31 row_mask:0xc bank_mask:0xf
	s_nop 0
	v_readlane_b32 s53, v102, 63
	s_nop 1
	v_mov_b32_e32 v101, s53
	v_fmamk_f32 v101, v101, 0x3aaaaaab, v197
	v_rsq_f32_e32 v103, v101
	s_nop 0
	v_mul_f32_e32 v64, v64, v103
	v_mul_f32_e32 v65, v65, v103
	v_mul_f32_e32 v66, v66, v103
	v_mul_f32_e32 v67, v67, v103
	v_mul_f32_e32 v68, v68, v103
	v_mul_f32_e32 v69, v69, v103
	v_mul_f32_e32 v70, v70, v103
	v_mul_f32_e32 v71, v71, v103
	v_mul_f32_e32 v72, v72, v103
	v_mul_f32_e32 v73, v73, v103
	v_mul_f32_e32 v74, v74, v103
	v_mul_f32_e32 v75, v75, v103
	v_fma_f32 v64, v222, v64, v234
	v_fma_f32 v65, v223, v65, v235
	v_fma_f32 v66, v224, v66, v236
	v_fma_f32 v67, v225, v67, v237
	v_fma_f32 v68, v226, v68, v238
	v_fma_f32 v69, v227, v69, v239
	v_fma_f32 v70, v228, v70, v240
	v_fma_f32 v71, v229, v71, v241
	v_fma_f32 v72, v230, v72, v242
	v_fma_f32 v73, v231, v73, v243
	v_fma_f32 v74, v232, v74, v244
	v_fma_f32 v75, v233, v75, v245
	s_lshl_b32 s52, s41, 11
	s_add_i32 s52, s52, 10240
	v_add_u32_e32 v196, s52, v3
	v_mul_f32_e32 v108, 0xbfb8aa3b, v64
	v_exp_f32_e32 v109, v108
	s_nop 0
	v_add_f32_e32 v110, 1.0, v109
	v_div_scale_f32 v111, s[54:55], v110, v110, 1.0
	v_rcp_f32_e32 v112, v111
	v_div_scale_f32 v113, vcc, 1.0, v110, 1.0
	v_fma_f32 v115, -v111, v112, 1.0
	v_fmac_f32_e32 v112, v115, v112
	v_mul_f32_e32 v114, v113, v112
	v_fma_f32 v115, -v111, v114, v113
	v_fmac_f32_e32 v114, v115, v112
	v_fma_f32 v115, -v111, v114, v113
	v_div_fmas_f32 v115, v115, v112, v114
	v_div_fixup_f32 v115, v115, v110, 1.0
	v_mul_f32_e32 v120, v64, v115
	v_mul_f32_e32 v108, 0xbfb8aa3b, v65
	v_exp_f32_e32 v109, v108
	s_nop 0
	v_add_f32_e32 v110, 1.0, v109
	v_div_scale_f32 v111, s[54:55], v110, v110, 1.0
	v_rcp_f32_e32 v112, v111
	v_div_scale_f32 v113, vcc, 1.0, v110, 1.0
	v_fma_f32 v115, -v111, v112, 1.0
	v_fmac_f32_e32 v112, v115, v112
	v_mul_f32_e32 v114, v113, v112
	v_fma_f32 v115, -v111, v114, v113
	v_fmac_f32_e32 v114, v115, v112
	v_fma_f32 v115, -v111, v114, v113
	v_div_fmas_f32 v115, v115, v112, v114
	v_div_fixup_f32 v115, v115, v110, 1.0
	v_mul_f32_e32 v121, v65, v115
	v_mul_f32_e32 v108, 0xbfb8aa3b, v66
	v_exp_f32_e32 v109, v108
	s_nop 0
	v_add_f32_e32 v110, 1.0, v109
	v_div_scale_f32 v111, s[54:55], v110, v110, 1.0
	v_rcp_f32_e32 v112, v111
	v_div_scale_f32 v113, vcc, 1.0, v110, 1.0
	v_fma_f32 v115, -v111, v112, 1.0
	v_fmac_f32_e32 v112, v115, v112
	v_mul_f32_e32 v114, v113, v112
	v_fma_f32 v115, -v111, v114, v113
	v_fmac_f32_e32 v114, v115, v112
	v_fma_f32 v115, -v111, v114, v113
	v_div_fmas_f32 v115, v115, v112, v114
	v_div_fixup_f32 v115, v115, v110, 1.0
	v_mul_f32_e32 v122, v66, v115
	v_mul_f32_e32 v108, 0xbfb8aa3b, v67
	v_exp_f32_e32 v109, v108
	s_nop 0
	v_add_f32_e32 v110, 1.0, v109
	v_div_scale_f32 v111, s[54:55], v110, v110, 1.0
	v_rcp_f32_e32 v112, v111
	v_div_scale_f32 v113, vcc, 1.0, v110, 1.0
	v_fma_f32 v115, -v111, v112, 1.0
	v_fmac_f32_e32 v112, v115, v112
	v_mul_f32_e32 v114, v113, v112
	v_fma_f32 v115, -v111, v114, v113
	v_fmac_f32_e32 v114, v115, v112
	v_fma_f32 v115, -v111, v114, v113
	v_div_fmas_f32 v115, v115, v112, v114
	v_div_fixup_f32 v115, v115, v110, 1.0
	v_mul_f32_e32 v123, v67, v115
	v_cvt_pk_bf16_f32 v124, v120, v121
	v_cvt_pk_bf16_f32 v125, v122, v123
	global_store_dwordx2 v196, v[124:125], s[44:45]
	v_mul_f32_e32 v108, 0xbfb8aa3b, v68
	v_exp_f32_e32 v109, v108
	s_nop 0
	v_add_f32_e32 v110, 1.0, v109
	v_div_scale_f32 v111, s[54:55], v110, v110, 1.0
	v_rcp_f32_e32 v112, v111
	v_div_scale_f32 v113, vcc, 1.0, v110, 1.0
	v_fma_f32 v115, -v111, v112, 1.0
	v_fmac_f32_e32 v112, v115, v112
	v_mul_f32_e32 v114, v113, v112
	v_fma_f32 v115, -v111, v114, v113
	v_fmac_f32_e32 v114, v115, v112
	v_fma_f32 v115, -v111, v114, v113
	v_div_fmas_f32 v115, v115, v112, v114
	v_div_fixup_f32 v115, v115, v110, 1.0
	v_mul_f32_e32 v120, v68, v115
	v_mul_f32_e32 v108, 0xbfb8aa3b, v69
	v_exp_f32_e32 v109, v108
	s_nop 0
	v_add_f32_e32 v110, 1.0, v109
	v_div_scale_f32 v111, s[54:55], v110, v110, 1.0
	v_rcp_f32_e32 v112, v111
	v_div_scale_f32 v113, vcc, 1.0, v110, 1.0
	v_fma_f32 v115, -v111, v112, 1.0
	v_fmac_f32_e32 v112, v115, v112
	v_mul_f32_e32 v114, v113, v112
	v_fma_f32 v115, -v111, v114, v113
	v_fmac_f32_e32 v114, v115, v112
	v_fma_f32 v115, -v111, v114, v113
	v_div_fmas_f32 v115, v115, v112, v114
	v_div_fixup_f32 v115, v115, v110, 1.0
	v_mul_f32_e32 v121, v69, v115
	v_mul_f32_e32 v108, 0xbfb8aa3b, v70
	v_exp_f32_e32 v109, v108
	s_nop 0
	v_add_f32_e32 v110, 1.0, v109
	v_div_scale_f32 v111, s[54:55], v110, v110, 1.0
	v_rcp_f32_e32 v112, v111
	v_div_scale_f32 v113, vcc, 1.0, v110, 1.0
	v_fma_f32 v115, -v111, v112, 1.0
	v_fmac_f32_e32 v112, v115, v112
	v_mul_f32_e32 v114, v113, v112
	v_fma_f32 v115, -v111, v114, v113
	v_fmac_f32_e32 v114, v115, v112
	v_fma_f32 v115, -v111, v114, v113
	v_div_fmas_f32 v115, v115, v112, v114
	v_div_fixup_f32 v115, v115, v110, 1.0
	v_mul_f32_e32 v122, v70, v115
	v_mul_f32_e32 v108, 0xbfb8aa3b, v71
	v_exp_f32_e32 v109, v108
	s_nop 0
	v_add_f32_e32 v110, 1.0, v109
	v_div_scale_f32 v111, s[54:55], v110, v110, 1.0
	v_rcp_f32_e32 v112, v111
	v_div_scale_f32 v113, vcc, 1.0, v110, 1.0
	v_fma_f32 v115, -v111, v112, 1.0
	v_fmac_f32_e32 v112, v115, v112
	v_mul_f32_e32 v114, v113, v112
	v_fma_f32 v115, -v111, v114, v113
	v_fmac_f32_e32 v114, v115, v112
	v_fma_f32 v115, -v111, v114, v113
	v_div_fmas_f32 v115, v115, v112, v114
	v_div_fixup_f32 v115, v115, v110, 1.0
	v_mul_f32_e32 v123, v71, v115
	v_cvt_pk_bf16_f32 v124, v120, v121
	v_cvt_pk_bf16_f32 v125, v122, v123
	global_store_dwordx2 v196, v[124:125], s[44:45] offset:512
	v_mul_f32_e32 v108, 0xbfb8aa3b, v72
	v_exp_f32_e32 v109, v108
	s_nop 0
	v_add_f32_e32 v110, 1.0, v109
	v_div_scale_f32 v111, s[54:55], v110, v110, 1.0
	v_rcp_f32_e32 v112, v111
	v_div_scale_f32 v113, vcc, 1.0, v110, 1.0
	v_fma_f32 v115, -v111, v112, 1.0
	v_fmac_f32_e32 v112, v115, v112
	v_mul_f32_e32 v114, v113, v112
	v_fma_f32 v115, -v111, v114, v113
	v_fmac_f32_e32 v114, v115, v112
	v_fma_f32 v115, -v111, v114, v113
	v_div_fmas_f32 v115, v115, v112, v114
	v_div_fixup_f32 v115, v115, v110, 1.0
	v_mul_f32_e32 v120, v72, v115
	v_mul_f32_e32 v108, 0xbfb8aa3b, v73
	v_exp_f32_e32 v109, v108
	s_nop 0
	v_add_f32_e32 v110, 1.0, v109
	v_div_scale_f32 v111, s[54:55], v110, v110, 1.0
	v_rcp_f32_e32 v112, v111
	v_div_scale_f32 v113, vcc, 1.0, v110, 1.0
	v_fma_f32 v115, -v111, v112, 1.0
	v_fmac_f32_e32 v112, v115, v112
	v_mul_f32_e32 v114, v113, v112
	v_fma_f32 v115, -v111, v114, v113
	v_fmac_f32_e32 v114, v115, v112
	v_fma_f32 v115, -v111, v114, v113
	v_div_fmas_f32 v115, v115, v112, v114
	v_div_fixup_f32 v115, v115, v110, 1.0
	v_mul_f32_e32 v121, v73, v115
	v_mul_f32_e32 v108, 0xbfb8aa3b, v74
	v_exp_f32_e32 v109, v108
	s_nop 0
	v_add_f32_e32 v110, 1.0, v109
	v_div_scale_f32 v111, s[54:55], v110, v110, 1.0
	v_rcp_f32_e32 v112, v111
	v_div_scale_f32 v113, vcc, 1.0, v110, 1.0
	v_fma_f32 v115, -v111, v112, 1.0
	v_fmac_f32_e32 v112, v115, v112
	v_mul_f32_e32 v114, v113, v112
	v_fma_f32 v115, -v111, v114, v113
	v_fmac_f32_e32 v114, v115, v112
	v_fma_f32 v115, -v111, v114, v113
	v_div_fmas_f32 v115, v115, v112, v114
	v_div_fixup_f32 v115, v115, v110, 1.0
	v_mul_f32_e32 v122, v74, v115
	v_mul_f32_e32 v108, 0xbfb8aa3b, v75
	v_exp_f32_e32 v109, v108
	s_nop 0
	v_add_f32_e32 v110, 1.0, v109
	v_div_scale_f32 v111, s[54:55], v110, v110, 1.0
	v_rcp_f32_e32 v112, v111
	v_div_scale_f32 v113, vcc, 1.0, v110, 1.0
	v_fma_f32 v115, -v111, v112, 1.0
	v_fmac_f32_e32 v112, v115, v112
	v_mul_f32_e32 v114, v113, v112
	v_fma_f32 v115, -v111, v114, v113
	v_fmac_f32_e32 v114, v115, v112
	v_fma_f32 v115, -v111, v114, v113
	v_div_fmas_f32 v115, v115, v112, v114
	v_div_fixup_f32 v115, v115, v110, 1.0
	v_mul_f32_e32 v123, v75, v115
	v_cvt_pk_bf16_f32 v124, v120, v121
	v_cvt_pk_bf16_f32 v125, v122, v123
	global_store_dwordx2 v196, v[124:125], s[44:45] offset:1024
	v_add_f32_e32 v100, v76, v77
	v_add_f32_e32 v100, v100, v78
	v_add_f32_e32 v100, v100, v79
	v_add_f32_e32 v100, v100, v80
	v_add_f32_e32 v100, v100, v81
	v_add_f32_e32 v100, v100, v82
	v_add_f32_e32 v100, v100, v83
	v_add_f32_e32 v100, v100, v84
	v_add_f32_e32 v100, v100, v85
	v_add_f32_e32 v100, v100, v86
	v_add_f32_e32 v100, v100, v87
	s_nop 1
	v_add_f32_dpp v100, v100, v100 row_shr:1 row_mask:0xf bank_mask:0xf bound_ctrl:1
	s_nop 1
	v_add_f32_dpp v100, v100, v100 row_shr:2 row_mask:0xf bank_mask:0xf bound_ctrl:1
	s_nop 1
	v_add_f32_dpp v100, v100, v100 row_shr:4 row_mask:0xf bank_mask:0xf bound_ctrl:1
	s_nop 1
	v_add_f32_dpp v100, v100, v100 row_shr:8 row_mask:0xf bank_mask:0xf bound_ctrl:1
	s_nop 1
	v_add_f32_dpp v100, v100, v100 row_bcast:15 row_mask:0xa bank_mask:0xf
	s_nop 1
	v_add_f32_dpp v100, v100, v100 row_bcast:31 row_mask:0xc bank_mask:0xf
	s_nop 0
	v_readlane_b32 s53, v100, 63
	s_nop 1
	v_mov_b32_e32 v101, s53
	v_fmac_f32_e32 v76, 0xbaaaaaab, v101
	v_fmac_f32_e32 v77, 0xbaaaaaab, v101
	v_fmac_f32_e32 v78, 0xbaaaaaab, v101
	v_fmac_f32_e32 v79, 0xbaaaaaab, v101
	v_fmac_f32_e32 v80, 0xbaaaaaab, v101
	v_fmac_f32_e32 v81, 0xbaaaaaab, v101
	v_fmac_f32_e32 v82, 0xbaaaaaab, v101
	v_fmac_f32_e32 v83, 0xbaaaaaab, v101
	v_fmac_f32_e32 v84, 0xbaaaaaab, v101
	v_fmac_f32_e32 v85, 0xbaaaaaab, v101
	v_fmac_f32_e32 v86, 0xbaaaaaab, v101
	v_fmac_f32_e32 v87, 0xbaaaaaab, v101
	v_mul_f32_e32 v102, v76, v76
	v_fmac_f32_e32 v102, v77, v77
	v_fmac_f32_e32 v102, v78, v78
	v_fmac_f32_e32 v102, v79, v79
	v_fmac_f32_e32 v102, v80, v80
	v_fmac_f32_e32 v102, v81, v81
	v_fmac_f32_e32 v102, v82, v82
	v_fmac_f32_e32 v102, v83, v83
	v_fmac_f32_e32 v102, v84, v84
	v_fmac_f32_e32 v102, v85, v85
	v_fmac_f32_e32 v102, v86, v86
	v_fmac_f32_e32 v102, v87, v87
	s_nop 1
	v_add_f32_dpp v102, v102, v102 row_shr:1 row_mask:0xf bank_mask:0xf bound_ctrl:1
	s_nop 1
	v_add_f32_dpp v102, v102, v102 row_shr:2 row_mask:0xf bank_mask:0xf bound_ctrl:1
	s_nop 1
	v_add_f32_dpp v102, v102, v102 row_shr:4 row_mask:0xf bank_mask:0xf bound_ctrl:1
	s_nop 1
	v_add_f32_dpp v102, v102, v102 row_shr:8 row_mask:0xf bank_mask:0xf bound_ctrl:1
	s_nop 1
	v_add_f32_dpp v102, v102, v102 row_bcast:15 row_mask:0xa bank_mask:0xf
	s_nop 1
	v_add_f32_dpp v102, v102, v102 row_bcast:31 row_mask:0xc bank_mask:0xf
	s_nop 0
	v_readlane_b32 s53, v102, 63
	s_nop 1
	v_mov_b32_e32 v101, s53
	v_fmamk_f32 v101, v101, 0x3aaaaaab, v197
	v_rsq_f32_e32 v103, v101
	s_nop 0
	v_mul_f32_e32 v76, v76, v103
	v_mul_f32_e32 v77, v77, v103
	v_mul_f32_e32 v78, v78, v103
	v_mul_f32_e32 v79, v79, v103
	v_mul_f32_e32 v80, v80, v103
	v_mul_f32_e32 v81, v81, v103
	v_mul_f32_e32 v82, v82, v103
	v_mul_f32_e32 v83, v83, v103
	v_mul_f32_e32 v84, v84, v103
	v_mul_f32_e32 v85, v85, v103
	v_mul_f32_e32 v86, v86, v103
	v_mul_f32_e32 v87, v87, v103
	v_fma_f32 v76, v222, v76, v234
	v_fma_f32 v77, v223, v77, v235
	v_fma_f32 v78, v224, v78, v236
	v_fma_f32 v79, v225, v79, v237
	v_fma_f32 v80, v226, v80, v238
	v_fma_f32 v81, v227, v81, v239
	v_fma_f32 v82, v228, v82, v240
	v_fma_f32 v83, v229, v83, v241
	v_fma_f32 v84, v230, v84, v242
	v_fma_f32 v85, v231, v85, v243
	v_fma_f32 v86, v232, v86, v244
	v_fma_f32 v87, v233, v87, v245
	s_lshl_b32 s52, s41, 11
	s_add_i32 s52, s52, 12288
	v_add_u32_e32 v196, s52, v3
	v_mul_f32_e32 v108, 0xbfb8aa3b, v76
	v_exp_f32_e32 v109, v108
	s_nop 0
	v_add_f32_e32 v110, 1.0, v109
	v_div_scale_f32 v111, s[54:55], v110, v110, 1.0
	v_rcp_f32_e32 v112, v111
	v_div_scale_f32 v113, vcc, 1.0, v110, 1.0
	v_fma_f32 v115, -v111, v112, 1.0
	v_fmac_f32_e32 v112, v115, v112
	v_mul_f32_e32 v114, v113, v112
	v_fma_f32 v115, -v111, v114, v113
	v_fmac_f32_e32 v114, v115, v112
	v_fma_f32 v115, -v111, v114, v113
	v_div_fmas_f32 v115, v115, v112, v114
	v_div_fixup_f32 v115, v115, v110, 1.0
	v_mul_f32_e32 v120, v76, v115
	v_mul_f32_e32 v108, 0xbfb8aa3b, v77
	v_exp_f32_e32 v109, v108
	s_nop 0
	v_add_f32_e32 v110, 1.0, v109
	v_div_scale_f32 v111, s[54:55], v110, v110, 1.0
	v_rcp_f32_e32 v112, v111
	v_div_scale_f32 v113, vcc, 1.0, v110, 1.0
	v_fma_f32 v115, -v111, v112, 1.0
	v_fmac_f32_e32 v112, v115, v112
	v_mul_f32_e32 v114, v113, v112
	v_fma_f32 v115, -v111, v114, v113
	v_fmac_f32_e32 v114, v115, v112
	v_fma_f32 v115, -v111, v114, v113
	v_div_fmas_f32 v115, v115, v112, v114
	v_div_fixup_f32 v115, v115, v110, 1.0
	v_mul_f32_e32 v121, v77, v115
	v_mul_f32_e32 v108, 0xbfb8aa3b, v78
	v_exp_f32_e32 v109, v108
	s_nop 0
	v_add_f32_e32 v110, 1.0, v109
	v_div_scale_f32 v111, s[54:55], v110, v110, 1.0
	v_rcp_f32_e32 v112, v111
	v_div_scale_f32 v113, vcc, 1.0, v110, 1.0
	v_fma_f32 v115, -v111, v112, 1.0
	v_fmac_f32_e32 v112, v115, v112
	v_mul_f32_e32 v114, v113, v112
	v_fma_f32 v115, -v111, v114, v113
	v_fmac_f32_e32 v114, v115, v112
	v_fma_f32 v115, -v111, v114, v113
	v_div_fmas_f32 v115, v115, v112, v114
	v_div_fixup_f32 v115, v115, v110, 1.0
	v_mul_f32_e32 v122, v78, v115
	v_mul_f32_e32 v108, 0xbfb8aa3b, v79
	v_exp_f32_e32 v109, v108
	s_nop 0
	v_add_f32_e32 v110, 1.0, v109
	v_div_scale_f32 v111, s[54:55], v110, v110, 1.0
	v_rcp_f32_e32 v112, v111
	v_div_scale_f32 v113, vcc, 1.0, v110, 1.0
	v_fma_f32 v115, -v111, v112, 1.0
	v_fmac_f32_e32 v112, v115, v112
	v_mul_f32_e32 v114, v113, v112
	v_fma_f32 v115, -v111, v114, v113
	v_fmac_f32_e32 v114, v115, v112
	v_fma_f32 v115, -v111, v114, v113
	v_div_fmas_f32 v115, v115, v112, v114
	v_div_fixup_f32 v115, v115, v110, 1.0
	v_mul_f32_e32 v123, v79, v115
	v_cvt_pk_bf16_f32 v124, v120, v121
	v_cvt_pk_bf16_f32 v125, v122, v123
	global_store_dwordx2 v196, v[124:125], s[44:45]
	v_mul_f32_e32 v108, 0xbfb8aa3b, v80
	v_exp_f32_e32 v109, v108
	s_nop 0
	v_add_f32_e32 v110, 1.0, v109
	v_div_scale_f32 v111, s[54:55], v110, v110, 1.0
	v_rcp_f32_e32 v112, v111
	v_div_scale_f32 v113, vcc, 1.0, v110, 1.0
	v_fma_f32 v115, -v111, v112, 1.0
	v_fmac_f32_e32 v112, v115, v112
	v_mul_f32_e32 v114, v113, v112
	v_fma_f32 v115, -v111, v114, v113
	v_fmac_f32_e32 v114, v115, v112
	v_fma_f32 v115, -v111, v114, v113
	v_div_fmas_f32 v115, v115, v112, v114
	v_div_fixup_f32 v115, v115, v110, 1.0
	v_mul_f32_e32 v120, v80, v115
	v_mul_f32_e32 v108, 0xbfb8aa3b, v81
	v_exp_f32_e32 v109, v108
	s_nop 0
	v_add_f32_e32 v110, 1.0, v109
	v_div_scale_f32 v111, s[54:55], v110, v110, 1.0
	v_rcp_f32_e32 v112, v111
	v_div_scale_f32 v113, vcc, 1.0, v110, 1.0
	v_fma_f32 v115, -v111, v112, 1.0
	v_fmac_f32_e32 v112, v115, v112
	v_mul_f32_e32 v114, v113, v112
	v_fma_f32 v115, -v111, v114, v113
	v_fmac_f32_e32 v114, v115, v112
	v_fma_f32 v115, -v111, v114, v113
	v_div_fmas_f32 v115, v115, v112, v114
	v_div_fixup_f32 v115, v115, v110, 1.0
	v_mul_f32_e32 v121, v81, v115
	v_mul_f32_e32 v108, 0xbfb8aa3b, v82
	v_exp_f32_e32 v109, v108
	s_nop 0
	v_add_f32_e32 v110, 1.0, v109
	v_div_scale_f32 v111, s[54:55], v110, v110, 1.0
	v_rcp_f32_e32 v112, v111
	v_div_scale_f32 v113, vcc, 1.0, v110, 1.0
	v_fma_f32 v115, -v111, v112, 1.0
	v_fmac_f32_e32 v112, v115, v112
	v_mul_f32_e32 v114, v113, v112
	v_fma_f32 v115, -v111, v114, v113
	v_fmac_f32_e32 v114, v115, v112
	v_fma_f32 v115, -v111, v114, v113
	v_div_fmas_f32 v115, v115, v112, v114
	v_div_fixup_f32 v115, v115, v110, 1.0
	v_mul_f32_e32 v122, v82, v115
	v_mul_f32_e32 v108, 0xbfb8aa3b, v83
	v_exp_f32_e32 v109, v108
	s_nop 0
	v_add_f32_e32 v110, 1.0, v109
	v_div_scale_f32 v111, s[54:55], v110, v110, 1.0
	v_rcp_f32_e32 v112, v111
	v_div_scale_f32 v113, vcc, 1.0, v110, 1.0
	v_fma_f32 v115, -v111, v112, 1.0
	v_fmac_f32_e32 v112, v115, v112
	v_mul_f32_e32 v114, v113, v112
	v_fma_f32 v115, -v111, v114, v113
	v_fmac_f32_e32 v114, v115, v112
	v_fma_f32 v115, -v111, v114, v113
	v_div_fmas_f32 v115, v115, v112, v114
	v_div_fixup_f32 v115, v115, v110, 1.0
	v_mul_f32_e32 v123, v83, v115
	v_cvt_pk_bf16_f32 v124, v120, v121
	v_cvt_pk_bf16_f32 v125, v122, v123
	global_store_dwordx2 v196, v[124:125], s[44:45] offset:512
	v_mul_f32_e32 v108, 0xbfb8aa3b, v84
	v_exp_f32_e32 v109, v108
	s_nop 0
	v_add_f32_e32 v110, 1.0, v109
	v_div_scale_f32 v111, s[54:55], v110, v110, 1.0
	v_rcp_f32_e32 v112, v111
	v_div_scale_f32 v113, vcc, 1.0, v110, 1.0
	v_fma_f32 v115, -v111, v112, 1.0
	v_fmac_f32_e32 v112, v115, v112
	v_mul_f32_e32 v114, v113, v112
	v_fma_f32 v115, -v111, v114, v113
	v_fmac_f32_e32 v114, v115, v112
	v_fma_f32 v115, -v111, v114, v113
	v_div_fmas_f32 v115, v115, v112, v114
	v_div_fixup_f32 v115, v115, v110, 1.0
	v_mul_f32_e32 v120, v84, v115
	v_mul_f32_e32 v108, 0xbfb8aa3b, v85
	v_exp_f32_e32 v109, v108
	s_nop 0
	v_add_f32_e32 v110, 1.0, v109
	v_div_scale_f32 v111, s[54:55], v110, v110, 1.0
	v_rcp_f32_e32 v112, v111
	v_div_scale_f32 v113, vcc, 1.0, v110, 1.0
	v_fma_f32 v115, -v111, v112, 1.0
	v_fmac_f32_e32 v112, v115, v112
	v_mul_f32_e32 v114, v113, v112
	v_fma_f32 v115, -v111, v114, v113
	v_fmac_f32_e32 v114, v115, v112
	v_fma_f32 v115, -v111, v114, v113
	v_div_fmas_f32 v115, v115, v112, v114
	v_div_fixup_f32 v115, v115, v110, 1.0
	v_mul_f32_e32 v121, v85, v115
	v_mul_f32_e32 v108, 0xbfb8aa3b, v86
	v_exp_f32_e32 v109, v108
	s_nop 0
	v_add_f32_e32 v110, 1.0, v109
	v_div_scale_f32 v111, s[54:55], v110, v110, 1.0
	v_rcp_f32_e32 v112, v111
	v_div_scale_f32 v113, vcc, 1.0, v110, 1.0
	v_fma_f32 v115, -v111, v112, 1.0
	v_fmac_f32_e32 v112, v115, v112
	v_mul_f32_e32 v114, v113, v112
	v_fma_f32 v115, -v111, v114, v113
	v_fmac_f32_e32 v114, v115, v112
	v_fma_f32 v115, -v111, v114, v113
	v_div_fmas_f32 v115, v115, v112, v114
	v_div_fixup_f32 v115, v115, v110, 1.0
	v_mul_f32_e32 v122, v86, v115
	v_mul_f32_e32 v108, 0xbfb8aa3b, v87
	v_exp_f32_e32 v109, v108
	s_nop 0
	v_add_f32_e32 v110, 1.0, v109
	v_div_scale_f32 v111, s[54:55], v110, v110, 1.0
	v_rcp_f32_e32 v112, v111
	v_div_scale_f32 v113, vcc, 1.0, v110, 1.0
	v_fma_f32 v115, -v111, v112, 1.0
	v_fmac_f32_e32 v112, v115, v112
	v_mul_f32_e32 v114, v113, v112
	v_fma_f32 v115, -v111, v114, v113
	v_fmac_f32_e32 v114, v115, v112
	v_fma_f32 v115, -v111, v114, v113
	v_div_fmas_f32 v115, v115, v112, v114
	v_div_fixup_f32 v115, v115, v110, 1.0
	v_mul_f32_e32 v123, v87, v115
	v_cvt_pk_bf16_f32 v124, v120, v121
	v_cvt_pk_bf16_f32 v125, v122, v123
	global_store_dwordx2 v196, v[124:125], s[44:45] offset:1024
	v_add_f32_e32 v100, v88, v89
	v_add_f32_e32 v100, v100, v90
	v_add_f32_e32 v100, v100, v91
	v_add_f32_e32 v100, v100, v92
	v_add_f32_e32 v100, v100, v93
	v_add_f32_e32 v100, v100, v94
	v_add_f32_e32 v100, v100, v95
	v_add_f32_e32 v100, v100, v96
	v_add_f32_e32 v100, v100, v97
	v_add_f32_e32 v100, v100, v98
	v_add_f32_e32 v100, v100, v99
	s_nop 1
	v_add_f32_dpp v100, v100, v100 row_shr:1 row_mask:0xf bank_mask:0xf bound_ctrl:1
	s_nop 1
	v_add_f32_dpp v100, v100, v100 row_shr:2 row_mask:0xf bank_mask:0xf bound_ctrl:1
	s_nop 1
	v_add_f32_dpp v100, v100, v100 row_shr:4 row_mask:0xf bank_mask:0xf bound_ctrl:1
	s_nop 1
	v_add_f32_dpp v100, v100, v100 row_shr:8 row_mask:0xf bank_mask:0xf bound_ctrl:1
	s_nop 1
	v_add_f32_dpp v100, v100, v100 row_bcast:15 row_mask:0xa bank_mask:0xf
	s_nop 1
	v_add_f32_dpp v100, v100, v100 row_bcast:31 row_mask:0xc bank_mask:0xf
	s_nop 0
	v_readlane_b32 s53, v100, 63
	s_nop 1
	v_mov_b32_e32 v101, s53
	v_fmac_f32_e32 v88, 0xbaaaaaab, v101
	v_fmac_f32_e32 v89, 0xbaaaaaab, v101
	v_fmac_f32_e32 v90, 0xbaaaaaab, v101
	v_fmac_f32_e32 v91, 0xbaaaaaab, v101
	v_fmac_f32_e32 v92, 0xbaaaaaab, v101
	v_fmac_f32_e32 v93, 0xbaaaaaab, v101
	v_fmac_f32_e32 v94, 0xbaaaaaab, v101
	v_fmac_f32_e32 v95, 0xbaaaaaab, v101
	v_fmac_f32_e32 v96, 0xbaaaaaab, v101
	v_fmac_f32_e32 v97, 0xbaaaaaab, v101
	v_fmac_f32_e32 v98, 0xbaaaaaab, v101
	v_fmac_f32_e32 v99, 0xbaaaaaab, v101
	v_mul_f32_e32 v102, v88, v88
	v_fmac_f32_e32 v102, v89, v89
	v_fmac_f32_e32 v102, v90, v90
	v_fmac_f32_e32 v102, v91, v91
	v_fmac_f32_e32 v102, v92, v92
	v_fmac_f32_e32 v102, v93, v93
	v_fmac_f32_e32 v102, v94, v94
	v_fmac_f32_e32 v102, v95, v95
	v_fmac_f32_e32 v102, v96, v96
	v_fmac_f32_e32 v102, v97, v97
	v_fmac_f32_e32 v102, v98, v98
	v_fmac_f32_e32 v102, v99, v99
	s_nop 1
	v_add_f32_dpp v102, v102, v102 row_shr:1 row_mask:0xf bank_mask:0xf bound_ctrl:1
	s_nop 1
	v_add_f32_dpp v102, v102, v102 row_shr:2 row_mask:0xf bank_mask:0xf bound_ctrl:1
	s_nop 1
	v_add_f32_dpp v102, v102, v102 row_shr:4 row_mask:0xf bank_mask:0xf bound_ctrl:1
	s_nop 1
	v_add_f32_dpp v102, v102, v102 row_shr:8 row_mask:0xf bank_mask:0xf bound_ctrl:1
	s_nop 1
	v_add_f32_dpp v102, v102, v102 row_bcast:15 row_mask:0xa bank_mask:0xf
	s_nop 1
	v_add_f32_dpp v102, v102, v102 row_bcast:31 row_mask:0xc bank_mask:0xf
	s_nop 0
	v_readlane_b32 s53, v102, 63
	s_nop 1
	v_mov_b32_e32 v101, s53
	v_fmamk_f32 v101, v101, 0x3aaaaaab, v197
	v_rsq_f32_e32 v103, v101
	s_nop 0
	v_mul_f32_e32 v88, v88, v103
	v_mul_f32_e32 v89, v89, v103
	v_mul_f32_e32 v90, v90, v103
	v_mul_f32_e32 v91, v91, v103
	v_mul_f32_e32 v92, v92, v103
	v_mul_f32_e32 v93, v93, v103
	v_mul_f32_e32 v94, v94, v103
	v_mul_f32_e32 v95, v95, v103
	v_mul_f32_e32 v96, v96, v103
	v_mul_f32_e32 v97, v97, v103
	v_mul_f32_e32 v98, v98, v103
	v_mul_f32_e32 v99, v99, v103
	v_fma_f32 v88, v222, v88, v234
	v_fma_f32 v89, v223, v89, v235
	v_fma_f32 v90, v224, v90, v236
	v_fma_f32 v91, v225, v91, v237
	v_fma_f32 v92, v226, v92, v238
	v_fma_f32 v93, v227, v93, v239
	v_fma_f32 v94, v228, v94, v240
	v_fma_f32 v95, v229, v95, v241
	v_fma_f32 v96, v230, v96, v242
	v_fma_f32 v97, v231, v97, v243
	v_fma_f32 v98, v232, v98, v244
	v_fma_f32 v99, v233, v99, v245
	s_lshl_b32 s52, s41, 11
	s_add_i32 s52, s52, 14336
	v_add_u32_e32 v196, s52, v3
	v_mul_f32_e32 v108, 0xbfb8aa3b, v88
	v_exp_f32_e32 v109, v108
	s_nop 0
	v_add_f32_e32 v110, 1.0, v109
	v_div_scale_f32 v111, s[54:55], v110, v110, 1.0
	v_rcp_f32_e32 v112, v111
	v_div_scale_f32 v113, vcc, 1.0, v110, 1.0
	v_fma_f32 v115, -v111, v112, 1.0
	v_fmac_f32_e32 v112, v115, v112
	v_mul_f32_e32 v114, v113, v112
	v_fma_f32 v115, -v111, v114, v113
	v_fmac_f32_e32 v114, v115, v112
	v_fma_f32 v115, -v111, v114, v113
	v_div_fmas_f32 v115, v115, v112, v114
	v_div_fixup_f32 v115, v115, v110, 1.0
	v_mul_f32_e32 v120, v88, v115
	v_mul_f32_e32 v108, 0xbfb8aa3b, v89
	v_exp_f32_e32 v109, v108
	s_nop 0
	v_add_f32_e32 v110, 1.0, v109
	v_div_scale_f32 v111, s[54:55], v110, v110, 1.0
	v_rcp_f32_e32 v112, v111
	v_div_scale_f32 v113, vcc, 1.0, v110, 1.0
	v_fma_f32 v115, -v111, v112, 1.0
	v_fmac_f32_e32 v112, v115, v112
	v_mul_f32_e32 v114, v113, v112
	v_fma_f32 v115, -v111, v114, v113
	v_fmac_f32_e32 v114, v115, v112
	v_fma_f32 v115, -v111, v114, v113
	v_div_fmas_f32 v115, v115, v112, v114
	v_div_fixup_f32 v115, v115, v110, 1.0
	v_mul_f32_e32 v121, v89, v115
	v_mul_f32_e32 v108, 0xbfb8aa3b, v90
	v_exp_f32_e32 v109, v108
	s_nop 0
	v_add_f32_e32 v110, 1.0, v109
	v_div_scale_f32 v111, s[54:55], v110, v110, 1.0
	v_rcp_f32_e32 v112, v111
	v_div_scale_f32 v113, vcc, 1.0, v110, 1.0
	v_fma_f32 v115, -v111, v112, 1.0
	v_fmac_f32_e32 v112, v115, v112
	v_mul_f32_e32 v114, v113, v112
	v_fma_f32 v115, -v111, v114, v113
	v_fmac_f32_e32 v114, v115, v112
	v_fma_f32 v115, -v111, v114, v113
	v_div_fmas_f32 v115, v115, v112, v114
	v_div_fixup_f32 v115, v115, v110, 1.0
	v_mul_f32_e32 v122, v90, v115
	v_mul_f32_e32 v108, 0xbfb8aa3b, v91
	v_exp_f32_e32 v109, v108
	s_nop 0
	v_add_f32_e32 v110, 1.0, v109
	v_div_scale_f32 v111, s[54:55], v110, v110, 1.0
	v_rcp_f32_e32 v112, v111
	v_div_scale_f32 v113, vcc, 1.0, v110, 1.0
	v_fma_f32 v115, -v111, v112, 1.0
	v_fmac_f32_e32 v112, v115, v112
	v_mul_f32_e32 v114, v113, v112
	v_fma_f32 v115, -v111, v114, v113
	v_fmac_f32_e32 v114, v115, v112
	v_fma_f32 v115, -v111, v114, v113
	v_div_fmas_f32 v115, v115, v112, v114
	v_div_fixup_f32 v115, v115, v110, 1.0
	v_mul_f32_e32 v123, v91, v115
	v_cvt_pk_bf16_f32 v124, v120, v121
	v_cvt_pk_bf16_f32 v125, v122, v123
	global_store_dwordx2 v196, v[124:125], s[44:45]
	v_mul_f32_e32 v108, 0xbfb8aa3b, v92
	v_exp_f32_e32 v109, v108
	s_nop 0
	v_add_f32_e32 v110, 1.0, v109
	v_div_scale_f32 v111, s[54:55], v110, v110, 1.0
	v_rcp_f32_e32 v112, v111
	v_div_scale_f32 v113, vcc, 1.0, v110, 1.0
	v_fma_f32 v115, -v111, v112, 1.0
	v_fmac_f32_e32 v112, v115, v112
	v_mul_f32_e32 v114, v113, v112
	v_fma_f32 v115, -v111, v114, v113
	v_fmac_f32_e32 v114, v115, v112
	v_fma_f32 v115, -v111, v114, v113
	v_div_fmas_f32 v115, v115, v112, v114
	v_div_fixup_f32 v115, v115, v110, 1.0
	v_mul_f32_e32 v120, v92, v115
	v_mul_f32_e32 v108, 0xbfb8aa3b, v93
	v_exp_f32_e32 v109, v108
	s_nop 0
	v_add_f32_e32 v110, 1.0, v109
	v_div_scale_f32 v111, s[54:55], v110, v110, 1.0
	v_rcp_f32_e32 v112, v111
	v_div_scale_f32 v113, vcc, 1.0, v110, 1.0
	v_fma_f32 v115, -v111, v112, 1.0
	v_fmac_f32_e32 v112, v115, v112
	v_mul_f32_e32 v114, v113, v112
	v_fma_f32 v115, -v111, v114, v113
	v_fmac_f32_e32 v114, v115, v112
	v_fma_f32 v115, -v111, v114, v113
	v_div_fmas_f32 v115, v115, v112, v114
	v_div_fixup_f32 v115, v115, v110, 1.0
	v_mul_f32_e32 v121, v93, v115
	v_mul_f32_e32 v108, 0xbfb8aa3b, v94
	v_exp_f32_e32 v109, v108
	s_nop 0
	v_add_f32_e32 v110, 1.0, v109
	v_div_scale_f32 v111, s[54:55], v110, v110, 1.0
	v_rcp_f32_e32 v112, v111
	v_div_scale_f32 v113, vcc, 1.0, v110, 1.0
	v_fma_f32 v115, -v111, v112, 1.0
	v_fmac_f32_e32 v112, v115, v112
	v_mul_f32_e32 v114, v113, v112
	v_fma_f32 v115, -v111, v114, v113
	v_fmac_f32_e32 v114, v115, v112
	v_fma_f32 v115, -v111, v114, v113
	v_div_fmas_f32 v115, v115, v112, v114
	v_div_fixup_f32 v115, v115, v110, 1.0
	v_mul_f32_e32 v122, v94, v115
	v_mul_f32_e32 v108, 0xbfb8aa3b, v95
	v_exp_f32_e32 v109, v108
	s_nop 0
	v_add_f32_e32 v110, 1.0, v109
	v_div_scale_f32 v111, s[54:55], v110, v110, 1.0
	v_rcp_f32_e32 v112, v111
	v_div_scale_f32 v113, vcc, 1.0, v110, 1.0
	v_fma_f32 v115, -v111, v112, 1.0
	v_fmac_f32_e32 v112, v115, v112
	v_mul_f32_e32 v114, v113, v112
	v_fma_f32 v115, -v111, v114, v113
	v_fmac_f32_e32 v114, v115, v112
	v_fma_f32 v115, -v111, v114, v113
	v_div_fmas_f32 v115, v115, v112, v114
	v_div_fixup_f32 v115, v115, v110, 1.0
	v_mul_f32_e32 v123, v95, v115
	v_cvt_pk_bf16_f32 v124, v120, v121
	v_cvt_pk_bf16_f32 v125, v122, v123
	global_store_dwordx2 v196, v[124:125], s[44:45] offset:512
	v_mul_f32_e32 v108, 0xbfb8aa3b, v96
	v_exp_f32_e32 v109, v108
	s_nop 0
	v_add_f32_e32 v110, 1.0, v109
	v_div_scale_f32 v111, s[54:55], v110, v110, 1.0
	v_rcp_f32_e32 v112, v111
	v_div_scale_f32 v113, vcc, 1.0, v110, 1.0
	v_fma_f32 v115, -v111, v112, 1.0
	v_fmac_f32_e32 v112, v115, v112
	v_mul_f32_e32 v114, v113, v112
	v_fma_f32 v115, -v111, v114, v113
	v_fmac_f32_e32 v114, v115, v112
	v_fma_f32 v115, -v111, v114, v113
	v_div_fmas_f32 v115, v115, v112, v114
	v_div_fixup_f32 v115, v115, v110, 1.0
	v_mul_f32_e32 v120, v96, v115
	v_mul_f32_e32 v108, 0xbfb8aa3b, v97
	v_exp_f32_e32 v109, v108
	s_nop 0
	v_add_f32_e32 v110, 1.0, v109
	v_div_scale_f32 v111, s[54:55], v110, v110, 1.0
	v_rcp_f32_e32 v112, v111
	v_div_scale_f32 v113, vcc, 1.0, v110, 1.0
	v_fma_f32 v115, -v111, v112, 1.0
	v_fmac_f32_e32 v112, v115, v112
	v_mul_f32_e32 v114, v113, v112
	v_fma_f32 v115, -v111, v114, v113
	v_fmac_f32_e32 v114, v115, v112
	v_fma_f32 v115, -v111, v114, v113
	v_div_fmas_f32 v115, v115, v112, v114
	v_div_fixup_f32 v115, v115, v110, 1.0
	v_mul_f32_e32 v121, v97, v115
	v_mul_f32_e32 v108, 0xbfb8aa3b, v98
	v_exp_f32_e32 v109, v108
	s_nop 0
	v_add_f32_e32 v110, 1.0, v109
	v_div_scale_f32 v111, s[54:55], v110, v110, 1.0
	v_rcp_f32_e32 v112, v111
	v_div_scale_f32 v113, vcc, 1.0, v110, 1.0
	v_fma_f32 v115, -v111, v112, 1.0
	v_fmac_f32_e32 v112, v115, v112
	v_mul_f32_e32 v114, v113, v112
	v_fma_f32 v115, -v111, v114, v113
	v_fmac_f32_e32 v114, v115, v112
	v_fma_f32 v115, -v111, v114, v113
	v_div_fmas_f32 v115, v115, v112, v114
	v_div_fixup_f32 v115, v115, v110, 1.0
	v_mul_f32_e32 v122, v98, v115
	v_mul_f32_e32 v108, 0xbfb8aa3b, v99
	v_exp_f32_e32 v109, v108
	s_nop 0
	v_add_f32_e32 v110, 1.0, v109
	v_div_scale_f32 v111, s[54:55], v110, v110, 1.0
	v_rcp_f32_e32 v112, v111
	v_div_scale_f32 v113, vcc, 1.0, v110, 1.0
	v_fma_f32 v115, -v111, v112, 1.0
	v_fmac_f32_e32 v112, v115, v112
	v_mul_f32_e32 v114, v113, v112
	v_fma_f32 v115, -v111, v114, v113
	v_fmac_f32_e32 v114, v115, v112
	v_fma_f32 v115, -v111, v114, v113
	v_div_fmas_f32 v115, v115, v112, v114
	v_div_fixup_f32 v115, v115, v110, 1.0
	v_mul_f32_e32 v123, v99, v115
	v_cvt_pk_bf16_f32 v124, v120, v121
	v_cvt_pk_bf16_f32 v125, v122, v123
	global_store_dwordx2 v196, v[124:125], s[44:45] offset:1024
	s_waitcnt vmcnt(0)
